# LayerNorm rows unrolled with 3-deep prefetch; GEMM per-segment s_setprio flips removed; weight-tile job search resumes from previous job
# speedup vs baseline: 1.0101x; 1.0101x over previous
.LBB0_15:
	s_or_b64 exec, exec, s[6:7]
	s_add_u32 s0, s74, 0xf960000
	s_addc_u32 s1, s75, 0
	v_writelane_b32 v252, s0, 2
	s_mov_b32 s31, 0
	s_mov_b32 s3, s31
	v_writelane_b32 v252, s1, 3
	s_add_u32 s0, s74, 0xb720000
	v_writelane_b32 v252, s0, 4
	s_addc_u32 s0, s75, 0
	v_writelane_b32 v252, s0, 5
	s_add_u32 s0, s74, 0xb960000
	s_addc_u32 s1, s75, 0
	v_writelane_b32 v252, s0, 6
	s_mov_b32 s30, s4
	s_load_dwordx4 s[68:71], s[72:73], 0x40
	v_writelane_b32 v252, s1, 7
	s_lshl_b32 s0, s2, 3
	s_lshl_b32 s1, s4, 3
	v_writelane_b32 v252, s1, 8
	s_add_u32 s1, s74, 0x5800000
	v_writelane_b32 v252, s1, 9
	s_addc_u32 s1, s75, 0
	s_add_u32 s6, s74, 0x1b960000
	v_writelane_b32 v252, s1, 10
	s_addc_u32 s7, s75, 0
	v_writelane_b32 v252, s6, 11
	v_lshrrev_b32_e32 v2, 5, v135
	v_lshrrev_b32_e32 v4, 1, v135
	v_writelane_b32 v252, s7, 12
	s_add_u32 s6, s74, 0x24160000
	s_addc_u32 s7, s75, 0
	v_writelane_b32 v252, s6, 13
	v_and_b32_e32 v2, 4, v2
	v_bfe_u32 v3, v135, 2, 2
	v_writelane_b32 v252, s7, 14
	s_add_u32 s6, s74, 0x24260000
	s_addc_u32 s7, s75, 0
	v_writelane_b32 v252, s6, 15
	v_and_b32_e32 v170, 24, v4
	v_bfe_u32 v1, v135, 2, 4
	v_writelane_b32 v252, s7, 16
	s_add_u32 s6, s74, 0x1f960000
	s_addc_u32 s7, s75, 0
	v_writelane_b32 v252, s6, 17
	s_cmpk_lt_i32 s2, 0x800
	v_or3_b32 v2, v2, v3, v170
	v_writelane_b32 v252, s7, 18
	s_cselect_b64 s[6:7], -1, 0
	v_writelane_b32 v252, s6, 19
	s_add_u32 s1, s74, 0xb700000
	v_lshrrev_b32_e32 v3, 3, v135
	v_writelane_b32 v252, s7, 20
	v_writelane_b32 v252, s1, 21
	s_addc_u32 s1, s75, 0
	v_writelane_b32 v252, s1, 22
	s_add_u32 s1, s74, 0xb300000
	v_writelane_b32 v252, s1, 23
	s_addc_u32 s1, s75, 0
	s_add_u32 s6, s74, 0x23960000
	v_writelane_b32 v252, s1, 24
	s_addc_u32 s7, s75, 0
	v_writelane_b32 v252, s6, 25
	v_lshlrev_b32_e32 v0, 4, v135
	s_load_dwordx16 s[40:55], s[72:73], 0x0
	v_writelane_b32 v252, s7, 26
	s_add_u32 s6, s74, 0x21960000
	s_addc_u32 s7, s75, 0
	v_writelane_b32 v252, s6, 27
	v_lshlrev_b32_e32 v177, 1, v170
	v_and_b32_e32 v175, 15, v135
	v_writelane_b32 v252, s7, 28
	s_add_u32 s6, s74, 0x23d60000
	s_addc_u32 s7, s75, 0
	v_writelane_b32 v252, s6, 29
	v_mov_b32_e32 v33, 0
	v_mov_b32_e32 v136, 0x3e000000
	v_writelane_b32 v252, s7, 30
	s_lshl_b64 s[6:7], s[2:3], 9
	v_writelane_b32 v252, s6, 31
	v_mov_b32_e32 v182, 0x42800000
	v_mov_b32_e32 v183, 0xf149f2ca
	v_writelane_b32 v252, s7, 32
	s_lshl_b64 s[6:7], s[30:31], 9
	v_writelane_b32 v252, s6, 33
	s_add_u32 s1, s74, 0xa400000
	v_mov_b32_e32 v185, 0x461c4000
	v_writelane_b32 v252, s7, 34
	v_writelane_b32 v252, s1, 35
	s_addc_u32 s1, s75, 0
	v_writelane_b32 v252, s1, 36
	s_add_u32 s1, s74, 0xaf00000
	v_writelane_b32 v252, s1, 37
	s_addc_u32 s1, s75, 0
	v_writelane_b32 v252, s1, 38
	s_add_u32 s1, s74, 0x8400000
	v_writelane_b32 v252, s1, 39
	s_addc_u32 s1, s75, 0
	v_writelane_b32 v252, s1, 40
	s_add_u32 s1, s74, 0x9c00000
	v_writelane_b32 v252, s1, 41
	s_addc_u32 s1, s75, 0
	s_add_u32 s6, s74, 0x17960000
	v_writelane_b32 v252, s1, 42
	s_addc_u32 s7, s75, 0
	v_writelane_b32 v252, s6, 43
	s_cmpk_lt_i32 s2, 0x200
	v_mov_b32_e32 v186, 0x58000
	v_writelane_b32 v252, s7, 44
	s_cselect_b64 s[6:7], -1, 0
	v_writelane_b32 v252, s6, 45
	s_cmpk_eq_i32 s4, 0x100
	v_mov_b32_e32 v138, 0x3e38aa3b
	v_writelane_b32 v252, s7, 46
	s_cselect_b64 s[6:7], -1, 0
	v_writelane_b32 v252, s6, 47
	s_ashr_i32 s1, s2, 5
	s_ashr_i32 s29, s4, 31
	v_writelane_b32 v252, s7, 48
	v_writelane_b32 v252, s0, 49
	s_and_b32 s0, s0, 56
	s_add_i32 s0, s0, s1
	s_lshr_b32 s1, s2, 2
	s_lshl_b32 s0, s0, 3
	s_and_b32 s1, s1, 6
	s_load_dword s6, s[72:73], 0x4d0
	s_or_b32 s0, s0, s1
	v_writelane_b32 v252, s0, 50
	s_add_i32 s0, s4, s2
	v_writelane_b32 v252, s0, 51
	s_waitcnt lgkmcnt(0)
	s_add_u32 s0, s70, 0xb720000
	s_addc_u32 s1, s71, 0
	v_writelane_b32 v252, s0, 52
	s_ashr_i32 s7, s6, 31
	v_mov_b32_e32 v187, 0x200
	v_writelane_b32 v252, s1, 53
	s_lshl_b64 s[0:1], s[6:7], 2
	s_add_u32 s0, s72, s0
	s_addc_u32 s1, s73, s1
	v_writelane_b32 v252, s0, 54
	v_mov_b32_e32 v188, 0x1f960000
	v_mov_b32_e32 v189, 0x21960000
	v_writelane_b32 v252, s1, 55
	s_movk_i32 s0, 0x70
	v_and_or_b32 v171, v3, s0, v1
	s_movk_i32 s0, 0x60
	v_and_or_b32 v172, v3, s0, v2
	v_add_u32_e32 v3, 0x2000, v0
	s_load_dword s1, s[72:73], 0x4e0
	v_lshrrev_b32_e32 v3, 7, v3
	s_movk_i32 s0, 0xf0
	v_and_or_b32 v173, v3, s0, v1
	s_movk_i32 s0, 0xe0
	v_and_or_b32 v174, v3, s0, v2
	s_mul_i32 s0, s5, s4
	s_add_i32 s5, s6, -1
	s_cmpk_lt_u32 s2, 0x120
	s_waitcnt lgkmcnt(0)
	s_mul_i32 s8, s0, s1
	s_cselect_b64 s[0:1], -1, 0
	v_writelane_b32 v252, s0, 56
	v_lshlrev_b32_e32 v179, 1, v171
	v_lshlrev_b32_e32 v180, 1, v173
	v_writelane_b32 v252, s1, 57
	s_add_u32 s0, s74, 0x27960200
	s_addc_u32 s1, s75, 0
	s_add_u32 s60, s74, 0x27960400
	s_addc_u32 s61, s75, 0
	s_add_u32 s62, s74, 0x27960500
	v_writelane_b32 v252, s0, 58
	s_addc_u32 s63, s75, 0
	v_mov_b32_e32 v190, 0x41b17218
	v_writelane_b32 v252, s1, 59
	s_add_u32 s0, s74, 0x27960600
	s_addc_u32 s1, s75, 0
	v_writelane_b32 v252, s0, 60
	v_mov_b32_e32 v191, 0x7f800000
	v_mov_b32_e32 v193, 0x9000
	v_writelane_b32 v252, s1, 61
	s_add_u32 s0, s74, 0x27960700
	s_addc_u32 s1, s75, 0
	v_writelane_b32 v252, s0, 62
	s_movk_i32 s38, 0x210
	s_mov_b32 s39, 0xefa18f08
	v_writelane_b32 v252, s1, 63
	s_add_u32 s0, s74, 0x27960800
	s_addc_u32 s1, s75, 0
	v_writelane_b32 v253, s0, 0
	s_mov_b32 s37, 0x800000
	s_movk_i32 s12, 0x88
	v_writelane_b32 v253, s1, 1
	s_add_u32 s0, s74, 0x27960900
	s_addc_u32 s1, s75, 0
	v_writelane_b32 v253, s0, 2
	s_mov_b32 s13, 0x5040100
	s_mov_b32 s15, 0x9000
	v_writelane_b32 v253, s1, 3
	s_add_u32 s0, s74, 0x27960a00
	s_addc_u32 s1, s75, 0
	v_writelane_b32 v253, s0, 4
	s_mov_b64 s[26:27], 0x80
	s_mov_b32 s28, 0x3fd744fd
	v_writelane_b32 v253, s1, 5
	s_add_u32 s0, s74, 0x27960b00
	s_addc_u32 s1, s75, 0
	v_writelane_b32 v253, s0, 6
	s_mov_b32 s24, 0x3b000000
	s_barrier
	v_writelane_b32 v253, s1, 7
	s_add_u32 s0, s74, 0x27960c00
	s_addc_u32 s1, s75, 0
	v_writelane_b32 v253, s0, 8
	s_nop 1
	v_writelane_b32 v253, s1, 9
	s_add_u32 s0, s74, 0x27960d00
	s_addc_u32 s1, s75, 0
	v_writelane_b32 v253, s0, 10
	s_nop 1
	v_writelane_b32 v253, s1, 11
	s_add_u32 s0, s74, 0x27960e00
	s_addc_u32 s1, s75, 0
	v_writelane_b32 v253, s0, 12
	s_nop 1
	v_writelane_b32 v253, s1, 13
	s_add_u32 s0, s74, 0x27960f00
	s_addc_u32 s1, s75, 0
	v_writelane_b32 v253, s0, 14
	s_nop 1
	v_writelane_b32 v253, s1, 15
	s_add_u32 s0, s74, 0x27961000
	s_addc_u32 s1, s75, 0
	v_writelane_b32 v253, s0, 16
	s_nop 1
	v_writelane_b32 v253, s1, 17
	s_add_u32 s0, s74, 0x27961100
	s_addc_u32 s1, s75, 0
	v_writelane_b32 v253, s0, 18
	s_nop 1
	v_writelane_b32 v253, s1, 19
	s_add_u32 s0, s74, 0x27961200
	s_addc_u32 s1, s75, 0
	v_writelane_b32 v253, s0, 20
	s_nop 1
	v_writelane_b32 v253, s1, 21
	s_add_u32 s0, s74, 0x27961300
	s_addc_u32 s1, s75, 0
	v_writelane_b32 v253, s0, 22
	s_cmp_eq_u32 s14, 15
	s_nop 0
	v_writelane_b32 v253, s1, 23
	s_cselect_b64 s[0:1], -1, 0
	v_writelane_b32 v253, s0, 24
	s_cmp_eq_u32 s14, 14
	s_nop 0
	v_writelane_b32 v253, s1, 25
	s_cselect_b64 s[0:1], -1, 0
	v_writelane_b32 v253, s0, 26
	s_cmp_eq_u32 s14, 13
	s_nop 0
	v_writelane_b32 v253, s1, 27
	s_cselect_b64 s[0:1], -1, 0
	v_writelane_b32 v253, s0, 28
	s_cmp_eq_u32 s14, 12
	s_nop 0
	v_writelane_b32 v253, s1, 29
	s_cselect_b64 s[0:1], -1, 0
	v_writelane_b32 v253, s0, 30
	s_cmp_eq_u32 s14, 11
	s_nop 0
	v_writelane_b32 v253, s1, 31
	s_cselect_b64 s[0:1], -1, 0
	v_writelane_b32 v253, s0, 32
	s_cmp_eq_u32 s14, 10
	s_nop 0
	v_writelane_b32 v253, s1, 33
	s_cselect_b64 s[0:1], -1, 0
	v_writelane_b32 v253, s0, 34
	s_cmp_eq_u32 s14, 9
	s_nop 0
	v_writelane_b32 v253, s1, 35
	s_cselect_b64 s[0:1], -1, 0
	v_writelane_b32 v253, s0, 36
	s_cmp_eq_u32 s14, 8
	s_nop 0
	v_writelane_b32 v253, s1, 37
	s_cselect_b64 s[0:1], -1, 0
	v_writelane_b32 v253, s0, 38
	s_cmp_eq_u32 s14, 7
	s_nop 0
	v_writelane_b32 v253, s1, 39
	s_cselect_b64 s[0:1], -1, 0
	v_writelane_b32 v253, s0, 40
	s_cmp_eq_u32 s14, 6
	s_nop 0
	v_writelane_b32 v253, s1, 41
	s_cselect_b64 s[0:1], -1, 0
	v_writelane_b32 v253, s0, 42
	s_cmp_eq_u32 s14, 5
	s_nop 0
	v_writelane_b32 v253, s1, 43
	s_cselect_b64 s[0:1], -1, 0
	v_writelane_b32 v253, s0, 44
	s_cmp_eq_u32 s14, 4
	s_nop 0
	v_writelane_b32 v253, s1, 45
	s_cselect_b64 s[0:1], -1, 0
	v_writelane_b32 v253, s0, 46
	s_cmp_eq_u32 s14, 3
	s_nop 0
	v_writelane_b32 v253, s1, 47
	s_cselect_b64 s[0:1], -1, 0
	v_writelane_b32 v253, s0, 48
	s_cmp_eq_u32 s14, 2
	s_nop 0
	v_writelane_b32 v253, s1, 49
	s_cselect_b64 s[0:1], -1, 0
	v_writelane_b32 v253, s0, 50
	s_cmp_eq_u32 s14, 1
	s_nop 0
	v_writelane_b32 v253, s1, 51
	s_cselect_b64 s[0:1], -1, 0
	v_writelane_b32 v253, s0, 52
	s_cmp_eq_u32 s14, 0
	s_nop 0
	v_writelane_b32 v253, s1, 53
	s_cselect_b64 s[0:1], -1, 0
	v_writelane_b32 v253, s0, 54
	s_nop 1
	v_writelane_b32 v253, s1, 55
	s_lshl_b32 s0, s14, 8
	s_add_u32 s0, s16, s0
	s_addc_u32 s1, s17, 0
	s_add_u32 s10, s0, 0x1400
	s_addc_u32 s11, s1, 0
	v_writelane_b32 v253, s10, 56
	s_add_u32 s0, s0, 0x2400
	s_addc_u32 s1, s1, 0
	v_writelane_b32 v253, s11, 57
	v_writelane_b32 v253, s0, 58
	s_mov_b32 s10, 0x1000504
	s_mov_b32 s11, 0x3020706
	v_writelane_b32 v253, s1, 59
	s_add_u32 s0, s74, 0x27963400
	s_addc_u32 s1, s75, 0
	v_writelane_b32 v253, s0, 60
	s_movk_i32 s14, 0x108
	s_nop 0
	v_writelane_b32 v253, s1, 61
	s_add_u32 s0, s74, 0x27963500
	s_addc_u32 s1, s75, 0
	s_abs_i32 s9, s4
	v_cvt_f32_u32_e32 v1, s9
	v_writelane_b32 v253, s0, 62
	v_rcp_iflag_f32_e32 v1, v1
	s_nop 0
	v_writelane_b32 v253, s1, 63
	s_sub_i32 s0, 0, s9
	v_mul_f32_e32 v1, 0x4f7ffffe, v1
	v_cvt_u32_f32_e32 v1, v1
	s_nop 0
	v_readfirstlane_b32 s1, v1
	s_mul_i32 s0, s0, s1
	s_mul_hi_u32 s0, s1, s0
	s_add_i32 s0, s1, s0
	v_writelane_b32 v254, s0, 0
	s_add_u32 s0, s74, 0xf6f9000
	s_addc_u32 s1, s75, 0
	v_writelane_b32 v254, s0, 1
	v_and_b32_e32 v1, 32, v135
	v_bitop3_b32 v0, v0, v1, 48 bitop3:0x6c
	v_writelane_b32 v254, s1, 2
	s_lshl_b32 s0, s2, 7
	v_writelane_b32 v254, s0, 3
	s_lshl_b32 s0, s4, 7
	v_writelane_b32 v254, s0, 4
	s_lshl_b64 s[0:1], s[2:3], 13
	v_writelane_b32 v254, s0, 5
	v_and_or_b32 v134, v135, 64, v0
	v_lshlrev_b32_e32 v0, 6, v135
	v_writelane_b32 v254, s1, 6
	s_lshl_b64 s[0:1], s[30:31], 13
	v_writelane_b32 v254, s0, 7
	v_lshlrev_b32_e32 v1, 2, v135
	v_and_b32_e32 v0, 0x3c0, v0
	v_writelane_b32 v254, s1, 8
	s_lshl_b64 s[0:1], s[2:3], 12
	s_add_u32 s0, s70, s0
	s_addc_u32 s1, s71, s1
	s_add_u32 s0, s0, 0xb960000
	s_addc_u32 s1, s1, 0
	v_writelane_b32 v254, s0, 9
	v_and_b32_e32 v1, 32, v1
	v_lshrrev_b32_e32 v176, 1, v134
	v_writelane_b32 v254, s1, 10
	v_cmp_gt_i64_e64 s[0:1], s[6:7], 1
	v_bitop3_b32 v178, v177, v1, v0 bitop3:0x36
	s_mov_b32 s6, 0
	v_writelane_b32 v254, s0, 11
	s_nop 1
	v_writelane_b32 v254, s1, 12
	s_lshl_b64 s[0:1], s[30:31], 12
	v_writelane_b32 v254, s0, 13
	s_nop 1
	v_writelane_b32 v254, s1, 14
	s_lshl_b64 s[0:1], s[2:3], 11
	v_writelane_b32 v254, s0, 15
	s_mov_b32 s3, s8
	s_mov_b32 s8, 0x3d800000
	v_writelane_b32 v254, s1, 16
	s_lshl_b64 s[0:1], s[30:31], 11
	v_writelane_b32 v254, s0, 17
	s_nop 1
	v_writelane_b32 v254, s1, 18
	s_add_u32 s0, s72, 0x450
	s_addc_u32 s1, s73, 0
	v_writelane_b32 v254, s0, 19
	s_add_i32 s36, 0, 0x1d400
	s_add_i32 s33, 0, 0x19000
	v_writelane_b32 v254, s1, 20
	s_add_i32 s0, 0, 0x12000
	v_writelane_b32 v254, s0, 21
	s_add_i32 s0, 0, 0x26000
	v_writelane_b32 v254, s0, 22
	s_add_i32 s0, 0, 0x26004
	v_writelane_b32 v254, s0, 23
	v_writelane_b32 v254, s40, 24
	s_mov_b32 s0, s2
	s_nop 0
	v_writelane_b32 v254, s41, 25
	v_writelane_b32 v254, s42, 26
	v_writelane_b32 v254, s43, 27
	v_writelane_b32 v254, s44, 28
	v_writelane_b32 v254, s45, 29
	v_writelane_b32 v254, s46, 30
	v_writelane_b32 v254, s47, 31
	v_writelane_b32 v254, s48, 32
	v_writelane_b32 v254, s49, 33
	v_writelane_b32 v254, s50, 34
	v_writelane_b32 v254, s51, 35
	v_writelane_b32 v254, s52, 36
	v_writelane_b32 v254, s53, 37
	v_writelane_b32 v254, s54, 38
	v_writelane_b32 v254, s55, 39
	v_writelane_b32 v254, s0, 40
	s_nop 1
	v_writelane_b32 v254, s1, 41
	v_writelane_b32 v254, s72, 42
	s_mov_b64 s[0:1], s[68:69]
	s_nop 0
	v_writelane_b32 v254, s73, 43
	v_writelane_b32 v254, s74, 44
	s_nop 1
	v_writelane_b32 v254, s75, 45
	v_writelane_b32 v254, s0, 46
	s_nop 1
	v_writelane_b32 v254, s1, 47
	v_writelane_b32 v254, s2, 48
	v_writelane_b32 v254, s3, 49
	v_writelane_b32 v254, s3, 50
	v_writelane_b32 v254, s60, 51
	s_nop 1
	v_writelane_b32 v254, s61, 52
	v_writelane_b32 v254, s62, 53
	s_nop 1
	v_writelane_b32 v254, s63, 54
	s_mov_b32 s0, 0
	v_writelane_b32 v255, s0, 61
	s_branch .LBB0_19

.LBB0_49:
	s_and_b64 vcc, exec, s[42:43]
	s_cbranch_vccz .LBB0_226
	v_mov_b32_e32 v0, v135
	v_readlane_b32 s1, v252, 49
	v_readfirstlane_b32 s0, v0
	s_ashr_i32 s0, s0, 6
	s_add_i32 s6, s0, s1
	s_cmpk_gt_i32 s6, 0x7fff
	v_readlane_b32 s3, v252, 8
	s_cbranch_scc1 .LBB0_53
	s_mul_i32 s0, s16, 0x90000
	v_readlane_b32 s1, v252, 4
	s_add_u32 s7, s1, s0
	v_readlane_b32 s0, v252, 5
	s_addc_u32 s18, s0, 0
	s_cmp_eq_u32 s64, 1
	s_cselect_b64 s[0:1], -1, 0
	v_cndmask_b32_e64 v8, 0.5, 1.0, s[0:1]
	s_and_b64 s[0:1], s[0:1], s[92:93]
	s_and_b64 s[0:1], s[0:1], exec
	s_brev_b32 s0, 16
	s_cselect_b32 s0, s0, 0xc000000
	v_readlane_b32 s20, v252, 2
	v_readlane_b32 s21, v252, 3
	s_add_u32 s0, s20, s0
	s_addc_u32 s1, s21, 0
	s_cmp_lt_u32 s86, 39
	s_mul_i32 s30, s64, 0xc00
	s_cselect_b64 s[20:21], -1, 0
	s_add_i32 s25, s30, 0xc00
	s_cmp_eq_u32 s64, 2
	s_cselect_b64 s[22:23], -1, 0
	s_and_b64 s[34:35], s[22:23], exec
	s_cselect_b32 s34, 0, s25
	s_and_b64 s[20:21], s[22:23], s[20:21]
	s_and_b64 s[20:21], s[20:21], exec
	s_cselect_b32 s20, 0x90000, 0
	s_add_u32 s25, s7, s20
	s_addc_u32 s40, s18, 0
	s_lshl_b64 s[20:21], s[30:31], 2
	s_add_u32 s20, s7, s20
	s_mov_b32 s35, s31
	s_addc_u32 s21, s18, s21
	s_lshl_b64 s[22:23], s[34:35], 2
	s_add_u32 s22, s25, s22
	s_mul_i32 s7, s16, 3
	s_addc_u32 s23, s40, s23
	s_add_i32 s7, s64, s7
	v_lshlrev_b32_e32 v0, 2, v0
	s_lshl_b32 s30, s7, 10
	v_readlane_b32 s40, v254, 24
	v_and_b32_e32 v1, 0xfc, v0
	s_movk_i32 s7, 0x80
	v_bfrev_b32_e32 v2, 0.5
	s_lshl_b64 s[34:35], s[30:31], 2
	v_readlane_b32 s50, v254, 34
	s_waitcnt vmcnt(0)
	v_bitop3_b32 v52, v0, s7, v2 bitop3:0x6c
	v_lshlrev_b32_e32 v32, 2, v1
	v_lshlrev_b32_e32 v0, 1, v1
	v_mov_b32_e32 v1, v33
	v_readlane_b32 s41, v254, 25
	v_readlane_b32 s51, v254, 35
	s_add_u32 s40, s50, s34
	v_lshl_add_u64 v[18:19], s[0:1], 0, v[0:1]
	v_lshl_add_u64 v[2:3], s[20:21], 0, v[32:33]
	s_mov_b64 s[0:1], 0x2000
	v_readlane_b32 s48, v254, 32
	s_addc_u32 s41, s51, s35
	v_lshl_add_u64 v[20:21], v[2:3], 0, s[0:1]
	v_lshl_add_u64 v[22:23], s[22:23], 0, v[32:33]
	s_mov_b64 s[0:1], 0x1000
	v_readlane_b32 s49, v254, 33
	s_add_u32 s34, s48, s34
	v_lshl_add_u64 v[24:25], v[22:23], 0, s[0:1]
	v_readlane_b32 s0, v252, 6
	s_addc_u32 s35, s49, s35
	v_readlane_b32 s1, v252, 7
	v_mov_b32_e32 v10, v8
	v_mov_b32_e32 v11, v8
	v_lshl_add_u64 v[12:13], s[34:35], 0, v[32:33]
	v_lshl_add_u64 v[14:15], s[40:41], 0, v[32:33]
	v_lshl_add_u64 v[16:17], s[68:69], 0, v[32:33]
	v_lshl_add_u64 v[26:27], s[0:1], 0, v[0:1]
	v_readlane_b32 s42, v254, 26
	v_readlane_b32 s43, v254, 27
	v_readlane_b32 s44, v254, 28
	v_readlane_b32 s45, v254, 29
	v_readlane_b32 s46, v254, 30
	v_readlane_b32 s47, v254, 31
	v_readlane_b32 s52, v254, 36
	v_readlane_b32 s53, v254, 37
	v_readlane_b32 s54, v254, 38
	v_readlane_b32 s55, v254, 39
	s_cmpk_lg_i32 s3, 0x800
	s_cbranch_scc1 .LBB0_52
	v_mov_b32_e32 v96, v52
	s_lshr_b32 s0, s6, 7
	s_and_b32 s7, s6, 7
	s_andn2_b32 s6, s6, 7
	s_lshl_b32 s6, s6, 4
	s_or_b32 s6, s6, s7
	v_mad_i64_i32 v[28:29], s[22:23], s0, v193, v[20:21]
	v_mad_i64_i32 v[30:31], s[22:23], s0, v193, v[22:23]
	v_mad_i64_i32 v[0:1], s[22:23], s0, v193, v[24:25]
	global_load_dwordx4 v[194:197], v[28:29], off
	global_load_dwordx4 v[198:201], v[28:29], off offset:1024
	global_load_dwordx4 v[202:205], v[28:29], off offset:2048
	global_load_dwordx4 v[206:209], v[28:29], off offset:3072
	global_load_dwordx4 v[210:213], v[30:31], off
	global_load_dwordx4 v[214:217], v[30:31], off offset:1024
	global_load_dwordx4 v[218:221], v[30:31], off offset:2048
	global_load_dwordx4 v[222:225], v[30:31], off offset:3072
	global_load_dwordx4 v[226:229], v[0:1], off
	global_load_dwordx4 v[230:233], v[0:1], off offset:1024
	global_load_dwordx4 v[234:237], v[0:1], off offset:2048
	global_load_dwordx4 v[238:241], v[0:1], off offset:3072
	global_load_dwordx4 v[140:143], v[12:13], off
	global_load_dwordx4 v[144:147], v[12:13], off offset:1024
	global_load_dwordx4 v[148:151], v[12:13], off offset:2048
	global_load_dwordx4 v[152:155], v[12:13], off offset:3072
	global_load_dwordx4 v[98:101], v[14:15], off
	global_load_dwordx4 v[102:105], v[14:15], off offset:1024
	global_load_dwordx4 v[106:109], v[14:15], off offset:2048
	global_load_dwordx4 v[110:113], v[14:15], off offset:3072
	s_ashr_i32 s7, s6, 31
	s_lshl_b64 s[40:41], s[6:7], 12
	s_lshl_b64 s[20:21], s[6:7], 11
	v_lshl_add_u64 v[82:83], v[16:17], 0, s[40:41]
	v_lshl_add_u64 v[84:85], v[18:19], 0, s[20:21]
	v_lshl_add_u64 v[88:89], v[26:27], 0, s[20:21]
	v_lshl_add_u64 v[86:87], v[16:17], 0, s[40:41]
	s_mov_b64 s[0:1], 0x8000
	s_mov_b64 s[20:21], 0x4000
	global_load_dwordx4 v[34:37], v[82:83], off nt
	global_load_dwordx4 v[38:41], v[82:83], off offset:1024 nt
	global_load_dwordx4 v[42:45], v[82:83], off offset:2048 nt
	global_load_dwordx4 v[46:49], v[82:83], off offset:3072 nt
	global_load_dwordx2 v[50:51], v[84:85], off nt
	global_load_dwordx2 v[52:53], v[84:85], off offset:512 nt
	global_load_dwordx2 v[54:55], v[84:85], off offset:1024 nt
	global_load_dwordx2 v[56:57], v[84:85], off offset:1536 nt
	v_lshl_add_u64 v[82:83], v[82:83], 0, s[0:1]
	v_lshl_add_u64 v[84:85], v[84:85], 0, s[20:21]
	global_load_dwordx4 v[58:61], v[82:83], off nt
	global_load_dwordx4 v[62:65], v[82:83], off offset:1024 nt
	global_load_dwordx4 v[66:69], v[82:83], off offset:2048 nt
	global_load_dwordx4 v[70:73], v[82:83], off offset:3072 nt
	global_load_dwordx2 v[74:75], v[84:85], off nt
	global_load_dwordx2 v[76:77], v[84:85], off offset:512 nt
	global_load_dwordx2 v[78:79], v[84:85], off offset:1024 nt
	global_load_dwordx2 v[80:81], v[84:85], off offset:1536 nt
	v_lshl_add_u64 v[82:83], v[82:83], 0, s[0:1]
	v_lshl_add_u64 v[84:85], v[84:85], 0, s[20:21]
	global_load_dwordx4 v[20:23], v[82:83], off nt
	global_load_dwordx4 v[24:27], v[82:83], off offset:1024 nt
	global_load_dwordx4 v[0:3], v[82:83], off offset:2048 nt
	global_load_dwordx4 v[4:7], v[82:83], off offset:3072 nt
	global_load_dwordx2 v[12:13], v[84:85], off nt
	global_load_dwordx2 v[14:15], v[84:85], off offset:512 nt
	global_load_dwordx2 v[16:17], v[84:85], off offset:1024 nt
	global_load_dwordx2 v[18:19], v[84:85], off offset:1536 nt
	v_lshl_add_u64 v[82:83], v[82:83], 0, s[0:1]
	v_lshl_add_u64 v[84:85], v[84:85], 0, s[20:21]
	s_waitcnt vmcnt(24)
	v_pk_add_f32 v[194:195], v[194:195], 1.0 op_sel_hi:[1,0]
	v_pk_add_f32 v[196:197], v[196:197], 1.0 op_sel_hi:[1,0]
	v_pk_add_f32 v[198:199], v[198:199], 1.0 op_sel_hi:[1,0]
	v_pk_add_f32 v[200:201], v[200:201], 1.0 op_sel_hi:[1,0]
	v_pk_add_f32 v[202:203], v[202:203], 1.0 op_sel_hi:[1,0]
	v_pk_add_f32 v[204:205], v[204:205], 1.0 op_sel_hi:[1,0]
	v_pk_add_f32 v[206:207], v[206:207], 1.0 op_sel_hi:[1,0]
	v_pk_add_f32 v[208:209], v[208:209], 1.0 op_sel_hi:[1,0]
	v_pk_add_f32 v[226:227], v[226:227], 1.0 op_sel_hi:[1,0]
	v_pk_add_f32 v[228:229], v[228:229], 1.0 op_sel_hi:[1,0]
	v_pk_add_f32 v[230:231], v[230:231], 1.0 op_sel_hi:[1,0]
	v_pk_add_f32 v[232:233], v[232:233], 1.0 op_sel_hi:[1,0]
	v_pk_add_f32 v[234:235], v[234:235], 1.0 op_sel_hi:[1,0]
	v_pk_add_f32 v[236:237], v[236:237], 1.0 op_sel_hi:[1,0]
	v_pk_add_f32 v[238:239], v[238:239], 1.0 op_sel_hi:[1,0]
	v_pk_add_f32 v[240:241], v[240:241], 1.0 op_sel_hi:[1,0]
	s_waitcnt vmcnt(16)
	v_lshlrev_b32_e32 v156, 16, v50
	v_and_b32_e32 v157, 0xffff0000, v50
	v_lshlrev_b32_e32 v50, 16, v51
	v_and_b32_e32 v51, 0xffff0000, v51
	v_lshlrev_b32_e32 v158, 16, v52
	v_and_b32_e32 v159, 0xffff0000, v52
	v_lshlrev_b32_e32 v52, 16, v53
	v_and_b32_e32 v53, 0xffff0000, v53
	v_lshlrev_b32_e32 v160, 16, v54
	v_and_b32_e32 v161, 0xffff0000, v54
	v_lshlrev_b32_e32 v54, 16, v55
	v_and_b32_e32 v55, 0xffff0000, v55
	v_lshlrev_b32_e32 v162, 16, v56
	v_and_b32_e32 v163, 0xffff0000, v56
	v_lshlrev_b32_e32 v56, 16, v57
	v_and_b32_e32 v57, 0xffff0000, v57
	v_pk_mul_f32 v[114:115], v[194:195], v[156:157]
	v_pk_mul_f32 v[116:117], v[196:197], v[50:51]
	v_pk_mul_f32 v[118:119], v[198:199], v[158:159]
	v_pk_mul_f32 v[120:121], v[200:201], v[52:53]
	v_pk_mul_f32 v[122:123], v[202:203], v[160:161]
	v_pk_mul_f32 v[124:125], v[204:205], v[54:55]
	v_pk_mul_f32 v[126:127], v[206:207], v[162:163]
	v_pk_mul_f32 v[128:129], v[208:209], v[56:57]
	v_pk_mul_f32 v[114:115], v[10:11], v[114:115]
	v_pk_mul_f32 v[116:117], v[10:11], v[116:117]
	v_pk_mul_f32 v[118:119], v[10:11], v[118:119]
	v_pk_mul_f32 v[120:121], v[10:11], v[120:121]
	v_pk_mul_f32 v[122:123], v[10:11], v[122:123]
	v_pk_mul_f32 v[124:125], v[10:11], v[124:125]
	v_pk_mul_f32 v[126:127], v[10:11], v[126:127]
	v_pk_mul_f32 v[128:129], v[10:11], v[128:129]
	v_pk_fma_f32 v[114:115], v[34:35], s[28:29], v[114:115] op_sel_hi:[1,0,1]
	v_pk_fma_f32 v[116:117], v[36:37], s[28:29], v[116:117] op_sel_hi:[1,0,1]
	v_pk_fma_f32 v[118:119], v[38:39], s[28:29], v[118:119] op_sel_hi:[1,0,1]
	v_pk_fma_f32 v[120:121], v[40:41], s[28:29], v[120:121] op_sel_hi:[1,0,1]
	v_pk_fma_f32 v[122:123], v[42:43], s[28:29], v[122:123] op_sel_hi:[1,0,1]
	v_pk_fma_f32 v[124:125], v[44:45], s[28:29], v[124:125] op_sel_hi:[1,0,1]
	v_pk_fma_f32 v[126:127], v[46:47], s[28:29], v[126:127] op_sel_hi:[1,0,1]
	v_pk_fma_f32 v[128:129], v[48:49], s[28:29], v[128:129] op_sel_hi:[1,0,1]
	v_add_f32_e32 v164, v114, v115
	v_add_f32_e32 v165, v116, v117
	v_add_f32_e32 v166, v118, v119
	v_add_f32_e32 v167, v120, v121
	v_add_f32_e32 v168, v122, v123
	v_add_f32_e32 v169, v124, v125
	v_add_f32_e32 v242, v126, v127
	v_add_f32_e32 v243, v128, v129
	v_add_f32_e32 v164, v164, v165
	v_add_f32_e32 v166, v166, v167
	v_add_f32_e32 v168, v168, v169
	v_add_f32_e32 v242, v242, v243
	v_add_f32_e32 v9, 0, v164
	v_add_f32_e32 v9, v9, v166
	v_add_f32_e32 v9, v9, v168
	v_add_f32_e32 v9, v9, v242
	ds_bpermute_b32 v28, v96, v9
	s_waitcnt lgkmcnt(0)
	v_add_f32_e32 v9, v9, v28
	ds_swizzle_b32 v28, v9 offset:swizzle(SWAP,16)
	s_waitcnt lgkmcnt(0)
	v_add_f32_e32 v9, v9, v28
	ds_swizzle_b32 v28, v9 offset:swizzle(SWAP,8)
	s_waitcnt lgkmcnt(0)
	v_add_f32_e32 v9, v9, v28
	ds_swizzle_b32 v28, v9 offset:swizzle(SWAP,4)
	s_waitcnt lgkmcnt(0)
	v_add_f32_e32 v9, v9, v28
	ds_swizzle_b32 v28, v9 offset:swizzle(SWAP,2)
	s_waitcnt lgkmcnt(0)
	v_add_f32_e32 v9, v9, v28
	ds_swizzle_b32 v28, v9 offset:swizzle(SWAP,1)
	s_waitcnt lgkmcnt(0)
	v_add_f32_e32 v9, v9, v28
	v_fmac_f32_e32 v114, 0xba800000, v9
	v_fmac_f32_e32 v115, 0xba800000, v9
	v_fmac_f32_e32 v116, 0xba800000, v9
	v_fmac_f32_e32 v117, 0xba800000, v9
	v_fmac_f32_e32 v118, 0xba800000, v9
	v_fmac_f32_e32 v119, 0xba800000, v9
	v_fmac_f32_e32 v120, 0xba800000, v9
	v_fmac_f32_e32 v121, 0xba800000, v9
	v_fmac_f32_e32 v122, 0xba800000, v9
	v_fmac_f32_e32 v123, 0xba800000, v9
	v_fmac_f32_e32 v124, 0xba800000, v9
	v_fmac_f32_e32 v125, 0xba800000, v9
	v_fmac_f32_e32 v126, 0xba800000, v9
	v_fmac_f32_e32 v127, 0xba800000, v9
	v_fmac_f32_e32 v128, 0xba800000, v9
	v_fmac_f32_e32 v129, 0xba800000, v9
	v_pk_mul_f32 v[244:245], v[114:115], v[114:115]
	v_pk_mul_f32 v[246:247], v[116:117], v[116:117]
	v_add_f32_e32 v244, v245, v244
	v_add_f32_e32 v246, v246, v247
	v_add_f32_e32 v164, v244, v246
	v_pk_mul_f32 v[244:245], v[118:119], v[118:119]
	v_pk_mul_f32 v[246:247], v[120:121], v[120:121]
	v_add_f32_e32 v244, v245, v244
	v_add_f32_e32 v246, v246, v247
	v_add_f32_e32 v165, v244, v246
	v_mul_f32_e32 v248, v122, v122
	v_mul_f32_e32 v249, v124, v124
	v_fmac_f32_e32 v248, v123, v123
	v_fmac_f32_e32 v249, v125, v125
	v_add_f32_e32 v166, v248, v249
	v_pk_mul_f32 v[244:245], v[126:127], v[126:127]
	v_pk_mul_f32 v[246:247], v[128:129], v[128:129]
	v_add_f32_e32 v244, v244, v245
	v_add_f32_e32 v246, v246, v247
	v_add_f32_e32 v167, v244, v246
	v_add_f32_e32 v164, v164, v165
	v_add_f32_e32 v164, v166, v164
	v_add_f32_e32 v9, v167, v164
	ds_bpermute_b32 v28, v96, v9
	s_waitcnt lgkmcnt(0)
	v_add_f32_e32 v9, v9, v28
	ds_swizzle_b32 v28, v9 offset:swizzle(SWAP,16)
	s_waitcnt lgkmcnt(0)
	v_add_f32_e32 v9, v9, v28
	ds_swizzle_b32 v28, v9 offset:swizzle(SWAP,8)
	s_waitcnt lgkmcnt(0)
	v_add_f32_e32 v9, v9, v28
	ds_swizzle_b32 v28, v9 offset:swizzle(SWAP,4)
	s_waitcnt lgkmcnt(0)
	v_add_f32_e32 v9, v9, v28
	ds_swizzle_b32 v28, v9 offset:swizzle(SWAP,2)
	s_waitcnt lgkmcnt(0)
	v_add_f32_e32 v9, v9, v28
	ds_swizzle_b32 v28, v9 offset:swizzle(SWAP,1)
	s_waitcnt lgkmcnt(0)
	v_add_f32_e32 v9, v9, v28
	v_mov_b32_e32 v28, 0x3727c5ac
	v_fmamk_f32 v9, v9, 0x3a800000, v28
	v_mul_f32_e32 v28, 0x4b800000, v9
	v_cmp_gt_f32_e32 vcc, s37, v9
	s_nop 1
	v_cndmask_b32_e32 v9, v9, v28, vcc
	v_rsq_f32_e32 v9, v9
	s_nop 0
	v_mul_f32_e32 v28, 0x45800000, v9
	v_cndmask_b32_e32 v30, v9, v28, vcc
	v_pk_mul_f32 v[114:115], v[114:115], v[30:31] op_sel_hi:[1,0]
	v_pk_mul_f32 v[116:117], v[116:117], v[30:31] op_sel_hi:[1,0]
	v_pk_fma_f32 v[34:35], v[140:141], v[114:115], v[98:99]
	v_pk_fma_f32 v[36:37], v[142:143], v[116:117], v[100:101]
	global_store_dwordx4 v[86:87], v[34:37], off sc1 nt
	v_pk_fma_f32 v[114:115], v[226:227], v[34:35], v[210:211]
	v_pk_fma_f32 v[116:117], v[228:229], v[36:37], v[212:213]
	s_nop 0
	v_cvt_pk_bf16_f32 v50, v114, v115
	v_cvt_pk_bf16_f32 v51, v116, v117
	global_store_dwordx2 v[88:89], v[50:51], off sc1
	v_pk_mul_f32 v[118:119], v[118:119], v[30:31] op_sel_hi:[1,0]
	v_pk_mul_f32 v[120:121], v[120:121], v[30:31] op_sel_hi:[1,0]
	v_pk_fma_f32 v[38:39], v[144:145], v[118:119], v[102:103]
	v_pk_fma_f32 v[40:41], v[146:147], v[120:121], v[104:105]
	global_store_dwordx4 v[86:87], v[38:41], off offset:1024 sc1 nt
	v_pk_fma_f32 v[118:119], v[230:231], v[38:39], v[214:215]
	v_pk_fma_f32 v[120:121], v[232:233], v[40:41], v[216:217]
	s_nop 0
	v_cvt_pk_bf16_f32 v52, v118, v119
	v_cvt_pk_bf16_f32 v53, v120, v121
	global_store_dwordx2 v[88:89], v[52:53], off offset:512 sc1
	v_pk_mul_f32 v[122:123], v[122:123], v[30:31] op_sel_hi:[1,0]
	v_pk_mul_f32 v[124:125], v[124:125], v[30:31] op_sel_hi:[1,0]
	v_pk_fma_f32 v[42:43], v[148:149], v[122:123], v[106:107]
	v_pk_fma_f32 v[44:45], v[150:151], v[124:125], v[108:109]
	global_store_dwordx4 v[86:87], v[42:45], off offset:2048 sc1 nt
	v_pk_fma_f32 v[122:123], v[234:235], v[42:43], v[218:219]
	v_pk_fma_f32 v[124:125], v[236:237], v[44:45], v[220:221]
	s_nop 0
	v_cvt_pk_bf16_f32 v54, v122, v123
	v_cvt_pk_bf16_f32 v55, v124, v125
	global_store_dwordx2 v[88:89], v[54:55], off offset:1024 sc1
	v_pk_mul_f32 v[126:127], v[126:127], v[30:31] op_sel_hi:[1,0]
	v_pk_mul_f32 v[128:129], v[128:129], v[30:31] op_sel_hi:[1,0]
	v_pk_fma_f32 v[46:47], v[152:153], v[126:127], v[110:111]
	v_pk_fma_f32 v[48:49], v[154:155], v[128:129], v[112:113]
	global_store_dwordx4 v[86:87], v[46:49], off offset:3072 sc1 nt
	v_pk_fma_f32 v[126:127], v[238:239], v[46:47], v[222:223]
	v_pk_fma_f32 v[128:129], v[240:241], v[48:49], v[224:225]
	s_nop 0
	v_cvt_pk_bf16_f32 v56, v126, v127
	v_cvt_pk_bf16_f32 v57, v128, v129
	global_store_dwordx2 v[88:89], v[56:57], off offset:1536 sc1
	v_lshl_add_u64 v[86:87], v[86:87], 0, s[0:1]
	v_lshl_add_u64 v[88:89], v[88:89], 0, s[20:21]
	global_load_dwordx4 v[34:37], v[82:83], off nt
	global_load_dwordx4 v[38:41], v[82:83], off offset:1024 nt
	global_load_dwordx4 v[42:45], v[82:83], off offset:2048 nt
	global_load_dwordx4 v[46:49], v[82:83], off offset:3072 nt
	global_load_dwordx2 v[50:51], v[84:85], off nt
	global_load_dwordx2 v[52:53], v[84:85], off offset:512 nt
	global_load_dwordx2 v[54:55], v[84:85], off offset:1024 nt
	global_load_dwordx2 v[56:57], v[84:85], off offset:1536 nt
	v_lshl_add_u64 v[82:83], v[82:83], 0, s[0:1]
	v_lshl_add_u64 v[84:85], v[84:85], 0, s[20:21]
	s_waitcnt vmcnt(24)
	v_lshlrev_b32_e32 v156, 16, v74
	v_and_b32_e32 v157, 0xffff0000, v74
	v_lshlrev_b32_e32 v74, 16, v75
	v_and_b32_e32 v75, 0xffff0000, v75
	v_lshlrev_b32_e32 v158, 16, v76
	v_and_b32_e32 v159, 0xffff0000, v76
	v_lshlrev_b32_e32 v76, 16, v77
	v_and_b32_e32 v77, 0xffff0000, v77
	v_lshlrev_b32_e32 v160, 16, v78
	v_and_b32_e32 v161, 0xffff0000, v78
	v_lshlrev_b32_e32 v78, 16, v79
	v_and_b32_e32 v79, 0xffff0000, v79
	v_lshlrev_b32_e32 v162, 16, v80
	v_and_b32_e32 v163, 0xffff0000, v80
	v_lshlrev_b32_e32 v80, 16, v81
	v_and_b32_e32 v81, 0xffff0000, v81
	v_pk_mul_f32 v[114:115], v[194:195], v[156:157]
	v_pk_mul_f32 v[116:117], v[196:197], v[74:75]
	v_pk_mul_f32 v[118:119], v[198:199], v[158:159]
	v_pk_mul_f32 v[120:121], v[200:201], v[76:77]
	v_pk_mul_f32 v[122:123], v[202:203], v[160:161]
	v_pk_mul_f32 v[124:125], v[204:205], v[78:79]
	v_pk_mul_f32 v[126:127], v[206:207], v[162:163]
	v_pk_mul_f32 v[128:129], v[208:209], v[80:81]
	v_pk_mul_f32 v[114:115], v[10:11], v[114:115]
	v_pk_mul_f32 v[116:117], v[10:11], v[116:117]
	v_pk_mul_f32 v[118:119], v[10:11], v[118:119]
	v_pk_mul_f32 v[120:121], v[10:11], v[120:121]
	v_pk_mul_f32 v[122:123], v[10:11], v[122:123]
	v_pk_mul_f32 v[124:125], v[10:11], v[124:125]
	v_pk_mul_f32 v[126:127], v[10:11], v[126:127]
	v_pk_mul_f32 v[128:129], v[10:11], v[128:129]
	v_pk_fma_f32 v[114:115], v[58:59], s[28:29], v[114:115] op_sel_hi:[1,0,1]
	v_pk_fma_f32 v[116:117], v[60:61], s[28:29], v[116:117] op_sel_hi:[1,0,1]
	v_pk_fma_f32 v[118:119], v[62:63], s[28:29], v[118:119] op_sel_hi:[1,0,1]
	v_pk_fma_f32 v[120:121], v[64:65], s[28:29], v[120:121] op_sel_hi:[1,0,1]
	v_pk_fma_f32 v[122:123], v[66:67], s[28:29], v[122:123] op_sel_hi:[1,0,1]
	v_pk_fma_f32 v[124:125], v[68:69], s[28:29], v[124:125] op_sel_hi:[1,0,1]
	v_pk_fma_f32 v[126:127], v[70:71], s[28:29], v[126:127] op_sel_hi:[1,0,1]
	v_pk_fma_f32 v[128:129], v[72:73], s[28:29], v[128:129] op_sel_hi:[1,0,1]
	v_add_f32_e32 v164, v114, v115
	v_add_f32_e32 v165, v116, v117
	v_add_f32_e32 v166, v118, v119
	v_add_f32_e32 v167, v120, v121
	v_add_f32_e32 v168, v122, v123
	v_add_f32_e32 v169, v124, v125
	v_add_f32_e32 v242, v126, v127
	v_add_f32_e32 v243, v128, v129
	v_add_f32_e32 v164, v164, v165
	v_add_f32_e32 v166, v166, v167
	v_add_f32_e32 v168, v168, v169
	v_add_f32_e32 v242, v242, v243
	v_add_f32_e32 v9, 0, v164
	v_add_f32_e32 v9, v9, v166
	v_add_f32_e32 v9, v9, v168
	v_add_f32_e32 v9, v9, v242
	ds_bpermute_b32 v28, v96, v9
	s_waitcnt lgkmcnt(0)
	v_add_f32_e32 v9, v9, v28
	ds_swizzle_b32 v28, v9 offset:swizzle(SWAP,16)
	s_waitcnt lgkmcnt(0)
	v_add_f32_e32 v9, v9, v28
	ds_swizzle_b32 v28, v9 offset:swizzle(SWAP,8)
	s_waitcnt lgkmcnt(0)
	v_add_f32_e32 v9, v9, v28
	ds_swizzle_b32 v28, v9 offset:swizzle(SWAP,4)
	s_waitcnt lgkmcnt(0)
	v_add_f32_e32 v9, v9, v28
	ds_swizzle_b32 v28, v9 offset:swizzle(SWAP,2)
	s_waitcnt lgkmcnt(0)
	v_add_f32_e32 v9, v9, v28
	ds_swizzle_b32 v28, v9 offset:swizzle(SWAP,1)
	s_waitcnt lgkmcnt(0)
	v_add_f32_e32 v9, v9, v28
	v_fmac_f32_e32 v114, 0xba800000, v9
	v_fmac_f32_e32 v115, 0xba800000, v9
	v_fmac_f32_e32 v116, 0xba800000, v9
	v_fmac_f32_e32 v117, 0xba800000, v9
	v_fmac_f32_e32 v118, 0xba800000, v9
	v_fmac_f32_e32 v119, 0xba800000, v9
	v_fmac_f32_e32 v120, 0xba800000, v9
	v_fmac_f32_e32 v121, 0xba800000, v9
	v_fmac_f32_e32 v122, 0xba800000, v9
	v_fmac_f32_e32 v123, 0xba800000, v9
	v_fmac_f32_e32 v124, 0xba800000, v9
	v_fmac_f32_e32 v125, 0xba800000, v9
	v_fmac_f32_e32 v126, 0xba800000, v9
	v_fmac_f32_e32 v127, 0xba800000, v9
	v_fmac_f32_e32 v128, 0xba800000, v9
	v_fmac_f32_e32 v129, 0xba800000, v9
	v_pk_mul_f32 v[244:245], v[114:115], v[114:115]
	v_pk_mul_f32 v[246:247], v[116:117], v[116:117]
	v_add_f32_e32 v244, v245, v244
	v_add_f32_e32 v246, v246, v247
	v_add_f32_e32 v164, v244, v246
	v_pk_mul_f32 v[244:245], v[118:119], v[118:119]
	v_pk_mul_f32 v[246:247], v[120:121], v[120:121]
	v_add_f32_e32 v244, v245, v244
	v_add_f32_e32 v246, v246, v247
	v_add_f32_e32 v165, v244, v246
	v_mul_f32_e32 v248, v122, v122
	v_mul_f32_e32 v249, v124, v124
	v_fmac_f32_e32 v248, v123, v123
	v_fmac_f32_e32 v249, v125, v125
	v_add_f32_e32 v166, v248, v249
	v_pk_mul_f32 v[244:245], v[126:127], v[126:127]
	v_pk_mul_f32 v[246:247], v[128:129], v[128:129]
	v_add_f32_e32 v244, v244, v245
	v_add_f32_e32 v246, v246, v247
	v_add_f32_e32 v167, v244, v246
	v_add_f32_e32 v164, v164, v165
	v_add_f32_e32 v164, v166, v164
	v_add_f32_e32 v9, v167, v164
	ds_bpermute_b32 v28, v96, v9
	s_waitcnt lgkmcnt(0)
	v_add_f32_e32 v9, v9, v28
	ds_swizzle_b32 v28, v9 offset:swizzle(SWAP,16)
	s_waitcnt lgkmcnt(0)
	v_add_f32_e32 v9, v9, v28
	ds_swizzle_b32 v28, v9 offset:swizzle(SWAP,8)
	s_waitcnt lgkmcnt(0)
	v_add_f32_e32 v9, v9, v28
	ds_swizzle_b32 v28, v9 offset:swizzle(SWAP,4)
	s_waitcnt lgkmcnt(0)
	v_add_f32_e32 v9, v9, v28
	ds_swizzle_b32 v28, v9 offset:swizzle(SWAP,2)
	s_waitcnt lgkmcnt(0)
	v_add_f32_e32 v9, v9, v28
	ds_swizzle_b32 v28, v9 offset:swizzle(SWAP,1)
	s_waitcnt lgkmcnt(0)
	v_add_f32_e32 v9, v9, v28
	v_mov_b32_e32 v28, 0x3727c5ac
	v_fmamk_f32 v9, v9, 0x3a800000, v28
	v_mul_f32_e32 v28, 0x4b800000, v9
	v_cmp_gt_f32_e32 vcc, s37, v9
	s_nop 1
	v_cndmask_b32_e32 v9, v9, v28, vcc
	v_rsq_f32_e32 v9, v9
	s_nop 0
	v_mul_f32_e32 v28, 0x45800000, v9
	v_cndmask_b32_e32 v30, v9, v28, vcc
	v_pk_mul_f32 v[114:115], v[114:115], v[30:31] op_sel_hi:[1,0]
	v_pk_mul_f32 v[116:117], v[116:117], v[30:31] op_sel_hi:[1,0]
	v_pk_fma_f32 v[58:59], v[140:141], v[114:115], v[98:99]
	v_pk_fma_f32 v[60:61], v[142:143], v[116:117], v[100:101]
	global_store_dwordx4 v[86:87], v[58:61], off sc1 nt
	v_pk_fma_f32 v[114:115], v[226:227], v[58:59], v[210:211]
	v_pk_fma_f32 v[116:117], v[228:229], v[60:61], v[212:213]
	s_nop 0
	v_cvt_pk_bf16_f32 v74, v114, v115
	v_cvt_pk_bf16_f32 v75, v116, v117
	global_store_dwordx2 v[88:89], v[74:75], off sc1
	v_pk_mul_f32 v[118:119], v[118:119], v[30:31] op_sel_hi:[1,0]
	v_pk_mul_f32 v[120:121], v[120:121], v[30:31] op_sel_hi:[1,0]
	v_pk_fma_f32 v[62:63], v[144:145], v[118:119], v[102:103]
	v_pk_fma_f32 v[64:65], v[146:147], v[120:121], v[104:105]
	global_store_dwordx4 v[86:87], v[62:65], off offset:1024 sc1 nt
	v_pk_fma_f32 v[118:119], v[230:231], v[62:63], v[214:215]
	v_pk_fma_f32 v[120:121], v[232:233], v[64:65], v[216:217]
	s_nop 0
	v_cvt_pk_bf16_f32 v76, v118, v119
	v_cvt_pk_bf16_f32 v77, v120, v121
	global_store_dwordx2 v[88:89], v[76:77], off offset:512 sc1
	v_pk_mul_f32 v[122:123], v[122:123], v[30:31] op_sel_hi:[1,0]
	v_pk_mul_f32 v[124:125], v[124:125], v[30:31] op_sel_hi:[1,0]
	v_pk_fma_f32 v[66:67], v[148:149], v[122:123], v[106:107]
	v_pk_fma_f32 v[68:69], v[150:151], v[124:125], v[108:109]
	global_store_dwordx4 v[86:87], v[66:69], off offset:2048 sc1 nt
	v_pk_fma_f32 v[122:123], v[234:235], v[66:67], v[218:219]
	v_pk_fma_f32 v[124:125], v[236:237], v[68:69], v[220:221]
	s_nop 0
	v_cvt_pk_bf16_f32 v78, v122, v123
	v_cvt_pk_bf16_f32 v79, v124, v125
	global_store_dwordx2 v[88:89], v[78:79], off offset:1024 sc1
	v_pk_mul_f32 v[126:127], v[126:127], v[30:31] op_sel_hi:[1,0]
	v_pk_mul_f32 v[128:129], v[128:129], v[30:31] op_sel_hi:[1,0]
	v_pk_fma_f32 v[70:71], v[152:153], v[126:127], v[110:111]
	v_pk_fma_f32 v[72:73], v[154:155], v[128:129], v[112:113]
	global_store_dwordx4 v[86:87], v[70:73], off offset:3072 sc1 nt
	v_pk_fma_f32 v[126:127], v[238:239], v[70:71], v[222:223]
	v_pk_fma_f32 v[128:129], v[240:241], v[72:73], v[224:225]
	s_nop 0
	v_cvt_pk_bf16_f32 v80, v126, v127
	v_cvt_pk_bf16_f32 v81, v128, v129
	global_store_dwordx2 v[88:89], v[80:81], off offset:1536 sc1
	v_lshl_add_u64 v[86:87], v[86:87], 0, s[0:1]
	v_lshl_add_u64 v[88:89], v[88:89], 0, s[20:21]
	global_load_dwordx4 v[58:61], v[82:83], off nt
	global_load_dwordx4 v[62:65], v[82:83], off offset:1024 nt
	global_load_dwordx4 v[66:69], v[82:83], off offset:2048 nt
	global_load_dwordx4 v[70:73], v[82:83], off offset:3072 nt
	global_load_dwordx2 v[74:75], v[84:85], off nt
	global_load_dwordx2 v[76:77], v[84:85], off offset:512 nt
	global_load_dwordx2 v[78:79], v[84:85], off offset:1024 nt
	global_load_dwordx2 v[80:81], v[84:85], off offset:1536 nt
	v_lshl_add_u64 v[82:83], v[82:83], 0, s[0:1]
	v_lshl_add_u64 v[84:85], v[84:85], 0, s[20:21]
	s_waitcnt vmcnt(32)
	v_lshlrev_b32_e32 v156, 16, v12
	v_and_b32_e32 v157, 0xffff0000, v12
	v_lshlrev_b32_e32 v12, 16, v13
	v_and_b32_e32 v13, 0xffff0000, v13
	v_lshlrev_b32_e32 v158, 16, v14
	v_and_b32_e32 v159, 0xffff0000, v14
	v_lshlrev_b32_e32 v14, 16, v15
	v_and_b32_e32 v15, 0xffff0000, v15
	v_lshlrev_b32_e32 v160, 16, v16
	v_and_b32_e32 v161, 0xffff0000, v16
	v_lshlrev_b32_e32 v16, 16, v17
	v_and_b32_e32 v17, 0xffff0000, v17
	v_lshlrev_b32_e32 v162, 16, v18
	v_and_b32_e32 v163, 0xffff0000, v18
	v_lshlrev_b32_e32 v18, 16, v19
	v_and_b32_e32 v19, 0xffff0000, v19
	v_pk_mul_f32 v[114:115], v[194:195], v[156:157]
	v_pk_mul_f32 v[116:117], v[196:197], v[12:13]
	v_pk_mul_f32 v[118:119], v[198:199], v[158:159]
	v_pk_mul_f32 v[120:121], v[200:201], v[14:15]
	v_pk_mul_f32 v[122:123], v[202:203], v[160:161]
	v_pk_mul_f32 v[124:125], v[204:205], v[16:17]
	v_pk_mul_f32 v[126:127], v[206:207], v[162:163]
	v_pk_mul_f32 v[128:129], v[208:209], v[18:19]
	v_pk_mul_f32 v[114:115], v[10:11], v[114:115]
	v_pk_mul_f32 v[116:117], v[10:11], v[116:117]
	v_pk_mul_f32 v[118:119], v[10:11], v[118:119]
	v_pk_mul_f32 v[120:121], v[10:11], v[120:121]
	v_pk_mul_f32 v[122:123], v[10:11], v[122:123]
	v_pk_mul_f32 v[124:125], v[10:11], v[124:125]
	v_pk_mul_f32 v[126:127], v[10:11], v[126:127]
	v_pk_mul_f32 v[128:129], v[10:11], v[128:129]
	v_pk_fma_f32 v[114:115], v[20:21], s[28:29], v[114:115] op_sel_hi:[1,0,1]
	v_pk_fma_f32 v[116:117], v[22:23], s[28:29], v[116:117] op_sel_hi:[1,0,1]
	v_pk_fma_f32 v[118:119], v[24:25], s[28:29], v[118:119] op_sel_hi:[1,0,1]
	v_pk_fma_f32 v[120:121], v[26:27], s[28:29], v[120:121] op_sel_hi:[1,0,1]
	v_pk_fma_f32 v[122:123], v[0:1], s[28:29], v[122:123] op_sel_hi:[1,0,1]
	v_pk_fma_f32 v[124:125], v[2:3], s[28:29], v[124:125] op_sel_hi:[1,0,1]
	v_pk_fma_f32 v[126:127], v[4:5], s[28:29], v[126:127] op_sel_hi:[1,0,1]
	v_pk_fma_f32 v[128:129], v[6:7], s[28:29], v[128:129] op_sel_hi:[1,0,1]
	v_add_f32_e32 v164, v114, v115
	v_add_f32_e32 v165, v116, v117
	v_add_f32_e32 v166, v118, v119
	v_add_f32_e32 v167, v120, v121
	v_add_f32_e32 v168, v122, v123
	v_add_f32_e32 v169, v124, v125
	v_add_f32_e32 v242, v126, v127
	v_add_f32_e32 v243, v128, v129
	v_add_f32_e32 v164, v164, v165
	v_add_f32_e32 v166, v166, v167
	v_add_f32_e32 v168, v168, v169
	v_add_f32_e32 v242, v242, v243
	v_add_f32_e32 v9, 0, v164
	v_add_f32_e32 v9, v9, v166
	v_add_f32_e32 v9, v9, v168
	v_add_f32_e32 v9, v9, v242
	ds_bpermute_b32 v28, v96, v9
	s_waitcnt lgkmcnt(0)
	v_add_f32_e32 v9, v9, v28
	ds_swizzle_b32 v28, v9 offset:swizzle(SWAP,16)
	s_waitcnt lgkmcnt(0)
	v_add_f32_e32 v9, v9, v28
	ds_swizzle_b32 v28, v9 offset:swizzle(SWAP,8)
	s_waitcnt lgkmcnt(0)
	v_add_f32_e32 v9, v9, v28
	ds_swizzle_b32 v28, v9 offset:swizzle(SWAP,4)
	s_waitcnt lgkmcnt(0)
	v_add_f32_e32 v9, v9, v28
	ds_swizzle_b32 v28, v9 offset:swizzle(SWAP,2)
	s_waitcnt lgkmcnt(0)
	v_add_f32_e32 v9, v9, v28
	ds_swizzle_b32 v28, v9 offset:swizzle(SWAP,1)
	s_waitcnt lgkmcnt(0)
	v_add_f32_e32 v9, v9, v28
	v_fmac_f32_e32 v114, 0xba800000, v9
	v_fmac_f32_e32 v115, 0xba800000, v9
	v_fmac_f32_e32 v116, 0xba800000, v9
	v_fmac_f32_e32 v117, 0xba800000, v9
	v_fmac_f32_e32 v118, 0xba800000, v9
	v_fmac_f32_e32 v119, 0xba800000, v9
	v_fmac_f32_e32 v120, 0xba800000, v9
	v_fmac_f32_e32 v121, 0xba800000, v9
	v_fmac_f32_e32 v122, 0xba800000, v9
	v_fmac_f32_e32 v123, 0xba800000, v9
	v_fmac_f32_e32 v124, 0xba800000, v9
	v_fmac_f32_e32 v125, 0xba800000, v9
	v_fmac_f32_e32 v126, 0xba800000, v9
	v_fmac_f32_e32 v127, 0xba800000, v9
	v_fmac_f32_e32 v128, 0xba800000, v9
	v_fmac_f32_e32 v129, 0xba800000, v9
	v_pk_mul_f32 v[244:245], v[114:115], v[114:115]
	v_pk_mul_f32 v[246:247], v[116:117], v[116:117]
	v_add_f32_e32 v244, v245, v244
	v_add_f32_e32 v246, v246, v247
	v_add_f32_e32 v164, v244, v246
	v_pk_mul_f32 v[244:245], v[118:119], v[118:119]
	v_pk_mul_f32 v[246:247], v[120:121], v[120:121]
	v_add_f32_e32 v244, v245, v244
	v_add_f32_e32 v246, v246, v247
	v_add_f32_e32 v165, v244, v246
	v_mul_f32_e32 v248, v122, v122
	v_mul_f32_e32 v249, v124, v124
	v_fmac_f32_e32 v248, v123, v123
	v_fmac_f32_e32 v249, v125, v125
	v_add_f32_e32 v166, v248, v249
	v_pk_mul_f32 v[244:245], v[126:127], v[126:127]
	v_pk_mul_f32 v[246:247], v[128:129], v[128:129]
	v_add_f32_e32 v244, v244, v245
	v_add_f32_e32 v246, v246, v247
	v_add_f32_e32 v167, v244, v246
	v_add_f32_e32 v164, v164, v165
	v_add_f32_e32 v164, v166, v164
	v_add_f32_e32 v9, v167, v164
	ds_bpermute_b32 v28, v96, v9
	s_waitcnt lgkmcnt(0)
	v_add_f32_e32 v9, v9, v28
	ds_swizzle_b32 v28, v9 offset:swizzle(SWAP,16)
	s_waitcnt lgkmcnt(0)
	v_add_f32_e32 v9, v9, v28
	ds_swizzle_b32 v28, v9 offset:swizzle(SWAP,8)
	s_waitcnt lgkmcnt(0)
	v_add_f32_e32 v9, v9, v28
	ds_swizzle_b32 v28, v9 offset:swizzle(SWAP,4)
	s_waitcnt lgkmcnt(0)
	v_add_f32_e32 v9, v9, v28
	ds_swizzle_b32 v28, v9 offset:swizzle(SWAP,2)
	s_waitcnt lgkmcnt(0)
	v_add_f32_e32 v9, v9, v28
	ds_swizzle_b32 v28, v9 offset:swizzle(SWAP,1)
	s_waitcnt lgkmcnt(0)
	v_add_f32_e32 v9, v9, v28
	v_mov_b32_e32 v28, 0x3727c5ac
	v_fmamk_f32 v9, v9, 0x3a800000, v28
	v_mul_f32_e32 v28, 0x4b800000, v9
	v_cmp_gt_f32_e32 vcc, s37, v9
	s_nop 1
	v_cndmask_b32_e32 v9, v9, v28, vcc
	v_rsq_f32_e32 v9, v9
	s_nop 0
	v_mul_f32_e32 v28, 0x45800000, v9
	v_cndmask_b32_e32 v30, v9, v28, vcc
	v_pk_mul_f32 v[114:115], v[114:115], v[30:31] op_sel_hi:[1,0]
	v_pk_mul_f32 v[116:117], v[116:117], v[30:31] op_sel_hi:[1,0]
	v_pk_fma_f32 v[20:21], v[140:141], v[114:115], v[98:99]
	v_pk_fma_f32 v[22:23], v[142:143], v[116:117], v[100:101]
	global_store_dwordx4 v[86:87], v[20:23], off sc1 nt
	v_pk_fma_f32 v[114:115], v[226:227], v[20:21], v[210:211]
	v_pk_fma_f32 v[116:117], v[228:229], v[22:23], v[212:213]
	s_nop 0
	v_cvt_pk_bf16_f32 v12, v114, v115
	v_cvt_pk_bf16_f32 v13, v116, v117
	global_store_dwordx2 v[88:89], v[12:13], off sc1
	v_pk_mul_f32 v[118:119], v[118:119], v[30:31] op_sel_hi:[1,0]
	v_pk_mul_f32 v[120:121], v[120:121], v[30:31] op_sel_hi:[1,0]
	v_pk_fma_f32 v[24:25], v[144:145], v[118:119], v[102:103]
	v_pk_fma_f32 v[26:27], v[146:147], v[120:121], v[104:105]
	global_store_dwordx4 v[86:87], v[24:27], off offset:1024 sc1 nt
	v_pk_fma_f32 v[118:119], v[230:231], v[24:25], v[214:215]
	v_pk_fma_f32 v[120:121], v[232:233], v[26:27], v[216:217]
	s_nop 0
	v_cvt_pk_bf16_f32 v14, v118, v119
	v_cvt_pk_bf16_f32 v15, v120, v121
	global_store_dwordx2 v[88:89], v[14:15], off offset:512 sc1
	v_pk_mul_f32 v[122:123], v[122:123], v[30:31] op_sel_hi:[1,0]
	v_pk_mul_f32 v[124:125], v[124:125], v[30:31] op_sel_hi:[1,0]
	v_pk_fma_f32 v[0:1], v[148:149], v[122:123], v[106:107]
	v_pk_fma_f32 v[2:3], v[150:151], v[124:125], v[108:109]
	global_store_dwordx4 v[86:87], v[0:3], off offset:2048 sc1 nt
	v_pk_fma_f32 v[122:123], v[234:235], v[0:1], v[218:219]
	v_pk_fma_f32 v[124:125], v[236:237], v[2:3], v[220:221]
	s_nop 0
	v_cvt_pk_bf16_f32 v16, v122, v123
	v_cvt_pk_bf16_f32 v17, v124, v125
	global_store_dwordx2 v[88:89], v[16:17], off offset:1024 sc1
	v_pk_mul_f32 v[126:127], v[126:127], v[30:31] op_sel_hi:[1,0]
	v_pk_mul_f32 v[128:129], v[128:129], v[30:31] op_sel_hi:[1,0]
	v_pk_fma_f32 v[4:5], v[152:153], v[126:127], v[110:111]
	v_pk_fma_f32 v[6:7], v[154:155], v[128:129], v[112:113]
	global_store_dwordx4 v[86:87], v[4:7], off offset:3072 sc1 nt
	v_pk_fma_f32 v[126:127], v[238:239], v[4:5], v[222:223]
	v_pk_fma_f32 v[128:129], v[240:241], v[6:7], v[224:225]
	s_nop 0
	v_cvt_pk_bf16_f32 v18, v126, v127
	v_cvt_pk_bf16_f32 v19, v128, v129
	global_store_dwordx2 v[88:89], v[18:19], off offset:1536 sc1
	v_lshl_add_u64 v[86:87], v[86:87], 0, s[0:1]
	v_lshl_add_u64 v[88:89], v[88:89], 0, s[20:21]
	global_load_dwordx4 v[20:23], v[82:83], off nt
	global_load_dwordx4 v[24:27], v[82:83], off offset:1024 nt
	global_load_dwordx4 v[0:3], v[82:83], off offset:2048 nt
	global_load_dwordx4 v[4:7], v[82:83], off offset:3072 nt
	global_load_dwordx2 v[12:13], v[84:85], off nt
	global_load_dwordx2 v[14:15], v[84:85], off offset:512 nt
	global_load_dwordx2 v[16:17], v[84:85], off offset:1024 nt
	global_load_dwordx2 v[18:19], v[84:85], off offset:1536 nt
	v_lshl_add_u64 v[82:83], v[82:83], 0, s[0:1]
	v_lshl_add_u64 v[84:85], v[84:85], 0, s[20:21]
	s_waitcnt vmcnt(32)
	v_lshlrev_b32_e32 v156, 16, v50
	v_and_b32_e32 v157, 0xffff0000, v50
	v_lshlrev_b32_e32 v50, 16, v51
	v_and_b32_e32 v51, 0xffff0000, v51
	v_lshlrev_b32_e32 v158, 16, v52
	v_and_b32_e32 v159, 0xffff0000, v52
	v_lshlrev_b32_e32 v52, 16, v53
	v_and_b32_e32 v53, 0xffff0000, v53
	v_lshlrev_b32_e32 v160, 16, v54
	v_and_b32_e32 v161, 0xffff0000, v54
	v_lshlrev_b32_e32 v54, 16, v55
	v_and_b32_e32 v55, 0xffff0000, v55
	v_lshlrev_b32_e32 v162, 16, v56
	v_and_b32_e32 v163, 0xffff0000, v56
	v_lshlrev_b32_e32 v56, 16, v57
	v_and_b32_e32 v57, 0xffff0000, v57
	v_pk_mul_f32 v[114:115], v[194:195], v[156:157]
	v_pk_mul_f32 v[116:117], v[196:197], v[50:51]
	v_pk_mul_f32 v[118:119], v[198:199], v[158:159]
	v_pk_mul_f32 v[120:121], v[200:201], v[52:53]
	v_pk_mul_f32 v[122:123], v[202:203], v[160:161]
	v_pk_mul_f32 v[124:125], v[204:205], v[54:55]
	v_pk_mul_f32 v[126:127], v[206:207], v[162:163]
	v_pk_mul_f32 v[128:129], v[208:209], v[56:57]
	v_pk_mul_f32 v[114:115], v[10:11], v[114:115]
	v_pk_mul_f32 v[116:117], v[10:11], v[116:117]
	v_pk_mul_f32 v[118:119], v[10:11], v[118:119]
	v_pk_mul_f32 v[120:121], v[10:11], v[120:121]
	v_pk_mul_f32 v[122:123], v[10:11], v[122:123]
	v_pk_mul_f32 v[124:125], v[10:11], v[124:125]
	v_pk_mul_f32 v[126:127], v[10:11], v[126:127]
	v_pk_mul_f32 v[128:129], v[10:11], v[128:129]
	v_pk_fma_f32 v[114:115], v[34:35], s[28:29], v[114:115] op_sel_hi:[1,0,1]
	v_pk_fma_f32 v[116:117], v[36:37], s[28:29], v[116:117] op_sel_hi:[1,0,1]
	v_pk_fma_f32 v[118:119], v[38:39], s[28:29], v[118:119] op_sel_hi:[1,0,1]
	v_pk_fma_f32 v[120:121], v[40:41], s[28:29], v[120:121] op_sel_hi:[1,0,1]
	v_pk_fma_f32 v[122:123], v[42:43], s[28:29], v[122:123] op_sel_hi:[1,0,1]
	v_pk_fma_f32 v[124:125], v[44:45], s[28:29], v[124:125] op_sel_hi:[1,0,1]
	v_pk_fma_f32 v[126:127], v[46:47], s[28:29], v[126:127] op_sel_hi:[1,0,1]
	v_pk_fma_f32 v[128:129], v[48:49], s[28:29], v[128:129] op_sel_hi:[1,0,1]
	v_add_f32_e32 v164, v114, v115
	v_add_f32_e32 v165, v116, v117
	v_add_f32_e32 v166, v118, v119
	v_add_f32_e32 v167, v120, v121
	v_add_f32_e32 v168, v122, v123
	v_add_f32_e32 v169, v124, v125
	v_add_f32_e32 v242, v126, v127
	v_add_f32_e32 v243, v128, v129
	v_add_f32_e32 v164, v164, v165
	v_add_f32_e32 v166, v166, v167
	v_add_f32_e32 v168, v168, v169
	v_add_f32_e32 v242, v242, v243
	v_add_f32_e32 v9, 0, v164
	v_add_f32_e32 v9, v9, v166
	v_add_f32_e32 v9, v9, v168
	v_add_f32_e32 v9, v9, v242
	ds_bpermute_b32 v28, v96, v9
	s_waitcnt lgkmcnt(0)
	v_add_f32_e32 v9, v9, v28
	ds_swizzle_b32 v28, v9 offset:swizzle(SWAP,16)
	s_waitcnt lgkmcnt(0)
	v_add_f32_e32 v9, v9, v28
	ds_swizzle_b32 v28, v9 offset:swizzle(SWAP,8)
	s_waitcnt lgkmcnt(0)
	v_add_f32_e32 v9, v9, v28
	ds_swizzle_b32 v28, v9 offset:swizzle(SWAP,4)
	s_waitcnt lgkmcnt(0)
	v_add_f32_e32 v9, v9, v28
	ds_swizzle_b32 v28, v9 offset:swizzle(SWAP,2)
	s_waitcnt lgkmcnt(0)
	v_add_f32_e32 v9, v9, v28
	ds_swizzle_b32 v28, v9 offset:swizzle(SWAP,1)
	s_waitcnt lgkmcnt(0)
	v_add_f32_e32 v9, v9, v28
	v_fmac_f32_e32 v114, 0xba800000, v9
	v_fmac_f32_e32 v115, 0xba800000, v9
	v_fmac_f32_e32 v116, 0xba800000, v9
	v_fmac_f32_e32 v117, 0xba800000, v9
	v_fmac_f32_e32 v118, 0xba800000, v9
	v_fmac_f32_e32 v119, 0xba800000, v9
	v_fmac_f32_e32 v120, 0xba800000, v9
	v_fmac_f32_e32 v121, 0xba800000, v9
	v_fmac_f32_e32 v122, 0xba800000, v9
	v_fmac_f32_e32 v123, 0xba800000, v9
	v_fmac_f32_e32 v124, 0xba800000, v9
	v_fmac_f32_e32 v125, 0xba800000, v9
	v_fmac_f32_e32 v126, 0xba800000, v9
	v_fmac_f32_e32 v127, 0xba800000, v9
	v_fmac_f32_e32 v128, 0xba800000, v9
	v_fmac_f32_e32 v129, 0xba800000, v9
	v_pk_mul_f32 v[244:245], v[114:115], v[114:115]
	v_pk_mul_f32 v[246:247], v[116:117], v[116:117]
	v_add_f32_e32 v244, v245, v244
	v_add_f32_e32 v246, v246, v247
	v_add_f32_e32 v164, v244, v246
	v_pk_mul_f32 v[244:245], v[118:119], v[118:119]
	v_pk_mul_f32 v[246:247], v[120:121], v[120:121]
	v_add_f32_e32 v244, v245, v244
	v_add_f32_e32 v246, v246, v247
	v_add_f32_e32 v165, v244, v246
	v_mul_f32_e32 v248, v122, v122
	v_mul_f32_e32 v249, v124, v124
	v_fmac_f32_e32 v248, v123, v123
	v_fmac_f32_e32 v249, v125, v125
	v_add_f32_e32 v166, v248, v249
	v_pk_mul_f32 v[244:245], v[126:127], v[126:127]
	v_pk_mul_f32 v[246:247], v[128:129], v[128:129]
	v_add_f32_e32 v244, v244, v245
	v_add_f32_e32 v246, v246, v247
	v_add_f32_e32 v167, v244, v246
	v_add_f32_e32 v164, v164, v165
	v_add_f32_e32 v164, v166, v164
	v_add_f32_e32 v9, v167, v164
	ds_bpermute_b32 v28, v96, v9
	s_waitcnt lgkmcnt(0)
	v_add_f32_e32 v9, v9, v28
	ds_swizzle_b32 v28, v9 offset:swizzle(SWAP,16)
	s_waitcnt lgkmcnt(0)
	v_add_f32_e32 v9, v9, v28
	ds_swizzle_b32 v28, v9 offset:swizzle(SWAP,8)
	s_waitcnt lgkmcnt(0)
	v_add_f32_e32 v9, v9, v28
	ds_swizzle_b32 v28, v9 offset:swizzle(SWAP,4)
	s_waitcnt lgkmcnt(0)
	v_add_f32_e32 v9, v9, v28
	ds_swizzle_b32 v28, v9 offset:swizzle(SWAP,2)
	s_waitcnt lgkmcnt(0)
	v_add_f32_e32 v9, v9, v28
	ds_swizzle_b32 v28, v9 offset:swizzle(SWAP,1)
	s_waitcnt lgkmcnt(0)
	v_add_f32_e32 v9, v9, v28
	v_mov_b32_e32 v28, 0x3727c5ac
	v_fmamk_f32 v9, v9, 0x3a800000, v28
	v_mul_f32_e32 v28, 0x4b800000, v9
	v_cmp_gt_f32_e32 vcc, s37, v9
	s_nop 1
	v_cndmask_b32_e32 v9, v9, v28, vcc
	v_rsq_f32_e32 v9, v9
	s_nop 0
	v_mul_f32_e32 v28, 0x45800000, v9
	v_cndmask_b32_e32 v30, v9, v28, vcc
	v_pk_mul_f32 v[114:115], v[114:115], v[30:31] op_sel_hi:[1,0]
	v_pk_mul_f32 v[116:117], v[116:117], v[30:31] op_sel_hi:[1,0]
	v_pk_fma_f32 v[34:35], v[140:141], v[114:115], v[98:99]
	v_pk_fma_f32 v[36:37], v[142:143], v[116:117], v[100:101]
	global_store_dwordx4 v[86:87], v[34:37], off sc1 nt
	v_pk_fma_f32 v[114:115], v[226:227], v[34:35], v[210:211]
	v_pk_fma_f32 v[116:117], v[228:229], v[36:37], v[212:213]
	s_nop 0
	v_cvt_pk_bf16_f32 v50, v114, v115
	v_cvt_pk_bf16_f32 v51, v116, v117
	global_store_dwordx2 v[88:89], v[50:51], off sc1
	v_pk_mul_f32 v[118:119], v[118:119], v[30:31] op_sel_hi:[1,0]
	v_pk_mul_f32 v[120:121], v[120:121], v[30:31] op_sel_hi:[1,0]
	v_pk_fma_f32 v[38:39], v[144:145], v[118:119], v[102:103]
	v_pk_fma_f32 v[40:41], v[146:147], v[120:121], v[104:105]
	global_store_dwordx4 v[86:87], v[38:41], off offset:1024 sc1 nt
	v_pk_fma_f32 v[118:119], v[230:231], v[38:39], v[214:215]
	v_pk_fma_f32 v[120:121], v[232:233], v[40:41], v[216:217]
	s_nop 0
	v_cvt_pk_bf16_f32 v52, v118, v119
	v_cvt_pk_bf16_f32 v53, v120, v121
	global_store_dwordx2 v[88:89], v[52:53], off offset:512 sc1
	v_pk_mul_f32 v[122:123], v[122:123], v[30:31] op_sel_hi:[1,0]
	v_pk_mul_f32 v[124:125], v[124:125], v[30:31] op_sel_hi:[1,0]
	v_pk_fma_f32 v[42:43], v[148:149], v[122:123], v[106:107]
	v_pk_fma_f32 v[44:45], v[150:151], v[124:125], v[108:109]
	global_store_dwordx4 v[86:87], v[42:45], off offset:2048 sc1 nt
	v_pk_fma_f32 v[122:123], v[234:235], v[42:43], v[218:219]
	v_pk_fma_f32 v[124:125], v[236:237], v[44:45], v[220:221]
	s_nop 0
	v_cvt_pk_bf16_f32 v54, v122, v123
	v_cvt_pk_bf16_f32 v55, v124, v125
	global_store_dwordx2 v[88:89], v[54:55], off offset:1024 sc1
	v_pk_mul_f32 v[126:127], v[126:127], v[30:31] op_sel_hi:[1,0]
	v_pk_mul_f32 v[128:129], v[128:129], v[30:31] op_sel_hi:[1,0]
	v_pk_fma_f32 v[46:47], v[152:153], v[126:127], v[110:111]
	v_pk_fma_f32 v[48:49], v[154:155], v[128:129], v[112:113]
	global_store_dwordx4 v[86:87], v[46:49], off offset:3072 sc1 nt
	v_pk_fma_f32 v[126:127], v[238:239], v[46:47], v[222:223]
	v_pk_fma_f32 v[128:129], v[240:241], v[48:49], v[224:225]
	s_nop 0
	v_cvt_pk_bf16_f32 v56, v126, v127
	v_cvt_pk_bf16_f32 v57, v128, v129
	global_store_dwordx2 v[88:89], v[56:57], off offset:1536 sc1
	v_lshl_add_u64 v[86:87], v[86:87], 0, s[0:1]
	v_lshl_add_u64 v[88:89], v[88:89], 0, s[20:21]
	global_load_dwordx4 v[34:37], v[82:83], off nt
	global_load_dwordx4 v[38:41], v[82:83], off offset:1024 nt
	global_load_dwordx4 v[42:45], v[82:83], off offset:2048 nt
	global_load_dwordx4 v[46:49], v[82:83], off offset:3072 nt
	global_load_dwordx2 v[50:51], v[84:85], off nt
	global_load_dwordx2 v[52:53], v[84:85], off offset:512 nt
	global_load_dwordx2 v[54:55], v[84:85], off offset:1024 nt
	global_load_dwordx2 v[56:57], v[84:85], off offset:1536 nt
	v_lshl_add_u64 v[82:83], v[82:83], 0, s[0:1]
	v_lshl_add_u64 v[84:85], v[84:85], 0, s[20:21]
	s_waitcnt vmcnt(32)
	v_lshlrev_b32_e32 v156, 16, v74
	v_and_b32_e32 v157, 0xffff0000, v74
	v_lshlrev_b32_e32 v74, 16, v75
	v_and_b32_e32 v75, 0xffff0000, v75
	v_lshlrev_b32_e32 v158, 16, v76
	v_and_b32_e32 v159, 0xffff0000, v76
	v_lshlrev_b32_e32 v76, 16, v77
	v_and_b32_e32 v77, 0xffff0000, v77
	v_lshlrev_b32_e32 v160, 16, v78
	v_and_b32_e32 v161, 0xffff0000, v78
	v_lshlrev_b32_e32 v78, 16, v79
	v_and_b32_e32 v79, 0xffff0000, v79
	v_lshlrev_b32_e32 v162, 16, v80
	v_and_b32_e32 v163, 0xffff0000, v80
	v_lshlrev_b32_e32 v80, 16, v81
	v_and_b32_e32 v81, 0xffff0000, v81
	v_pk_mul_f32 v[114:115], v[194:195], v[156:157]
	v_pk_mul_f32 v[116:117], v[196:197], v[74:75]
	v_pk_mul_f32 v[118:119], v[198:199], v[158:159]
	v_pk_mul_f32 v[120:121], v[200:201], v[76:77]
	v_pk_mul_f32 v[122:123], v[202:203], v[160:161]
	v_pk_mul_f32 v[124:125], v[204:205], v[78:79]
	v_pk_mul_f32 v[126:127], v[206:207], v[162:163]
	v_pk_mul_f32 v[128:129], v[208:209], v[80:81]
	v_pk_mul_f32 v[114:115], v[10:11], v[114:115]
	v_pk_mul_f32 v[116:117], v[10:11], v[116:117]
	v_pk_mul_f32 v[118:119], v[10:11], v[118:119]
	v_pk_mul_f32 v[120:121], v[10:11], v[120:121]
	v_pk_mul_f32 v[122:123], v[10:11], v[122:123]
	v_pk_mul_f32 v[124:125], v[10:11], v[124:125]
	v_pk_mul_f32 v[126:127], v[10:11], v[126:127]
	v_pk_mul_f32 v[128:129], v[10:11], v[128:129]
	v_pk_fma_f32 v[114:115], v[58:59], s[28:29], v[114:115] op_sel_hi:[1,0,1]
	v_pk_fma_f32 v[116:117], v[60:61], s[28:29], v[116:117] op_sel_hi:[1,0,1]
	v_pk_fma_f32 v[118:119], v[62:63], s[28:29], v[118:119] op_sel_hi:[1,0,1]
	v_pk_fma_f32 v[120:121], v[64:65], s[28:29], v[120:121] op_sel_hi:[1,0,1]
	v_pk_fma_f32 v[122:123], v[66:67], s[28:29], v[122:123] op_sel_hi:[1,0,1]
	v_pk_fma_f32 v[124:125], v[68:69], s[28:29], v[124:125] op_sel_hi:[1,0,1]
	v_pk_fma_f32 v[126:127], v[70:71], s[28:29], v[126:127] op_sel_hi:[1,0,1]
	v_pk_fma_f32 v[128:129], v[72:73], s[28:29], v[128:129] op_sel_hi:[1,0,1]
	v_add_f32_e32 v164, v114, v115
	v_add_f32_e32 v165, v116, v117
	v_add_f32_e32 v166, v118, v119
	v_add_f32_e32 v167, v120, v121
	v_add_f32_e32 v168, v122, v123
	v_add_f32_e32 v169, v124, v125
	v_add_f32_e32 v242, v126, v127
	v_add_f32_e32 v243, v128, v129
	v_add_f32_e32 v164, v164, v165
	v_add_f32_e32 v166, v166, v167
	v_add_f32_e32 v168, v168, v169
	v_add_f32_e32 v242, v242, v243
	v_add_f32_e32 v9, 0, v164
	v_add_f32_e32 v9, v9, v166
	v_add_f32_e32 v9, v9, v168
	v_add_f32_e32 v9, v9, v242
	ds_bpermute_b32 v28, v96, v9
	s_waitcnt lgkmcnt(0)
	v_add_f32_e32 v9, v9, v28
	ds_swizzle_b32 v28, v9 offset:swizzle(SWAP,16)
	s_waitcnt lgkmcnt(0)
	v_add_f32_e32 v9, v9, v28
	ds_swizzle_b32 v28, v9 offset:swizzle(SWAP,8)
	s_waitcnt lgkmcnt(0)
	v_add_f32_e32 v9, v9, v28
	ds_swizzle_b32 v28, v9 offset:swizzle(SWAP,4)
	s_waitcnt lgkmcnt(0)
	v_add_f32_e32 v9, v9, v28
	ds_swizzle_b32 v28, v9 offset:swizzle(SWAP,2)
	s_waitcnt lgkmcnt(0)
	v_add_f32_e32 v9, v9, v28
	ds_swizzle_b32 v28, v9 offset:swizzle(SWAP,1)
	s_waitcnt lgkmcnt(0)
	v_add_f32_e32 v9, v9, v28
	v_fmac_f32_e32 v114, 0xba800000, v9
	v_fmac_f32_e32 v115, 0xba800000, v9
	v_fmac_f32_e32 v116, 0xba800000, v9
	v_fmac_f32_e32 v117, 0xba800000, v9
	v_fmac_f32_e32 v118, 0xba800000, v9
	v_fmac_f32_e32 v119, 0xba800000, v9
	v_fmac_f32_e32 v120, 0xba800000, v9
	v_fmac_f32_e32 v121, 0xba800000, v9
	v_fmac_f32_e32 v122, 0xba800000, v9
	v_fmac_f32_e32 v123, 0xba800000, v9
	v_fmac_f32_e32 v124, 0xba800000, v9
	v_fmac_f32_e32 v125, 0xba800000, v9
	v_fmac_f32_e32 v126, 0xba800000, v9
	v_fmac_f32_e32 v127, 0xba800000, v9
	v_fmac_f32_e32 v128, 0xba800000, v9
	v_fmac_f32_e32 v129, 0xba800000, v9
	v_pk_mul_f32 v[244:245], v[114:115], v[114:115]
	v_pk_mul_f32 v[246:247], v[116:117], v[116:117]
	v_add_f32_e32 v244, v245, v244
	v_add_f32_e32 v246, v246, v247
	v_add_f32_e32 v164, v244, v246
	v_pk_mul_f32 v[244:245], v[118:119], v[118:119]
	v_pk_mul_f32 v[246:247], v[120:121], v[120:121]
	v_add_f32_e32 v244, v245, v244
	v_add_f32_e32 v246, v246, v247
	v_add_f32_e32 v165, v244, v246
	v_mul_f32_e32 v248, v122, v122
	v_mul_f32_e32 v249, v124, v124
	v_fmac_f32_e32 v248, v123, v123
	v_fmac_f32_e32 v249, v125, v125
	v_add_f32_e32 v166, v248, v249
	v_pk_mul_f32 v[244:245], v[126:127], v[126:127]
	v_pk_mul_f32 v[246:247], v[128:129], v[128:129]
	v_add_f32_e32 v244, v244, v245
	v_add_f32_e32 v246, v246, v247
	v_add_f32_e32 v167, v244, v246
	v_add_f32_e32 v164, v164, v165
	v_add_f32_e32 v164, v166, v164
	v_add_f32_e32 v9, v167, v164
	ds_bpermute_b32 v28, v96, v9
	s_waitcnt lgkmcnt(0)
	v_add_f32_e32 v9, v9, v28
	ds_swizzle_b32 v28, v9 offset:swizzle(SWAP,16)
	s_waitcnt lgkmcnt(0)
	v_add_f32_e32 v9, v9, v28
	ds_swizzle_b32 v28, v9 offset:swizzle(SWAP,8)
	s_waitcnt lgkmcnt(0)
	v_add_f32_e32 v9, v9, v28
	ds_swizzle_b32 v28, v9 offset:swizzle(SWAP,4)
	s_waitcnt lgkmcnt(0)
	v_add_f32_e32 v9, v9, v28
	ds_swizzle_b32 v28, v9 offset:swizzle(SWAP,2)
	s_waitcnt lgkmcnt(0)
	v_add_f32_e32 v9, v9, v28
	ds_swizzle_b32 v28, v9 offset:swizzle(SWAP,1)
	s_waitcnt lgkmcnt(0)
	v_add_f32_e32 v9, v9, v28
	v_mov_b32_e32 v28, 0x3727c5ac
	v_fmamk_f32 v9, v9, 0x3a800000, v28
	v_mul_f32_e32 v28, 0x4b800000, v9
	v_cmp_gt_f32_e32 vcc, s37, v9
	s_nop 1
	v_cndmask_b32_e32 v9, v9, v28, vcc
	v_rsq_f32_e32 v9, v9
	s_nop 0
	v_mul_f32_e32 v28, 0x45800000, v9
	v_cndmask_b32_e32 v30, v9, v28, vcc
	v_pk_mul_f32 v[114:115], v[114:115], v[30:31] op_sel_hi:[1,0]
	v_pk_mul_f32 v[116:117], v[116:117], v[30:31] op_sel_hi:[1,0]
	v_pk_fma_f32 v[58:59], v[140:141], v[114:115], v[98:99]
	v_pk_fma_f32 v[60:61], v[142:143], v[116:117], v[100:101]
	global_store_dwordx4 v[86:87], v[58:61], off sc1 nt
	v_pk_fma_f32 v[114:115], v[226:227], v[58:59], v[210:211]
	v_pk_fma_f32 v[116:117], v[228:229], v[60:61], v[212:213]
	s_nop 0
	v_cvt_pk_bf16_f32 v74, v114, v115
	v_cvt_pk_bf16_f32 v75, v116, v117
	global_store_dwordx2 v[88:89], v[74:75], off sc1
	v_pk_mul_f32 v[118:119], v[118:119], v[30:31] op_sel_hi:[1,0]
	v_pk_mul_f32 v[120:121], v[120:121], v[30:31] op_sel_hi:[1,0]
	v_pk_fma_f32 v[62:63], v[144:145], v[118:119], v[102:103]
	v_pk_fma_f32 v[64:65], v[146:147], v[120:121], v[104:105]
	global_store_dwordx4 v[86:87], v[62:65], off offset:1024 sc1 nt
	v_pk_fma_f32 v[118:119], v[230:231], v[62:63], v[214:215]
	v_pk_fma_f32 v[120:121], v[232:233], v[64:65], v[216:217]
	s_nop 0
	v_cvt_pk_bf16_f32 v76, v118, v119
	v_cvt_pk_bf16_f32 v77, v120, v121
	global_store_dwordx2 v[88:89], v[76:77], off offset:512 sc1
	v_pk_mul_f32 v[122:123], v[122:123], v[30:31] op_sel_hi:[1,0]
	v_pk_mul_f32 v[124:125], v[124:125], v[30:31] op_sel_hi:[1,0]
	v_pk_fma_f32 v[66:67], v[148:149], v[122:123], v[106:107]
	v_pk_fma_f32 v[68:69], v[150:151], v[124:125], v[108:109]
	global_store_dwordx4 v[86:87], v[66:69], off offset:2048 sc1 nt
	v_pk_fma_f32 v[122:123], v[234:235], v[66:67], v[218:219]
	v_pk_fma_f32 v[124:125], v[236:237], v[68:69], v[220:221]
	s_nop 0
	v_cvt_pk_bf16_f32 v78, v122, v123
	v_cvt_pk_bf16_f32 v79, v124, v125
	global_store_dwordx2 v[88:89], v[78:79], off offset:1024 sc1
	v_pk_mul_f32 v[126:127], v[126:127], v[30:31] op_sel_hi:[1,0]
	v_pk_mul_f32 v[128:129], v[128:129], v[30:31] op_sel_hi:[1,0]
	v_pk_fma_f32 v[70:71], v[152:153], v[126:127], v[110:111]
	v_pk_fma_f32 v[72:73], v[154:155], v[128:129], v[112:113]
	global_store_dwordx4 v[86:87], v[70:73], off offset:3072 sc1 nt
	v_pk_fma_f32 v[126:127], v[238:239], v[70:71], v[222:223]
	v_pk_fma_f32 v[128:129], v[240:241], v[72:73], v[224:225]
	s_nop 0
	v_cvt_pk_bf16_f32 v80, v126, v127
	v_cvt_pk_bf16_f32 v81, v128, v129
	global_store_dwordx2 v[88:89], v[80:81], off offset:1536 sc1
	v_lshl_add_u64 v[86:87], v[86:87], 0, s[0:1]
	v_lshl_add_u64 v[88:89], v[88:89], 0, s[20:21]
	global_load_dwordx4 v[58:61], v[82:83], off nt
	global_load_dwordx4 v[62:65], v[82:83], off offset:1024 nt
	global_load_dwordx4 v[66:69], v[82:83], off offset:2048 nt
	global_load_dwordx4 v[70:73], v[82:83], off offset:3072 nt
	global_load_dwordx2 v[74:75], v[84:85], off nt
	global_load_dwordx2 v[76:77], v[84:85], off offset:512 nt
	global_load_dwordx2 v[78:79], v[84:85], off offset:1024 nt
	global_load_dwordx2 v[80:81], v[84:85], off offset:1536 nt
	v_lshl_add_u64 v[82:83], v[82:83], 0, s[0:1]
	v_lshl_add_u64 v[84:85], v[84:85], 0, s[20:21]
	s_waitcnt vmcnt(32)
	v_lshlrev_b32_e32 v156, 16, v12
	v_and_b32_e32 v157, 0xffff0000, v12
	v_lshlrev_b32_e32 v12, 16, v13
	v_and_b32_e32 v13, 0xffff0000, v13
	v_lshlrev_b32_e32 v158, 16, v14
	v_and_b32_e32 v159, 0xffff0000, v14
	v_lshlrev_b32_e32 v14, 16, v15
	v_and_b32_e32 v15, 0xffff0000, v15
	v_lshlrev_b32_e32 v160, 16, v16
	v_and_b32_e32 v161, 0xffff0000, v16
	v_lshlrev_b32_e32 v16, 16, v17
	v_and_b32_e32 v17, 0xffff0000, v17
	v_lshlrev_b32_e32 v162, 16, v18
	v_and_b32_e32 v163, 0xffff0000, v18
	v_lshlrev_b32_e32 v18, 16, v19
	v_and_b32_e32 v19, 0xffff0000, v19
	v_pk_mul_f32 v[114:115], v[194:195], v[156:157]
	v_pk_mul_f32 v[116:117], v[196:197], v[12:13]
	v_pk_mul_f32 v[118:119], v[198:199], v[158:159]
	v_pk_mul_f32 v[120:121], v[200:201], v[14:15]
	v_pk_mul_f32 v[122:123], v[202:203], v[160:161]
	v_pk_mul_f32 v[124:125], v[204:205], v[16:17]
	v_pk_mul_f32 v[126:127], v[206:207], v[162:163]
	v_pk_mul_f32 v[128:129], v[208:209], v[18:19]
	v_pk_mul_f32 v[114:115], v[10:11], v[114:115]
	v_pk_mul_f32 v[116:117], v[10:11], v[116:117]
	v_pk_mul_f32 v[118:119], v[10:11], v[118:119]
	v_pk_mul_f32 v[120:121], v[10:11], v[120:121]
	v_pk_mul_f32 v[122:123], v[10:11], v[122:123]
	v_pk_mul_f32 v[124:125], v[10:11], v[124:125]
	v_pk_mul_f32 v[126:127], v[10:11], v[126:127]
	v_pk_mul_f32 v[128:129], v[10:11], v[128:129]
	v_pk_fma_f32 v[114:115], v[20:21], s[28:29], v[114:115] op_sel_hi:[1,0,1]
	v_pk_fma_f32 v[116:117], v[22:23], s[28:29], v[116:117] op_sel_hi:[1,0,1]
	v_pk_fma_f32 v[118:119], v[24:25], s[28:29], v[118:119] op_sel_hi:[1,0,1]
	v_pk_fma_f32 v[120:121], v[26:27], s[28:29], v[120:121] op_sel_hi:[1,0,1]
	v_pk_fma_f32 v[122:123], v[0:1], s[28:29], v[122:123] op_sel_hi:[1,0,1]
	v_pk_fma_f32 v[124:125], v[2:3], s[28:29], v[124:125] op_sel_hi:[1,0,1]
	v_pk_fma_f32 v[126:127], v[4:5], s[28:29], v[126:127] op_sel_hi:[1,0,1]
	v_pk_fma_f32 v[128:129], v[6:7], s[28:29], v[128:129] op_sel_hi:[1,0,1]
	v_add_f32_e32 v164, v114, v115
	v_add_f32_e32 v165, v116, v117
	v_add_f32_e32 v166, v118, v119
	v_add_f32_e32 v167, v120, v121
	v_add_f32_e32 v168, v122, v123
	v_add_f32_e32 v169, v124, v125
	v_add_f32_e32 v242, v126, v127
	v_add_f32_e32 v243, v128, v129
	v_add_f32_e32 v164, v164, v165
	v_add_f32_e32 v166, v166, v167
	v_add_f32_e32 v168, v168, v169
	v_add_f32_e32 v242, v242, v243
	v_add_f32_e32 v9, 0, v164
	v_add_f32_e32 v9, v9, v166
	v_add_f32_e32 v9, v9, v168
	v_add_f32_e32 v9, v9, v242
	ds_bpermute_b32 v28, v96, v9
	s_waitcnt lgkmcnt(0)
	v_add_f32_e32 v9, v9, v28
	ds_swizzle_b32 v28, v9 offset:swizzle(SWAP,16)
	s_waitcnt lgkmcnt(0)
	v_add_f32_e32 v9, v9, v28
	ds_swizzle_b32 v28, v9 offset:swizzle(SWAP,8)
	s_waitcnt lgkmcnt(0)
	v_add_f32_e32 v9, v9, v28
	ds_swizzle_b32 v28, v9 offset:swizzle(SWAP,4)
	s_waitcnt lgkmcnt(0)
	v_add_f32_e32 v9, v9, v28
	ds_swizzle_b32 v28, v9 offset:swizzle(SWAP,2)
	s_waitcnt lgkmcnt(0)
	v_add_f32_e32 v9, v9, v28
	ds_swizzle_b32 v28, v9 offset:swizzle(SWAP,1)
	s_waitcnt lgkmcnt(0)
	v_add_f32_e32 v9, v9, v28
	v_fmac_f32_e32 v114, 0xba800000, v9
	v_fmac_f32_e32 v115, 0xba800000, v9
	v_fmac_f32_e32 v116, 0xba800000, v9
	v_fmac_f32_e32 v117, 0xba800000, v9
	v_fmac_f32_e32 v118, 0xba800000, v9
	v_fmac_f32_e32 v119, 0xba800000, v9
	v_fmac_f32_e32 v120, 0xba800000, v9
	v_fmac_f32_e32 v121, 0xba800000, v9
	v_fmac_f32_e32 v122, 0xba800000, v9
	v_fmac_f32_e32 v123, 0xba800000, v9
	v_fmac_f32_e32 v124, 0xba800000, v9
	v_fmac_f32_e32 v125, 0xba800000, v9
	v_fmac_f32_e32 v126, 0xba800000, v9
	v_fmac_f32_e32 v127, 0xba800000, v9
	v_fmac_f32_e32 v128, 0xba800000, v9
	v_fmac_f32_e32 v129, 0xba800000, v9
	v_pk_mul_f32 v[244:245], v[114:115], v[114:115]
	v_pk_mul_f32 v[246:247], v[116:117], v[116:117]
	v_add_f32_e32 v244, v245, v244
	v_add_f32_e32 v246, v246, v247
	v_add_f32_e32 v164, v244, v246
	v_pk_mul_f32 v[244:245], v[118:119], v[118:119]
	v_pk_mul_f32 v[246:247], v[120:121], v[120:121]
	v_add_f32_e32 v244, v245, v244
	v_add_f32_e32 v246, v246, v247
	v_add_f32_e32 v165, v244, v246
	v_mul_f32_e32 v248, v122, v122
	v_mul_f32_e32 v249, v124, v124
	v_fmac_f32_e32 v248, v123, v123
	v_fmac_f32_e32 v249, v125, v125
	v_add_f32_e32 v166, v248, v249
	v_pk_mul_f32 v[244:245], v[126:127], v[126:127]
	v_pk_mul_f32 v[246:247], v[128:129], v[128:129]
	v_add_f32_e32 v244, v244, v245
	v_add_f32_e32 v246, v246, v247
	v_add_f32_e32 v167, v244, v246
	v_add_f32_e32 v164, v164, v165
	v_add_f32_e32 v164, v166, v164
	v_add_f32_e32 v9, v167, v164
	ds_bpermute_b32 v28, v96, v9
	s_waitcnt lgkmcnt(0)
	v_add_f32_e32 v9, v9, v28
	ds_swizzle_b32 v28, v9 offset:swizzle(SWAP,16)
	s_waitcnt lgkmcnt(0)
	v_add_f32_e32 v9, v9, v28
	ds_swizzle_b32 v28, v9 offset:swizzle(SWAP,8)
	s_waitcnt lgkmcnt(0)
	v_add_f32_e32 v9, v9, v28
	ds_swizzle_b32 v28, v9 offset:swizzle(SWAP,4)
	s_waitcnt lgkmcnt(0)
	v_add_f32_e32 v9, v9, v28
	ds_swizzle_b32 v28, v9 offset:swizzle(SWAP,2)
	s_waitcnt lgkmcnt(0)
	v_add_f32_e32 v9, v9, v28
	ds_swizzle_b32 v28, v9 offset:swizzle(SWAP,1)
	s_waitcnt lgkmcnt(0)
	v_add_f32_e32 v9, v9, v28
	v_mov_b32_e32 v28, 0x3727c5ac
	v_fmamk_f32 v9, v9, 0x3a800000, v28
	v_mul_f32_e32 v28, 0x4b800000, v9
	v_cmp_gt_f32_e32 vcc, s37, v9
	s_nop 1
	v_cndmask_b32_e32 v9, v9, v28, vcc
	v_rsq_f32_e32 v9, v9
	s_nop 0
	v_mul_f32_e32 v28, 0x45800000, v9
	v_cndmask_b32_e32 v30, v9, v28, vcc
	v_pk_mul_f32 v[114:115], v[114:115], v[30:31] op_sel_hi:[1,0]
	v_pk_mul_f32 v[116:117], v[116:117], v[30:31] op_sel_hi:[1,0]
	v_pk_fma_f32 v[20:21], v[140:141], v[114:115], v[98:99]
	v_pk_fma_f32 v[22:23], v[142:143], v[116:117], v[100:101]
	global_store_dwordx4 v[86:87], v[20:23], off sc1 nt
	v_pk_fma_f32 v[114:115], v[226:227], v[20:21], v[210:211]
	v_pk_fma_f32 v[116:117], v[228:229], v[22:23], v[212:213]
	s_nop 0
	v_cvt_pk_bf16_f32 v12, v114, v115
	v_cvt_pk_bf16_f32 v13, v116, v117
	global_store_dwordx2 v[88:89], v[12:13], off sc1
	v_pk_mul_f32 v[118:119], v[118:119], v[30:31] op_sel_hi:[1,0]
	v_pk_mul_f32 v[120:121], v[120:121], v[30:31] op_sel_hi:[1,0]
	v_pk_fma_f32 v[24:25], v[144:145], v[118:119], v[102:103]
	v_pk_fma_f32 v[26:27], v[146:147], v[120:121], v[104:105]
	global_store_dwordx4 v[86:87], v[24:27], off offset:1024 sc1 nt
	v_pk_fma_f32 v[118:119], v[230:231], v[24:25], v[214:215]
	v_pk_fma_f32 v[120:121], v[232:233], v[26:27], v[216:217]
	s_nop 0
	v_cvt_pk_bf16_f32 v14, v118, v119
	v_cvt_pk_bf16_f32 v15, v120, v121
	global_store_dwordx2 v[88:89], v[14:15], off offset:512 sc1
	v_pk_mul_f32 v[122:123], v[122:123], v[30:31] op_sel_hi:[1,0]
	v_pk_mul_f32 v[124:125], v[124:125], v[30:31] op_sel_hi:[1,0]
	v_pk_fma_f32 v[0:1], v[148:149], v[122:123], v[106:107]
	v_pk_fma_f32 v[2:3], v[150:151], v[124:125], v[108:109]
	global_store_dwordx4 v[86:87], v[0:3], off offset:2048 sc1 nt
	v_pk_fma_f32 v[122:123], v[234:235], v[0:1], v[218:219]
	v_pk_fma_f32 v[124:125], v[236:237], v[2:3], v[220:221]
	s_nop 0
	v_cvt_pk_bf16_f32 v16, v122, v123
	v_cvt_pk_bf16_f32 v17, v124, v125
	global_store_dwordx2 v[88:89], v[16:17], off offset:1024 sc1
	v_pk_mul_f32 v[126:127], v[126:127], v[30:31] op_sel_hi:[1,0]
	v_pk_mul_f32 v[128:129], v[128:129], v[30:31] op_sel_hi:[1,0]
	v_pk_fma_f32 v[4:5], v[152:153], v[126:127], v[110:111]
	v_pk_fma_f32 v[6:7], v[154:155], v[128:129], v[112:113]
	global_store_dwordx4 v[86:87], v[4:7], off offset:3072 sc1 nt
	v_pk_fma_f32 v[126:127], v[238:239], v[4:5], v[222:223]
	v_pk_fma_f32 v[128:129], v[240:241], v[6:7], v[224:225]
	s_nop 0
	v_cvt_pk_bf16_f32 v18, v126, v127
	v_cvt_pk_bf16_f32 v19, v128, v129
	global_store_dwordx2 v[88:89], v[18:19], off offset:1536 sc1
	v_lshl_add_u64 v[86:87], v[86:87], 0, s[0:1]
	v_lshl_add_u64 v[88:89], v[88:89], 0, s[20:21]
	global_load_dwordx4 v[20:23], v[82:83], off nt
	global_load_dwordx4 v[24:27], v[82:83], off offset:1024 nt
	global_load_dwordx4 v[0:3], v[82:83], off offset:2048 nt
	global_load_dwordx4 v[4:7], v[82:83], off offset:3072 nt
	global_load_dwordx2 v[12:13], v[84:85], off nt
	global_load_dwordx2 v[14:15], v[84:85], off offset:512 nt
	global_load_dwordx2 v[16:17], v[84:85], off offset:1024 nt
	global_load_dwordx2 v[18:19], v[84:85], off offset:1536 nt
	v_lshl_add_u64 v[82:83], v[82:83], 0, s[0:1]
	v_lshl_add_u64 v[84:85], v[84:85], 0, s[20:21]
	s_waitcnt vmcnt(32)
	v_lshlrev_b32_e32 v156, 16, v50
	v_and_b32_e32 v157, 0xffff0000, v50
	v_lshlrev_b32_e32 v50, 16, v51
	v_and_b32_e32 v51, 0xffff0000, v51
	v_lshlrev_b32_e32 v158, 16, v52
	v_and_b32_e32 v159, 0xffff0000, v52
	v_lshlrev_b32_e32 v52, 16, v53
	v_and_b32_e32 v53, 0xffff0000, v53
	v_lshlrev_b32_e32 v160, 16, v54
	v_and_b32_e32 v161, 0xffff0000, v54
	v_lshlrev_b32_e32 v54, 16, v55
	v_and_b32_e32 v55, 0xffff0000, v55
	v_lshlrev_b32_e32 v162, 16, v56
	v_and_b32_e32 v163, 0xffff0000, v56
	v_lshlrev_b32_e32 v56, 16, v57
	v_and_b32_e32 v57, 0xffff0000, v57
	v_pk_mul_f32 v[114:115], v[194:195], v[156:157]
	v_pk_mul_f32 v[116:117], v[196:197], v[50:51]
	v_pk_mul_f32 v[118:119], v[198:199], v[158:159]
	v_pk_mul_f32 v[120:121], v[200:201], v[52:53]
	v_pk_mul_f32 v[122:123], v[202:203], v[160:161]
	v_pk_mul_f32 v[124:125], v[204:205], v[54:55]
	v_pk_mul_f32 v[126:127], v[206:207], v[162:163]
	v_pk_mul_f32 v[128:129], v[208:209], v[56:57]
	v_pk_mul_f32 v[114:115], v[10:11], v[114:115]
	v_pk_mul_f32 v[116:117], v[10:11], v[116:117]
	v_pk_mul_f32 v[118:119], v[10:11], v[118:119]
	v_pk_mul_f32 v[120:121], v[10:11], v[120:121]
	v_pk_mul_f32 v[122:123], v[10:11], v[122:123]
	v_pk_mul_f32 v[124:125], v[10:11], v[124:125]
	v_pk_mul_f32 v[126:127], v[10:11], v[126:127]
	v_pk_mul_f32 v[128:129], v[10:11], v[128:129]
	v_pk_fma_f32 v[114:115], v[34:35], s[28:29], v[114:115] op_sel_hi:[1,0,1]
	v_pk_fma_f32 v[116:117], v[36:37], s[28:29], v[116:117] op_sel_hi:[1,0,1]
	v_pk_fma_f32 v[118:119], v[38:39], s[28:29], v[118:119] op_sel_hi:[1,0,1]
	v_pk_fma_f32 v[120:121], v[40:41], s[28:29], v[120:121] op_sel_hi:[1,0,1]
	v_pk_fma_f32 v[122:123], v[42:43], s[28:29], v[122:123] op_sel_hi:[1,0,1]
	v_pk_fma_f32 v[124:125], v[44:45], s[28:29], v[124:125] op_sel_hi:[1,0,1]
	v_pk_fma_f32 v[126:127], v[46:47], s[28:29], v[126:127] op_sel_hi:[1,0,1]
	v_pk_fma_f32 v[128:129], v[48:49], s[28:29], v[128:129] op_sel_hi:[1,0,1]
	v_add_f32_e32 v164, v114, v115
	v_add_f32_e32 v165, v116, v117
	v_add_f32_e32 v166, v118, v119
	v_add_f32_e32 v167, v120, v121
	v_add_f32_e32 v168, v122, v123
	v_add_f32_e32 v169, v124, v125
	v_add_f32_e32 v242, v126, v127
	v_add_f32_e32 v243, v128, v129
	v_add_f32_e32 v164, v164, v165
	v_add_f32_e32 v166, v166, v167
	v_add_f32_e32 v168, v168, v169
	v_add_f32_e32 v242, v242, v243
	v_add_f32_e32 v9, 0, v164
	v_add_f32_e32 v9, v9, v166
	v_add_f32_e32 v9, v9, v168
	v_add_f32_e32 v9, v9, v242
	ds_bpermute_b32 v28, v96, v9
	s_waitcnt lgkmcnt(0)
	v_add_f32_e32 v9, v9, v28
	ds_swizzle_b32 v28, v9 offset:swizzle(SWAP,16)
	s_waitcnt lgkmcnt(0)
	v_add_f32_e32 v9, v9, v28
	ds_swizzle_b32 v28, v9 offset:swizzle(SWAP,8)
	s_waitcnt lgkmcnt(0)
	v_add_f32_e32 v9, v9, v28
	ds_swizzle_b32 v28, v9 offset:swizzle(SWAP,4)
	s_waitcnt lgkmcnt(0)
	v_add_f32_e32 v9, v9, v28
	ds_swizzle_b32 v28, v9 offset:swizzle(SWAP,2)
	s_waitcnt lgkmcnt(0)
	v_add_f32_e32 v9, v9, v28
	ds_swizzle_b32 v28, v9 offset:swizzle(SWAP,1)
	s_waitcnt lgkmcnt(0)
	v_add_f32_e32 v9, v9, v28
	v_fmac_f32_e32 v114, 0xba800000, v9
	v_fmac_f32_e32 v115, 0xba800000, v9
	v_fmac_f32_e32 v116, 0xba800000, v9
	v_fmac_f32_e32 v117, 0xba800000, v9
	v_fmac_f32_e32 v118, 0xba800000, v9
	v_fmac_f32_e32 v119, 0xba800000, v9
	v_fmac_f32_e32 v120, 0xba800000, v9
	v_fmac_f32_e32 v121, 0xba800000, v9
	v_fmac_f32_e32 v122, 0xba800000, v9
	v_fmac_f32_e32 v123, 0xba800000, v9
	v_fmac_f32_e32 v124, 0xba800000, v9
	v_fmac_f32_e32 v125, 0xba800000, v9
	v_fmac_f32_e32 v126, 0xba800000, v9
	v_fmac_f32_e32 v127, 0xba800000, v9
	v_fmac_f32_e32 v128, 0xba800000, v9
	v_fmac_f32_e32 v129, 0xba800000, v9
	v_pk_mul_f32 v[244:245], v[114:115], v[114:115]
	v_pk_mul_f32 v[246:247], v[116:117], v[116:117]
	v_add_f32_e32 v244, v245, v244
	v_add_f32_e32 v246, v246, v247
	v_add_f32_e32 v164, v244, v246
	v_pk_mul_f32 v[244:245], v[118:119], v[118:119]
	v_pk_mul_f32 v[246:247], v[120:121], v[120:121]
	v_add_f32_e32 v244, v245, v244
	v_add_f32_e32 v246, v246, v247
	v_add_f32_e32 v165, v244, v246
	v_mul_f32_e32 v248, v122, v122
	v_mul_f32_e32 v249, v124, v124
	v_fmac_f32_e32 v248, v123, v123
	v_fmac_f32_e32 v249, v125, v125
	v_add_f32_e32 v166, v248, v249
	v_pk_mul_f32 v[244:245], v[126:127], v[126:127]
	v_pk_mul_f32 v[246:247], v[128:129], v[128:129]
	v_add_f32_e32 v244, v244, v245
	v_add_f32_e32 v246, v246, v247
	v_add_f32_e32 v167, v244, v246
	v_add_f32_e32 v164, v164, v165
	v_add_f32_e32 v164, v166, v164
	v_add_f32_e32 v9, v167, v164
	ds_bpermute_b32 v28, v96, v9
	s_waitcnt lgkmcnt(0)
	v_add_f32_e32 v9, v9, v28
	ds_swizzle_b32 v28, v9 offset:swizzle(SWAP,16)
	s_waitcnt lgkmcnt(0)
	v_add_f32_e32 v9, v9, v28
	ds_swizzle_b32 v28, v9 offset:swizzle(SWAP,8)
	s_waitcnt lgkmcnt(0)
	v_add_f32_e32 v9, v9, v28
	ds_swizzle_b32 v28, v9 offset:swizzle(SWAP,4)
	s_waitcnt lgkmcnt(0)
	v_add_f32_e32 v9, v9, v28
	ds_swizzle_b32 v28, v9 offset:swizzle(SWAP,2)
	s_waitcnt lgkmcnt(0)
	v_add_f32_e32 v9, v9, v28
	ds_swizzle_b32 v28, v9 offset:swizzle(SWAP,1)
	s_waitcnt lgkmcnt(0)
	v_add_f32_e32 v9, v9, v28
	v_mov_b32_e32 v28, 0x3727c5ac
	v_fmamk_f32 v9, v9, 0x3a800000, v28
	v_mul_f32_e32 v28, 0x4b800000, v9
	v_cmp_gt_f32_e32 vcc, s37, v9
	s_nop 1
	v_cndmask_b32_e32 v9, v9, v28, vcc
	v_rsq_f32_e32 v9, v9
	s_nop 0
	v_mul_f32_e32 v28, 0x45800000, v9
	v_cndmask_b32_e32 v30, v9, v28, vcc
	v_pk_mul_f32 v[114:115], v[114:115], v[30:31] op_sel_hi:[1,0]
	v_pk_mul_f32 v[116:117], v[116:117], v[30:31] op_sel_hi:[1,0]
	v_pk_fma_f32 v[34:35], v[140:141], v[114:115], v[98:99]
	v_pk_fma_f32 v[36:37], v[142:143], v[116:117], v[100:101]
	global_store_dwordx4 v[86:87], v[34:37], off sc1 nt
	v_pk_fma_f32 v[114:115], v[226:227], v[34:35], v[210:211]
	v_pk_fma_f32 v[116:117], v[228:229], v[36:37], v[212:213]
	s_nop 0
	v_cvt_pk_bf16_f32 v50, v114, v115
	v_cvt_pk_bf16_f32 v51, v116, v117
	global_store_dwordx2 v[88:89], v[50:51], off sc1
	v_pk_mul_f32 v[118:119], v[118:119], v[30:31] op_sel_hi:[1,0]
	v_pk_mul_f32 v[120:121], v[120:121], v[30:31] op_sel_hi:[1,0]
	v_pk_fma_f32 v[38:39], v[144:145], v[118:119], v[102:103]
	v_pk_fma_f32 v[40:41], v[146:147], v[120:121], v[104:105]
	global_store_dwordx4 v[86:87], v[38:41], off offset:1024 sc1 nt
	v_pk_fma_f32 v[118:119], v[230:231], v[38:39], v[214:215]
	v_pk_fma_f32 v[120:121], v[232:233], v[40:41], v[216:217]
	s_nop 0
	v_cvt_pk_bf16_f32 v52, v118, v119
	v_cvt_pk_bf16_f32 v53, v120, v121
	global_store_dwordx2 v[88:89], v[52:53], off offset:512 sc1
	v_pk_mul_f32 v[122:123], v[122:123], v[30:31] op_sel_hi:[1,0]
	v_pk_mul_f32 v[124:125], v[124:125], v[30:31] op_sel_hi:[1,0]
	v_pk_fma_f32 v[42:43], v[148:149], v[122:123], v[106:107]
	v_pk_fma_f32 v[44:45], v[150:151], v[124:125], v[108:109]
	global_store_dwordx4 v[86:87], v[42:45], off offset:2048 sc1 nt
	v_pk_fma_f32 v[122:123], v[234:235], v[42:43], v[218:219]
	v_pk_fma_f32 v[124:125], v[236:237], v[44:45], v[220:221]
	s_nop 0
	v_cvt_pk_bf16_f32 v54, v122, v123
	v_cvt_pk_bf16_f32 v55, v124, v125
	global_store_dwordx2 v[88:89], v[54:55], off offset:1024 sc1
	v_pk_mul_f32 v[126:127], v[126:127], v[30:31] op_sel_hi:[1,0]
	v_pk_mul_f32 v[128:129], v[128:129], v[30:31] op_sel_hi:[1,0]
	v_pk_fma_f32 v[46:47], v[152:153], v[126:127], v[110:111]
	v_pk_fma_f32 v[48:49], v[154:155], v[128:129], v[112:113]
	global_store_dwordx4 v[86:87], v[46:49], off offset:3072 sc1 nt
	v_pk_fma_f32 v[126:127], v[238:239], v[46:47], v[222:223]
	v_pk_fma_f32 v[128:129], v[240:241], v[48:49], v[224:225]
	s_nop 0
	v_cvt_pk_bf16_f32 v56, v126, v127
	v_cvt_pk_bf16_f32 v57, v128, v129
	global_store_dwordx2 v[88:89], v[56:57], off offset:1536 sc1
	v_lshl_add_u64 v[86:87], v[86:87], 0, s[0:1]
	v_lshl_add_u64 v[88:89], v[88:89], 0, s[20:21]
	global_load_dwordx4 v[34:37], v[82:83], off nt
	global_load_dwordx4 v[38:41], v[82:83], off offset:1024 nt
	global_load_dwordx4 v[42:45], v[82:83], off offset:2048 nt
	global_load_dwordx4 v[46:49], v[82:83], off offset:3072 nt
	global_load_dwordx2 v[50:51], v[84:85], off nt
	global_load_dwordx2 v[52:53], v[84:85], off offset:512 nt
	global_load_dwordx2 v[54:55], v[84:85], off offset:1024 nt
	global_load_dwordx2 v[56:57], v[84:85], off offset:1536 nt
	v_lshl_add_u64 v[82:83], v[82:83], 0, s[0:1]
	v_lshl_add_u64 v[84:85], v[84:85], 0, s[20:21]
	s_waitcnt vmcnt(32)
	v_lshlrev_b32_e32 v156, 16, v74
	v_and_b32_e32 v157, 0xffff0000, v74
	v_lshlrev_b32_e32 v74, 16, v75
	v_and_b32_e32 v75, 0xffff0000, v75
	v_lshlrev_b32_e32 v158, 16, v76
	v_and_b32_e32 v159, 0xffff0000, v76
	v_lshlrev_b32_e32 v76, 16, v77
	v_and_b32_e32 v77, 0xffff0000, v77
	v_lshlrev_b32_e32 v160, 16, v78
	v_and_b32_e32 v161, 0xffff0000, v78
	v_lshlrev_b32_e32 v78, 16, v79
	v_and_b32_e32 v79, 0xffff0000, v79
	v_lshlrev_b32_e32 v162, 16, v80
	v_and_b32_e32 v163, 0xffff0000, v80
	v_lshlrev_b32_e32 v80, 16, v81
	v_and_b32_e32 v81, 0xffff0000, v81
	v_pk_mul_f32 v[114:115], v[194:195], v[156:157]
	v_pk_mul_f32 v[116:117], v[196:197], v[74:75]
	v_pk_mul_f32 v[118:119], v[198:199], v[158:159]
	v_pk_mul_f32 v[120:121], v[200:201], v[76:77]
	v_pk_mul_f32 v[122:123], v[202:203], v[160:161]
	v_pk_mul_f32 v[124:125], v[204:205], v[78:79]
	v_pk_mul_f32 v[126:127], v[206:207], v[162:163]
	v_pk_mul_f32 v[128:129], v[208:209], v[80:81]
	v_pk_mul_f32 v[114:115], v[10:11], v[114:115]
	v_pk_mul_f32 v[116:117], v[10:11], v[116:117]
	v_pk_mul_f32 v[118:119], v[10:11], v[118:119]
	v_pk_mul_f32 v[120:121], v[10:11], v[120:121]
	v_pk_mul_f32 v[122:123], v[10:11], v[122:123]
	v_pk_mul_f32 v[124:125], v[10:11], v[124:125]
	v_pk_mul_f32 v[126:127], v[10:11], v[126:127]
	v_pk_mul_f32 v[128:129], v[10:11], v[128:129]
	v_pk_fma_f32 v[114:115], v[58:59], s[28:29], v[114:115] op_sel_hi:[1,0,1]
	v_pk_fma_f32 v[116:117], v[60:61], s[28:29], v[116:117] op_sel_hi:[1,0,1]
	v_pk_fma_f32 v[118:119], v[62:63], s[28:29], v[118:119] op_sel_hi:[1,0,1]
	v_pk_fma_f32 v[120:121], v[64:65], s[28:29], v[120:121] op_sel_hi:[1,0,1]
	v_pk_fma_f32 v[122:123], v[66:67], s[28:29], v[122:123] op_sel_hi:[1,0,1]
	v_pk_fma_f32 v[124:125], v[68:69], s[28:29], v[124:125] op_sel_hi:[1,0,1]
	v_pk_fma_f32 v[126:127], v[70:71], s[28:29], v[126:127] op_sel_hi:[1,0,1]
	v_pk_fma_f32 v[128:129], v[72:73], s[28:29], v[128:129] op_sel_hi:[1,0,1]
	v_add_f32_e32 v164, v114, v115
	v_add_f32_e32 v165, v116, v117
	v_add_f32_e32 v166, v118, v119
	v_add_f32_e32 v167, v120, v121
	v_add_f32_e32 v168, v122, v123
	v_add_f32_e32 v169, v124, v125
	v_add_f32_e32 v242, v126, v127
	v_add_f32_e32 v243, v128, v129
	v_add_f32_e32 v164, v164, v165
	v_add_f32_e32 v166, v166, v167
	v_add_f32_e32 v168, v168, v169
	v_add_f32_e32 v242, v242, v243
	v_add_f32_e32 v9, 0, v164
	v_add_f32_e32 v9, v9, v166
	v_add_f32_e32 v9, v9, v168
	v_add_f32_e32 v9, v9, v242
	ds_bpermute_b32 v28, v96, v9
	s_waitcnt lgkmcnt(0)
	v_add_f32_e32 v9, v9, v28
	ds_swizzle_b32 v28, v9 offset:swizzle(SWAP,16)
	s_waitcnt lgkmcnt(0)
	v_add_f32_e32 v9, v9, v28
	ds_swizzle_b32 v28, v9 offset:swizzle(SWAP,8)
	s_waitcnt lgkmcnt(0)
	v_add_f32_e32 v9, v9, v28
	ds_swizzle_b32 v28, v9 offset:swizzle(SWAP,4)
	s_waitcnt lgkmcnt(0)
	v_add_f32_e32 v9, v9, v28
	ds_swizzle_b32 v28, v9 offset:swizzle(SWAP,2)
	s_waitcnt lgkmcnt(0)
	v_add_f32_e32 v9, v9, v28
	ds_swizzle_b32 v28, v9 offset:swizzle(SWAP,1)
	s_waitcnt lgkmcnt(0)
	v_add_f32_e32 v9, v9, v28
	v_fmac_f32_e32 v114, 0xba800000, v9
	v_fmac_f32_e32 v115, 0xba800000, v9
	v_fmac_f32_e32 v116, 0xba800000, v9
	v_fmac_f32_e32 v117, 0xba800000, v9
	v_fmac_f32_e32 v118, 0xba800000, v9
	v_fmac_f32_e32 v119, 0xba800000, v9
	v_fmac_f32_e32 v120, 0xba800000, v9
	v_fmac_f32_e32 v121, 0xba800000, v9
	v_fmac_f32_e32 v122, 0xba800000, v9
	v_fmac_f32_e32 v123, 0xba800000, v9
	v_fmac_f32_e32 v124, 0xba800000, v9
	v_fmac_f32_e32 v125, 0xba800000, v9
	v_fmac_f32_e32 v126, 0xba800000, v9
	v_fmac_f32_e32 v127, 0xba800000, v9
	v_fmac_f32_e32 v128, 0xba800000, v9
	v_fmac_f32_e32 v129, 0xba800000, v9
	v_pk_mul_f32 v[244:245], v[114:115], v[114:115]
	v_pk_mul_f32 v[246:247], v[116:117], v[116:117]
	v_add_f32_e32 v244, v245, v244
	v_add_f32_e32 v246, v246, v247
	v_add_f32_e32 v164, v244, v246
	v_pk_mul_f32 v[244:245], v[118:119], v[118:119]
	v_pk_mul_f32 v[246:247], v[120:121], v[120:121]
	v_add_f32_e32 v244, v245, v244
	v_add_f32_e32 v246, v246, v247
	v_add_f32_e32 v165, v244, v246
	v_mul_f32_e32 v248, v122, v122
	v_mul_f32_e32 v249, v124, v124
	v_fmac_f32_e32 v248, v123, v123
	v_fmac_f32_e32 v249, v125, v125
	v_add_f32_e32 v166, v248, v249
	v_pk_mul_f32 v[244:245], v[126:127], v[126:127]
	v_pk_mul_f32 v[246:247], v[128:129], v[128:129]
	v_add_f32_e32 v244, v244, v245
	v_add_f32_e32 v246, v246, v247
	v_add_f32_e32 v167, v244, v246
	v_add_f32_e32 v164, v164, v165
	v_add_f32_e32 v164, v166, v164
	v_add_f32_e32 v9, v167, v164
	ds_bpermute_b32 v28, v96, v9
	s_waitcnt lgkmcnt(0)
	v_add_f32_e32 v9, v9, v28
	ds_swizzle_b32 v28, v9 offset:swizzle(SWAP,16)
	s_waitcnt lgkmcnt(0)
	v_add_f32_e32 v9, v9, v28
	ds_swizzle_b32 v28, v9 offset:swizzle(SWAP,8)
	s_waitcnt lgkmcnt(0)
	v_add_f32_e32 v9, v9, v28
	ds_swizzle_b32 v28, v9 offset:swizzle(SWAP,4)
	s_waitcnt lgkmcnt(0)
	v_add_f32_e32 v9, v9, v28
	ds_swizzle_b32 v28, v9 offset:swizzle(SWAP,2)
	s_waitcnt lgkmcnt(0)
	v_add_f32_e32 v9, v9, v28
	ds_swizzle_b32 v28, v9 offset:swizzle(SWAP,1)
	s_waitcnt lgkmcnt(0)
	v_add_f32_e32 v9, v9, v28
	v_mov_b32_e32 v28, 0x3727c5ac
	v_fmamk_f32 v9, v9, 0x3a800000, v28
	v_mul_f32_e32 v28, 0x4b800000, v9
	v_cmp_gt_f32_e32 vcc, s37, v9
	s_nop 1
	v_cndmask_b32_e32 v9, v9, v28, vcc
	v_rsq_f32_e32 v9, v9
	s_nop 0
	v_mul_f32_e32 v28, 0x45800000, v9
	v_cndmask_b32_e32 v30, v9, v28, vcc
	v_pk_mul_f32 v[114:115], v[114:115], v[30:31] op_sel_hi:[1,0]
	v_pk_mul_f32 v[116:117], v[116:117], v[30:31] op_sel_hi:[1,0]
	v_pk_fma_f32 v[58:59], v[140:141], v[114:115], v[98:99]
	v_pk_fma_f32 v[60:61], v[142:143], v[116:117], v[100:101]
	global_store_dwordx4 v[86:87], v[58:61], off sc1 nt
	v_pk_fma_f32 v[114:115], v[226:227], v[58:59], v[210:211]
	v_pk_fma_f32 v[116:117], v[228:229], v[60:61], v[212:213]
	s_nop 0
	v_cvt_pk_bf16_f32 v74, v114, v115
	v_cvt_pk_bf16_f32 v75, v116, v117
	global_store_dwordx2 v[88:89], v[74:75], off sc1
	v_pk_mul_f32 v[118:119], v[118:119], v[30:31] op_sel_hi:[1,0]
	v_pk_mul_f32 v[120:121], v[120:121], v[30:31] op_sel_hi:[1,0]
	v_pk_fma_f32 v[62:63], v[144:145], v[118:119], v[102:103]
	v_pk_fma_f32 v[64:65], v[146:147], v[120:121], v[104:105]
	global_store_dwordx4 v[86:87], v[62:65], off offset:1024 sc1 nt
	v_pk_fma_f32 v[118:119], v[230:231], v[62:63], v[214:215]
	v_pk_fma_f32 v[120:121], v[232:233], v[64:65], v[216:217]
	s_nop 0
	v_cvt_pk_bf16_f32 v76, v118, v119
	v_cvt_pk_bf16_f32 v77, v120, v121
	global_store_dwordx2 v[88:89], v[76:77], off offset:512 sc1
	v_pk_mul_f32 v[122:123], v[122:123], v[30:31] op_sel_hi:[1,0]
	v_pk_mul_f32 v[124:125], v[124:125], v[30:31] op_sel_hi:[1,0]
	v_pk_fma_f32 v[66:67], v[148:149], v[122:123], v[106:107]
	v_pk_fma_f32 v[68:69], v[150:151], v[124:125], v[108:109]
	global_store_dwordx4 v[86:87], v[66:69], off offset:2048 sc1 nt
	v_pk_fma_f32 v[122:123], v[234:235], v[66:67], v[218:219]
	v_pk_fma_f32 v[124:125], v[236:237], v[68:69], v[220:221]
	s_nop 0
	v_cvt_pk_bf16_f32 v78, v122, v123
	v_cvt_pk_bf16_f32 v79, v124, v125
	global_store_dwordx2 v[88:89], v[78:79], off offset:1024 sc1
	v_pk_mul_f32 v[126:127], v[126:127], v[30:31] op_sel_hi:[1,0]
	v_pk_mul_f32 v[128:129], v[128:129], v[30:31] op_sel_hi:[1,0]
	v_pk_fma_f32 v[70:71], v[152:153], v[126:127], v[110:111]
	v_pk_fma_f32 v[72:73], v[154:155], v[128:129], v[112:113]
	global_store_dwordx4 v[86:87], v[70:73], off offset:3072 sc1 nt
	v_pk_fma_f32 v[126:127], v[238:239], v[70:71], v[222:223]
	v_pk_fma_f32 v[128:129], v[240:241], v[72:73], v[224:225]
	s_nop 0
	v_cvt_pk_bf16_f32 v80, v126, v127
	v_cvt_pk_bf16_f32 v81, v128, v129
	global_store_dwordx2 v[88:89], v[80:81], off offset:1536 sc1
	v_lshl_add_u64 v[86:87], v[86:87], 0, s[0:1]
	v_lshl_add_u64 v[88:89], v[88:89], 0, s[20:21]
	global_load_dwordx4 v[58:61], v[82:83], off nt
	global_load_dwordx4 v[62:65], v[82:83], off offset:1024 nt
	global_load_dwordx4 v[66:69], v[82:83], off offset:2048 nt
	global_load_dwordx4 v[70:73], v[82:83], off offset:3072 nt
	global_load_dwordx2 v[74:75], v[84:85], off nt
	global_load_dwordx2 v[76:77], v[84:85], off offset:512 nt
	global_load_dwordx2 v[78:79], v[84:85], off offset:1024 nt
	global_load_dwordx2 v[80:81], v[84:85], off offset:1536 nt
	v_lshl_add_u64 v[82:83], v[82:83], 0, s[0:1]
	v_lshl_add_u64 v[84:85], v[84:85], 0, s[20:21]
	s_waitcnt vmcnt(32)
	v_lshlrev_b32_e32 v156, 16, v12
	v_and_b32_e32 v157, 0xffff0000, v12
	v_lshlrev_b32_e32 v12, 16, v13
	v_and_b32_e32 v13, 0xffff0000, v13
	v_lshlrev_b32_e32 v158, 16, v14
	v_and_b32_e32 v159, 0xffff0000, v14
	v_lshlrev_b32_e32 v14, 16, v15
	v_and_b32_e32 v15, 0xffff0000, v15
	v_lshlrev_b32_e32 v160, 16, v16
	v_and_b32_e32 v161, 0xffff0000, v16
	v_lshlrev_b32_e32 v16, 16, v17
	v_and_b32_e32 v17, 0xffff0000, v17
	v_lshlrev_b32_e32 v162, 16, v18
	v_and_b32_e32 v163, 0xffff0000, v18
	v_lshlrev_b32_e32 v18, 16, v19
	v_and_b32_e32 v19, 0xffff0000, v19
	v_pk_mul_f32 v[114:115], v[194:195], v[156:157]
	v_pk_mul_f32 v[116:117], v[196:197], v[12:13]
	v_pk_mul_f32 v[118:119], v[198:199], v[158:159]
	v_pk_mul_f32 v[120:121], v[200:201], v[14:15]
	v_pk_mul_f32 v[122:123], v[202:203], v[160:161]
	v_pk_mul_f32 v[124:125], v[204:205], v[16:17]
	v_pk_mul_f32 v[126:127], v[206:207], v[162:163]
	v_pk_mul_f32 v[128:129], v[208:209], v[18:19]
	v_pk_mul_f32 v[114:115], v[10:11], v[114:115]
	v_pk_mul_f32 v[116:117], v[10:11], v[116:117]
	v_pk_mul_f32 v[118:119], v[10:11], v[118:119]
	v_pk_mul_f32 v[120:121], v[10:11], v[120:121]
	v_pk_mul_f32 v[122:123], v[10:11], v[122:123]
	v_pk_mul_f32 v[124:125], v[10:11], v[124:125]
	v_pk_mul_f32 v[126:127], v[10:11], v[126:127]
	v_pk_mul_f32 v[128:129], v[10:11], v[128:129]
	v_pk_fma_f32 v[114:115], v[20:21], s[28:29], v[114:115] op_sel_hi:[1,0,1]
	v_pk_fma_f32 v[116:117], v[22:23], s[28:29], v[116:117] op_sel_hi:[1,0,1]
	v_pk_fma_f32 v[118:119], v[24:25], s[28:29], v[118:119] op_sel_hi:[1,0,1]
	v_pk_fma_f32 v[120:121], v[26:27], s[28:29], v[120:121] op_sel_hi:[1,0,1]
	v_pk_fma_f32 v[122:123], v[0:1], s[28:29], v[122:123] op_sel_hi:[1,0,1]
	v_pk_fma_f32 v[124:125], v[2:3], s[28:29], v[124:125] op_sel_hi:[1,0,1]
	v_pk_fma_f32 v[126:127], v[4:5], s[28:29], v[126:127] op_sel_hi:[1,0,1]
	v_pk_fma_f32 v[128:129], v[6:7], s[28:29], v[128:129] op_sel_hi:[1,0,1]
	v_add_f32_e32 v164, v114, v115
	v_add_f32_e32 v165, v116, v117
	v_add_f32_e32 v166, v118, v119
	v_add_f32_e32 v167, v120, v121
	v_add_f32_e32 v168, v122, v123
	v_add_f32_e32 v169, v124, v125
	v_add_f32_e32 v242, v126, v127
	v_add_f32_e32 v243, v128, v129
	v_add_f32_e32 v164, v164, v165
	v_add_f32_e32 v166, v166, v167
	v_add_f32_e32 v168, v168, v169
	v_add_f32_e32 v242, v242, v243
	v_add_f32_e32 v9, 0, v164
	v_add_f32_e32 v9, v9, v166
	v_add_f32_e32 v9, v9, v168
	v_add_f32_e32 v9, v9, v242
	ds_bpermute_b32 v28, v96, v9
	s_waitcnt lgkmcnt(0)
	v_add_f32_e32 v9, v9, v28
	ds_swizzle_b32 v28, v9 offset:swizzle(SWAP,16)
	s_waitcnt lgkmcnt(0)
	v_add_f32_e32 v9, v9, v28
	ds_swizzle_b32 v28, v9 offset:swizzle(SWAP,8)
	s_waitcnt lgkmcnt(0)
	v_add_f32_e32 v9, v9, v28
	ds_swizzle_b32 v28, v9 offset:swizzle(SWAP,4)
	s_waitcnt lgkmcnt(0)
	v_add_f32_e32 v9, v9, v28
	ds_swizzle_b32 v28, v9 offset:swizzle(SWAP,2)
	s_waitcnt lgkmcnt(0)
	v_add_f32_e32 v9, v9, v28
	ds_swizzle_b32 v28, v9 offset:swizzle(SWAP,1)
	s_waitcnt lgkmcnt(0)
	v_add_f32_e32 v9, v9, v28
	v_fmac_f32_e32 v114, 0xba800000, v9
	v_fmac_f32_e32 v115, 0xba800000, v9
	v_fmac_f32_e32 v116, 0xba800000, v9
	v_fmac_f32_e32 v117, 0xba800000, v9
	v_fmac_f32_e32 v118, 0xba800000, v9
	v_fmac_f32_e32 v119, 0xba800000, v9
	v_fmac_f32_e32 v120, 0xba800000, v9
	v_fmac_f32_e32 v121, 0xba800000, v9
	v_fmac_f32_e32 v122, 0xba800000, v9
	v_fmac_f32_e32 v123, 0xba800000, v9
	v_fmac_f32_e32 v124, 0xba800000, v9
	v_fmac_f32_e32 v125, 0xba800000, v9
	v_fmac_f32_e32 v126, 0xba800000, v9
	v_fmac_f32_e32 v127, 0xba800000, v9
	v_fmac_f32_e32 v128, 0xba800000, v9
	v_fmac_f32_e32 v129, 0xba800000, v9
	v_pk_mul_f32 v[244:245], v[114:115], v[114:115]
	v_pk_mul_f32 v[246:247], v[116:117], v[116:117]
	v_add_f32_e32 v244, v245, v244
	v_add_f32_e32 v246, v246, v247
	v_add_f32_e32 v164, v244, v246
	v_pk_mul_f32 v[244:245], v[118:119], v[118:119]
	v_pk_mul_f32 v[246:247], v[120:121], v[120:121]
	v_add_f32_e32 v244, v245, v244
	v_add_f32_e32 v246, v246, v247
	v_add_f32_e32 v165, v244, v246
	v_mul_f32_e32 v248, v122, v122
	v_mul_f32_e32 v249, v124, v124
	v_fmac_f32_e32 v248, v123, v123
	v_fmac_f32_e32 v249, v125, v125
	v_add_f32_e32 v166, v248, v249
	v_pk_mul_f32 v[244:245], v[126:127], v[126:127]
	v_pk_mul_f32 v[246:247], v[128:129], v[128:129]
	v_add_f32_e32 v244, v244, v245
	v_add_f32_e32 v246, v246, v247
	v_add_f32_e32 v167, v244, v246
	v_add_f32_e32 v164, v164, v165
	v_add_f32_e32 v164, v166, v164
	v_add_f32_e32 v9, v167, v164
	ds_bpermute_b32 v28, v96, v9
	s_waitcnt lgkmcnt(0)
	v_add_f32_e32 v9, v9, v28
	ds_swizzle_b32 v28, v9 offset:swizzle(SWAP,16)
	s_waitcnt lgkmcnt(0)
	v_add_f32_e32 v9, v9, v28
	ds_swizzle_b32 v28, v9 offset:swizzle(SWAP,8)
	s_waitcnt lgkmcnt(0)
	v_add_f32_e32 v9, v9, v28
	ds_swizzle_b32 v28, v9 offset:swizzle(SWAP,4)
	s_waitcnt lgkmcnt(0)
	v_add_f32_e32 v9, v9, v28
	ds_swizzle_b32 v28, v9 offset:swizzle(SWAP,2)
	s_waitcnt lgkmcnt(0)
	v_add_f32_e32 v9, v9, v28
	ds_swizzle_b32 v28, v9 offset:swizzle(SWAP,1)
	s_waitcnt lgkmcnt(0)
	v_add_f32_e32 v9, v9, v28
	v_mov_b32_e32 v28, 0x3727c5ac
	v_fmamk_f32 v9, v9, 0x3a800000, v28
	v_mul_f32_e32 v28, 0x4b800000, v9
	v_cmp_gt_f32_e32 vcc, s37, v9
	s_nop 1
	v_cndmask_b32_e32 v9, v9, v28, vcc
	v_rsq_f32_e32 v9, v9
	s_nop 0
	v_mul_f32_e32 v28, 0x45800000, v9
	v_cndmask_b32_e32 v30, v9, v28, vcc
	v_pk_mul_f32 v[114:115], v[114:115], v[30:31] op_sel_hi:[1,0]
	v_pk_mul_f32 v[116:117], v[116:117], v[30:31] op_sel_hi:[1,0]
	v_pk_fma_f32 v[20:21], v[140:141], v[114:115], v[98:99]
	v_pk_fma_f32 v[22:23], v[142:143], v[116:117], v[100:101]
	global_store_dwordx4 v[86:87], v[20:23], off sc1 nt
	v_pk_fma_f32 v[114:115], v[226:227], v[20:21], v[210:211]
	v_pk_fma_f32 v[116:117], v[228:229], v[22:23], v[212:213]
	s_nop 0
	v_cvt_pk_bf16_f32 v12, v114, v115
	v_cvt_pk_bf16_f32 v13, v116, v117
	global_store_dwordx2 v[88:89], v[12:13], off sc1
	v_pk_mul_f32 v[118:119], v[118:119], v[30:31] op_sel_hi:[1,0]
	v_pk_mul_f32 v[120:121], v[120:121], v[30:31] op_sel_hi:[1,0]
	v_pk_fma_f32 v[24:25], v[144:145], v[118:119], v[102:103]
	v_pk_fma_f32 v[26:27], v[146:147], v[120:121], v[104:105]
	global_store_dwordx4 v[86:87], v[24:27], off offset:1024 sc1 nt
	v_pk_fma_f32 v[118:119], v[230:231], v[24:25], v[214:215]
	v_pk_fma_f32 v[120:121], v[232:233], v[26:27], v[216:217]
	s_nop 0
	v_cvt_pk_bf16_f32 v14, v118, v119
	v_cvt_pk_bf16_f32 v15, v120, v121
	global_store_dwordx2 v[88:89], v[14:15], off offset:512 sc1
	v_pk_mul_f32 v[122:123], v[122:123], v[30:31] op_sel_hi:[1,0]
	v_pk_mul_f32 v[124:125], v[124:125], v[30:31] op_sel_hi:[1,0]
	v_pk_fma_f32 v[0:1], v[148:149], v[122:123], v[106:107]
	v_pk_fma_f32 v[2:3], v[150:151], v[124:125], v[108:109]
	global_store_dwordx4 v[86:87], v[0:3], off offset:2048 sc1 nt
	v_pk_fma_f32 v[122:123], v[234:235], v[0:1], v[218:219]
	v_pk_fma_f32 v[124:125], v[236:237], v[2:3], v[220:221]
	s_nop 0
	v_cvt_pk_bf16_f32 v16, v122, v123
	v_cvt_pk_bf16_f32 v17, v124, v125
	global_store_dwordx2 v[88:89], v[16:17], off offset:1024 sc1
	v_pk_mul_f32 v[126:127], v[126:127], v[30:31] op_sel_hi:[1,0]
	v_pk_mul_f32 v[128:129], v[128:129], v[30:31] op_sel_hi:[1,0]
	v_pk_fma_f32 v[4:5], v[152:153], v[126:127], v[110:111]
	v_pk_fma_f32 v[6:7], v[154:155], v[128:129], v[112:113]
	global_store_dwordx4 v[86:87], v[4:7], off offset:3072 sc1 nt
	v_pk_fma_f32 v[126:127], v[238:239], v[4:5], v[222:223]
	v_pk_fma_f32 v[128:129], v[240:241], v[6:7], v[224:225]
	s_nop 0
	v_cvt_pk_bf16_f32 v18, v126, v127
	v_cvt_pk_bf16_f32 v19, v128, v129
	global_store_dwordx2 v[88:89], v[18:19], off offset:1536 sc1
	v_lshl_add_u64 v[86:87], v[86:87], 0, s[0:1]
	v_lshl_add_u64 v[88:89], v[88:89], 0, s[20:21]
	global_load_dwordx4 v[20:23], v[82:83], off nt
	global_load_dwordx4 v[24:27], v[82:83], off offset:1024 nt
	global_load_dwordx4 v[0:3], v[82:83], off offset:2048 nt
	global_load_dwordx4 v[4:7], v[82:83], off offset:3072 nt
	global_load_dwordx2 v[12:13], v[84:85], off nt
	global_load_dwordx2 v[14:15], v[84:85], off offset:512 nt
	global_load_dwordx2 v[16:17], v[84:85], off offset:1024 nt
	global_load_dwordx2 v[18:19], v[84:85], off offset:1536 nt
	v_lshl_add_u64 v[82:83], v[82:83], 0, s[0:1]
	v_lshl_add_u64 v[84:85], v[84:85], 0, s[20:21]
	s_waitcnt vmcnt(32)
	v_lshlrev_b32_e32 v156, 16, v50
	v_and_b32_e32 v157, 0xffff0000, v50
	v_lshlrev_b32_e32 v50, 16, v51
	v_and_b32_e32 v51, 0xffff0000, v51
	v_lshlrev_b32_e32 v158, 16, v52
	v_and_b32_e32 v159, 0xffff0000, v52
	v_lshlrev_b32_e32 v52, 16, v53
	v_and_b32_e32 v53, 0xffff0000, v53
	v_lshlrev_b32_e32 v160, 16, v54
	v_and_b32_e32 v161, 0xffff0000, v54
	v_lshlrev_b32_e32 v54, 16, v55
	v_and_b32_e32 v55, 0xffff0000, v55
	v_lshlrev_b32_e32 v162, 16, v56
	v_and_b32_e32 v163, 0xffff0000, v56
	v_lshlrev_b32_e32 v56, 16, v57
	v_and_b32_e32 v57, 0xffff0000, v57
	v_pk_mul_f32 v[114:115], v[194:195], v[156:157]
	v_pk_mul_f32 v[116:117], v[196:197], v[50:51]
	v_pk_mul_f32 v[118:119], v[198:199], v[158:159]
	v_pk_mul_f32 v[120:121], v[200:201], v[52:53]
	v_pk_mul_f32 v[122:123], v[202:203], v[160:161]
	v_pk_mul_f32 v[124:125], v[204:205], v[54:55]
	v_pk_mul_f32 v[126:127], v[206:207], v[162:163]
	v_pk_mul_f32 v[128:129], v[208:209], v[56:57]
	v_pk_mul_f32 v[114:115], v[10:11], v[114:115]
	v_pk_mul_f32 v[116:117], v[10:11], v[116:117]
	v_pk_mul_f32 v[118:119], v[10:11], v[118:119]
	v_pk_mul_f32 v[120:121], v[10:11], v[120:121]
	v_pk_mul_f32 v[122:123], v[10:11], v[122:123]
	v_pk_mul_f32 v[124:125], v[10:11], v[124:125]
	v_pk_mul_f32 v[126:127], v[10:11], v[126:127]
	v_pk_mul_f32 v[128:129], v[10:11], v[128:129]
	v_pk_fma_f32 v[114:115], v[34:35], s[28:29], v[114:115] op_sel_hi:[1,0,1]
	v_pk_fma_f32 v[116:117], v[36:37], s[28:29], v[116:117] op_sel_hi:[1,0,1]
	v_pk_fma_f32 v[118:119], v[38:39], s[28:29], v[118:119] op_sel_hi:[1,0,1]
	v_pk_fma_f32 v[120:121], v[40:41], s[28:29], v[120:121] op_sel_hi:[1,0,1]
	v_pk_fma_f32 v[122:123], v[42:43], s[28:29], v[122:123] op_sel_hi:[1,0,1]
	v_pk_fma_f32 v[124:125], v[44:45], s[28:29], v[124:125] op_sel_hi:[1,0,1]
	v_pk_fma_f32 v[126:127], v[46:47], s[28:29], v[126:127] op_sel_hi:[1,0,1]
	v_pk_fma_f32 v[128:129], v[48:49], s[28:29], v[128:129] op_sel_hi:[1,0,1]
	v_add_f32_e32 v164, v114, v115
	v_add_f32_e32 v165, v116, v117
	v_add_f32_e32 v166, v118, v119
	v_add_f32_e32 v167, v120, v121
	v_add_f32_e32 v168, v122, v123
	v_add_f32_e32 v169, v124, v125
	v_add_f32_e32 v242, v126, v127
	v_add_f32_e32 v243, v128, v129
	v_add_f32_e32 v164, v164, v165
	v_add_f32_e32 v166, v166, v167
	v_add_f32_e32 v168, v168, v169
	v_add_f32_e32 v242, v242, v243
	v_add_f32_e32 v9, 0, v164
	v_add_f32_e32 v9, v9, v166
	v_add_f32_e32 v9, v9, v168
	v_add_f32_e32 v9, v9, v242
	ds_bpermute_b32 v28, v96, v9
	s_waitcnt lgkmcnt(0)
	v_add_f32_e32 v9, v9, v28
	ds_swizzle_b32 v28, v9 offset:swizzle(SWAP,16)
	s_waitcnt lgkmcnt(0)
	v_add_f32_e32 v9, v9, v28
	ds_swizzle_b32 v28, v9 offset:swizzle(SWAP,8)
	s_waitcnt lgkmcnt(0)
	v_add_f32_e32 v9, v9, v28
	ds_swizzle_b32 v28, v9 offset:swizzle(SWAP,4)
	s_waitcnt lgkmcnt(0)
	v_add_f32_e32 v9, v9, v28
	ds_swizzle_b32 v28, v9 offset:swizzle(SWAP,2)
	s_waitcnt lgkmcnt(0)
	v_add_f32_e32 v9, v9, v28
	ds_swizzle_b32 v28, v9 offset:swizzle(SWAP,1)
	s_waitcnt lgkmcnt(0)
	v_add_f32_e32 v9, v9, v28
	v_fmac_f32_e32 v114, 0xba800000, v9
	v_fmac_f32_e32 v115, 0xba800000, v9
	v_fmac_f32_e32 v116, 0xba800000, v9
	v_fmac_f32_e32 v117, 0xba800000, v9
	v_fmac_f32_e32 v118, 0xba800000, v9
	v_fmac_f32_e32 v119, 0xba800000, v9
	v_fmac_f32_e32 v120, 0xba800000, v9
	v_fmac_f32_e32 v121, 0xba800000, v9
	v_fmac_f32_e32 v122, 0xba800000, v9
	v_fmac_f32_e32 v123, 0xba800000, v9
	v_fmac_f32_e32 v124, 0xba800000, v9
	v_fmac_f32_e32 v125, 0xba800000, v9
	v_fmac_f32_e32 v126, 0xba800000, v9
	v_fmac_f32_e32 v127, 0xba800000, v9
	v_fmac_f32_e32 v128, 0xba800000, v9
	v_fmac_f32_e32 v129, 0xba800000, v9
	v_pk_mul_f32 v[244:245], v[114:115], v[114:115]
	v_pk_mul_f32 v[246:247], v[116:117], v[116:117]
	v_add_f32_e32 v244, v245, v244
	v_add_f32_e32 v246, v246, v247
	v_add_f32_e32 v164, v244, v246
	v_pk_mul_f32 v[244:245], v[118:119], v[118:119]
	v_pk_mul_f32 v[246:247], v[120:121], v[120:121]
	v_add_f32_e32 v244, v245, v244
	v_add_f32_e32 v246, v246, v247
	v_add_f32_e32 v165, v244, v246
	v_mul_f32_e32 v248, v122, v122
	v_mul_f32_e32 v249, v124, v124
	v_fmac_f32_e32 v248, v123, v123
	v_fmac_f32_e32 v249, v125, v125
	v_add_f32_e32 v166, v248, v249
	v_pk_mul_f32 v[244:245], v[126:127], v[126:127]
	v_pk_mul_f32 v[246:247], v[128:129], v[128:129]
	v_add_f32_e32 v244, v244, v245
	v_add_f32_e32 v246, v246, v247
	v_add_f32_e32 v167, v244, v246
	v_add_f32_e32 v164, v164, v165
	v_add_f32_e32 v164, v166, v164
	v_add_f32_e32 v9, v167, v164
	ds_bpermute_b32 v28, v96, v9
	s_waitcnt lgkmcnt(0)
	v_add_f32_e32 v9, v9, v28
	ds_swizzle_b32 v28, v9 offset:swizzle(SWAP,16)
	s_waitcnt lgkmcnt(0)
	v_add_f32_e32 v9, v9, v28
	ds_swizzle_b32 v28, v9 offset:swizzle(SWAP,8)
	s_waitcnt lgkmcnt(0)
	v_add_f32_e32 v9, v9, v28
	ds_swizzle_b32 v28, v9 offset:swizzle(SWAP,4)
	s_waitcnt lgkmcnt(0)
	v_add_f32_e32 v9, v9, v28
	ds_swizzle_b32 v28, v9 offset:swizzle(SWAP,2)
	s_waitcnt lgkmcnt(0)
	v_add_f32_e32 v9, v9, v28
	ds_swizzle_b32 v28, v9 offset:swizzle(SWAP,1)
	s_waitcnt lgkmcnt(0)
	v_add_f32_e32 v9, v9, v28
	v_mov_b32_e32 v28, 0x3727c5ac
	v_fmamk_f32 v9, v9, 0x3a800000, v28
	v_mul_f32_e32 v28, 0x4b800000, v9
	v_cmp_gt_f32_e32 vcc, s37, v9
	s_nop 1
	v_cndmask_b32_e32 v9, v9, v28, vcc
	v_rsq_f32_e32 v9, v9
	s_nop 0
	v_mul_f32_e32 v28, 0x45800000, v9
	v_cndmask_b32_e32 v30, v9, v28, vcc
	v_pk_mul_f32 v[114:115], v[114:115], v[30:31] op_sel_hi:[1,0]
	v_pk_mul_f32 v[116:117], v[116:117], v[30:31] op_sel_hi:[1,0]
	v_pk_fma_f32 v[34:35], v[140:141], v[114:115], v[98:99]
	v_pk_fma_f32 v[36:37], v[142:143], v[116:117], v[100:101]
	global_store_dwordx4 v[86:87], v[34:37], off sc1 nt
	v_pk_fma_f32 v[114:115], v[226:227], v[34:35], v[210:211]
	v_pk_fma_f32 v[116:117], v[228:229], v[36:37], v[212:213]
	s_nop 0
	v_cvt_pk_bf16_f32 v50, v114, v115
	v_cvt_pk_bf16_f32 v51, v116, v117
	global_store_dwordx2 v[88:89], v[50:51], off sc1
	v_pk_mul_f32 v[118:119], v[118:119], v[30:31] op_sel_hi:[1,0]
	v_pk_mul_f32 v[120:121], v[120:121], v[30:31] op_sel_hi:[1,0]
	v_pk_fma_f32 v[38:39], v[144:145], v[118:119], v[102:103]
	v_pk_fma_f32 v[40:41], v[146:147], v[120:121], v[104:105]
	global_store_dwordx4 v[86:87], v[38:41], off offset:1024 sc1 nt
	v_pk_fma_f32 v[118:119], v[230:231], v[38:39], v[214:215]
	v_pk_fma_f32 v[120:121], v[232:233], v[40:41], v[216:217]
	s_nop 0
	v_cvt_pk_bf16_f32 v52, v118, v119
	v_cvt_pk_bf16_f32 v53, v120, v121
	global_store_dwordx2 v[88:89], v[52:53], off offset:512 sc1
	v_pk_mul_f32 v[122:123], v[122:123], v[30:31] op_sel_hi:[1,0]
	v_pk_mul_f32 v[124:125], v[124:125], v[30:31] op_sel_hi:[1,0]
	v_pk_fma_f32 v[42:43], v[148:149], v[122:123], v[106:107]
	v_pk_fma_f32 v[44:45], v[150:151], v[124:125], v[108:109]
	global_store_dwordx4 v[86:87], v[42:45], off offset:2048 sc1 nt
	v_pk_fma_f32 v[122:123], v[234:235], v[42:43], v[218:219]
	v_pk_fma_f32 v[124:125], v[236:237], v[44:45], v[220:221]
	s_nop 0
	v_cvt_pk_bf16_f32 v54, v122, v123
	v_cvt_pk_bf16_f32 v55, v124, v125
	global_store_dwordx2 v[88:89], v[54:55], off offset:1024 sc1
	v_pk_mul_f32 v[126:127], v[126:127], v[30:31] op_sel_hi:[1,0]
	v_pk_mul_f32 v[128:129], v[128:129], v[30:31] op_sel_hi:[1,0]
	v_pk_fma_f32 v[46:47], v[152:153], v[126:127], v[110:111]
	v_pk_fma_f32 v[48:49], v[154:155], v[128:129], v[112:113]
	global_store_dwordx4 v[86:87], v[46:49], off offset:3072 sc1 nt
	v_pk_fma_f32 v[126:127], v[238:239], v[46:47], v[222:223]
	v_pk_fma_f32 v[128:129], v[240:241], v[48:49], v[224:225]
	s_nop 0
	v_cvt_pk_bf16_f32 v56, v126, v127
	v_cvt_pk_bf16_f32 v57, v128, v129
	global_store_dwordx2 v[88:89], v[56:57], off offset:1536 sc1
	v_lshl_add_u64 v[86:87], v[86:87], 0, s[0:1]
	v_lshl_add_u64 v[88:89], v[88:89], 0, s[20:21]
	global_load_dwordx4 v[34:37], v[82:83], off nt
	global_load_dwordx4 v[38:41], v[82:83], off offset:1024 nt
	global_load_dwordx4 v[42:45], v[82:83], off offset:2048 nt
	global_load_dwordx4 v[46:49], v[82:83], off offset:3072 nt
	global_load_dwordx2 v[50:51], v[84:85], off nt
	global_load_dwordx2 v[52:53], v[84:85], off offset:512 nt
	global_load_dwordx2 v[54:55], v[84:85], off offset:1024 nt
	global_load_dwordx2 v[56:57], v[84:85], off offset:1536 nt
	v_lshl_add_u64 v[82:83], v[82:83], 0, s[0:1]
	v_lshl_add_u64 v[84:85], v[84:85], 0, s[20:21]
	s_waitcnt vmcnt(32)
	v_lshlrev_b32_e32 v156, 16, v74
	v_and_b32_e32 v157, 0xffff0000, v74
	v_lshlrev_b32_e32 v74, 16, v75
	v_and_b32_e32 v75, 0xffff0000, v75
	v_lshlrev_b32_e32 v158, 16, v76
	v_and_b32_e32 v159, 0xffff0000, v76
	v_lshlrev_b32_e32 v76, 16, v77
	v_and_b32_e32 v77, 0xffff0000, v77
	v_lshlrev_b32_e32 v160, 16, v78
	v_and_b32_e32 v161, 0xffff0000, v78
	v_lshlrev_b32_e32 v78, 16, v79
	v_and_b32_e32 v79, 0xffff0000, v79
	v_lshlrev_b32_e32 v162, 16, v80
	v_and_b32_e32 v163, 0xffff0000, v80
	v_lshlrev_b32_e32 v80, 16, v81
	v_and_b32_e32 v81, 0xffff0000, v81
	v_pk_mul_f32 v[114:115], v[194:195], v[156:157]
	v_pk_mul_f32 v[116:117], v[196:197], v[74:75]
	v_pk_mul_f32 v[118:119], v[198:199], v[158:159]
	v_pk_mul_f32 v[120:121], v[200:201], v[76:77]
	v_pk_mul_f32 v[122:123], v[202:203], v[160:161]
	v_pk_mul_f32 v[124:125], v[204:205], v[78:79]
	v_pk_mul_f32 v[126:127], v[206:207], v[162:163]
	v_pk_mul_f32 v[128:129], v[208:209], v[80:81]
	v_pk_mul_f32 v[114:115], v[10:11], v[114:115]
	v_pk_mul_f32 v[116:117], v[10:11], v[116:117]
	v_pk_mul_f32 v[118:119], v[10:11], v[118:119]
	v_pk_mul_f32 v[120:121], v[10:11], v[120:121]
	v_pk_mul_f32 v[122:123], v[10:11], v[122:123]
	v_pk_mul_f32 v[124:125], v[10:11], v[124:125]
	v_pk_mul_f32 v[126:127], v[10:11], v[126:127]
	v_pk_mul_f32 v[128:129], v[10:11], v[128:129]
	v_pk_fma_f32 v[114:115], v[58:59], s[28:29], v[114:115] op_sel_hi:[1,0,1]
	v_pk_fma_f32 v[116:117], v[60:61], s[28:29], v[116:117] op_sel_hi:[1,0,1]
	v_pk_fma_f32 v[118:119], v[62:63], s[28:29], v[118:119] op_sel_hi:[1,0,1]
	v_pk_fma_f32 v[120:121], v[64:65], s[28:29], v[120:121] op_sel_hi:[1,0,1]
	v_pk_fma_f32 v[122:123], v[66:67], s[28:29], v[122:123] op_sel_hi:[1,0,1]
	v_pk_fma_f32 v[124:125], v[68:69], s[28:29], v[124:125] op_sel_hi:[1,0,1]
	v_pk_fma_f32 v[126:127], v[70:71], s[28:29], v[126:127] op_sel_hi:[1,0,1]
	v_pk_fma_f32 v[128:129], v[72:73], s[28:29], v[128:129] op_sel_hi:[1,0,1]
	v_add_f32_e32 v164, v114, v115
	v_add_f32_e32 v165, v116, v117
	v_add_f32_e32 v166, v118, v119
	v_add_f32_e32 v167, v120, v121
	v_add_f32_e32 v168, v122, v123
	v_add_f32_e32 v169, v124, v125
	v_add_f32_e32 v242, v126, v127
	v_add_f32_e32 v243, v128, v129
	v_add_f32_e32 v164, v164, v165
	v_add_f32_e32 v166, v166, v167
	v_add_f32_e32 v168, v168, v169
	v_add_f32_e32 v242, v242, v243
	v_add_f32_e32 v9, 0, v164
	v_add_f32_e32 v9, v9, v166
	v_add_f32_e32 v9, v9, v168
	v_add_f32_e32 v9, v9, v242
	ds_bpermute_b32 v28, v96, v9
	s_waitcnt lgkmcnt(0)
	v_add_f32_e32 v9, v9, v28
	ds_swizzle_b32 v28, v9 offset:swizzle(SWAP,16)
	s_waitcnt lgkmcnt(0)
	v_add_f32_e32 v9, v9, v28
	ds_swizzle_b32 v28, v9 offset:swizzle(SWAP,8)
	s_waitcnt lgkmcnt(0)
	v_add_f32_e32 v9, v9, v28
	ds_swizzle_b32 v28, v9 offset:swizzle(SWAP,4)
	s_waitcnt lgkmcnt(0)
	v_add_f32_e32 v9, v9, v28
	ds_swizzle_b32 v28, v9 offset:swizzle(SWAP,2)
	s_waitcnt lgkmcnt(0)
	v_add_f32_e32 v9, v9, v28
	ds_swizzle_b32 v28, v9 offset:swizzle(SWAP,1)
	s_waitcnt lgkmcnt(0)
	v_add_f32_e32 v9, v9, v28
	v_fmac_f32_e32 v114, 0xba800000, v9
	v_fmac_f32_e32 v115, 0xba800000, v9
	v_fmac_f32_e32 v116, 0xba800000, v9
	v_fmac_f32_e32 v117, 0xba800000, v9
	v_fmac_f32_e32 v118, 0xba800000, v9
	v_fmac_f32_e32 v119, 0xba800000, v9
	v_fmac_f32_e32 v120, 0xba800000, v9
	v_fmac_f32_e32 v121, 0xba800000, v9
	v_fmac_f32_e32 v122, 0xba800000, v9
	v_fmac_f32_e32 v123, 0xba800000, v9
	v_fmac_f32_e32 v124, 0xba800000, v9
	v_fmac_f32_e32 v125, 0xba800000, v9
	v_fmac_f32_e32 v126, 0xba800000, v9
	v_fmac_f32_e32 v127, 0xba800000, v9
	v_fmac_f32_e32 v128, 0xba800000, v9
	v_fmac_f32_e32 v129, 0xba800000, v9
	v_pk_mul_f32 v[244:245], v[114:115], v[114:115]
	v_pk_mul_f32 v[246:247], v[116:117], v[116:117]
	v_add_f32_e32 v244, v245, v244
	v_add_f32_e32 v246, v246, v247
	v_add_f32_e32 v164, v244, v246
	v_pk_mul_f32 v[244:245], v[118:119], v[118:119]
	v_pk_mul_f32 v[246:247], v[120:121], v[120:121]
	v_add_f32_e32 v244, v245, v244
	v_add_f32_e32 v246, v246, v247
	v_add_f32_e32 v165, v244, v246
	v_mul_f32_e32 v248, v122, v122
	v_mul_f32_e32 v249, v124, v124
	v_fmac_f32_e32 v248, v123, v123
	v_fmac_f32_e32 v249, v125, v125
	v_add_f32_e32 v166, v248, v249
	v_pk_mul_f32 v[244:245], v[126:127], v[126:127]
	v_pk_mul_f32 v[246:247], v[128:129], v[128:129]
	v_add_f32_e32 v244, v244, v245
	v_add_f32_e32 v246, v246, v247
	v_add_f32_e32 v167, v244, v246
	v_add_f32_e32 v164, v164, v165
	v_add_f32_e32 v164, v166, v164
	v_add_f32_e32 v9, v167, v164
	ds_bpermute_b32 v28, v96, v9
	s_waitcnt lgkmcnt(0)
	v_add_f32_e32 v9, v9, v28
	ds_swizzle_b32 v28, v9 offset:swizzle(SWAP,16)
	s_waitcnt lgkmcnt(0)
	v_add_f32_e32 v9, v9, v28
	ds_swizzle_b32 v28, v9 offset:swizzle(SWAP,8)
	s_waitcnt lgkmcnt(0)
	v_add_f32_e32 v9, v9, v28
	ds_swizzle_b32 v28, v9 offset:swizzle(SWAP,4)
	s_waitcnt lgkmcnt(0)
	v_add_f32_e32 v9, v9, v28
	ds_swizzle_b32 v28, v9 offset:swizzle(SWAP,2)
	s_waitcnt lgkmcnt(0)
	v_add_f32_e32 v9, v9, v28
	ds_swizzle_b32 v28, v9 offset:swizzle(SWAP,1)
	s_waitcnt lgkmcnt(0)
	v_add_f32_e32 v9, v9, v28
	v_mov_b32_e32 v28, 0x3727c5ac
	v_fmamk_f32 v9, v9, 0x3a800000, v28
	v_mul_f32_e32 v28, 0x4b800000, v9
	v_cmp_gt_f32_e32 vcc, s37, v9
	s_nop 1
	v_cndmask_b32_e32 v9, v9, v28, vcc
	v_rsq_f32_e32 v9, v9
	s_nop 0
	v_mul_f32_e32 v28, 0x45800000, v9
	v_cndmask_b32_e32 v30, v9, v28, vcc
	v_pk_mul_f32 v[114:115], v[114:115], v[30:31] op_sel_hi:[1,0]
	v_pk_mul_f32 v[116:117], v[116:117], v[30:31] op_sel_hi:[1,0]
	v_pk_fma_f32 v[58:59], v[140:141], v[114:115], v[98:99]
	v_pk_fma_f32 v[60:61], v[142:143], v[116:117], v[100:101]
	global_store_dwordx4 v[86:87], v[58:61], off sc1 nt
	v_pk_fma_f32 v[114:115], v[226:227], v[58:59], v[210:211]
	v_pk_fma_f32 v[116:117], v[228:229], v[60:61], v[212:213]
	s_nop 0
	v_cvt_pk_bf16_f32 v74, v114, v115
	v_cvt_pk_bf16_f32 v75, v116, v117
	global_store_dwordx2 v[88:89], v[74:75], off sc1
	v_pk_mul_f32 v[118:119], v[118:119], v[30:31] op_sel_hi:[1,0]
	v_pk_mul_f32 v[120:121], v[120:121], v[30:31] op_sel_hi:[1,0]
	v_pk_fma_f32 v[62:63], v[144:145], v[118:119], v[102:103]
	v_pk_fma_f32 v[64:65], v[146:147], v[120:121], v[104:105]
	global_store_dwordx4 v[86:87], v[62:65], off offset:1024 sc1 nt
	v_pk_fma_f32 v[118:119], v[230:231], v[62:63], v[214:215]
	v_pk_fma_f32 v[120:121], v[232:233], v[64:65], v[216:217]
	s_nop 0
	v_cvt_pk_bf16_f32 v76, v118, v119
	v_cvt_pk_bf16_f32 v77, v120, v121
	global_store_dwordx2 v[88:89], v[76:77], off offset:512 sc1
	v_pk_mul_f32 v[122:123], v[122:123], v[30:31] op_sel_hi:[1,0]
	v_pk_mul_f32 v[124:125], v[124:125], v[30:31] op_sel_hi:[1,0]
	v_pk_fma_f32 v[66:67], v[148:149], v[122:123], v[106:107]
	v_pk_fma_f32 v[68:69], v[150:151], v[124:125], v[108:109]
	global_store_dwordx4 v[86:87], v[66:69], off offset:2048 sc1 nt
	v_pk_fma_f32 v[122:123], v[234:235], v[66:67], v[218:219]
	v_pk_fma_f32 v[124:125], v[236:237], v[68:69], v[220:221]
	s_nop 0
	v_cvt_pk_bf16_f32 v78, v122, v123
	v_cvt_pk_bf16_f32 v79, v124, v125
	global_store_dwordx2 v[88:89], v[78:79], off offset:1024 sc1
	v_pk_mul_f32 v[126:127], v[126:127], v[30:31] op_sel_hi:[1,0]
	v_pk_mul_f32 v[128:129], v[128:129], v[30:31] op_sel_hi:[1,0]
	v_pk_fma_f32 v[70:71], v[152:153], v[126:127], v[110:111]
	v_pk_fma_f32 v[72:73], v[154:155], v[128:129], v[112:113]
	global_store_dwordx4 v[86:87], v[70:73], off offset:3072 sc1 nt
	v_pk_fma_f32 v[126:127], v[238:239], v[70:71], v[222:223]
	v_pk_fma_f32 v[128:129], v[240:241], v[72:73], v[224:225]
	s_nop 0
	v_cvt_pk_bf16_f32 v80, v126, v127
	v_cvt_pk_bf16_f32 v81, v128, v129
	global_store_dwordx2 v[88:89], v[80:81], off offset:1536 sc1
	v_lshl_add_u64 v[86:87], v[86:87], 0, s[0:1]
	v_lshl_add_u64 v[88:89], v[88:89], 0, s[20:21]
	global_load_dwordx4 v[58:61], v[82:83], off nt
	global_load_dwordx4 v[62:65], v[82:83], off offset:1024 nt
	global_load_dwordx4 v[66:69], v[82:83], off offset:2048 nt
	global_load_dwordx4 v[70:73], v[82:83], off offset:3072 nt
	global_load_dwordx2 v[74:75], v[84:85], off nt
	global_load_dwordx2 v[76:77], v[84:85], off offset:512 nt
	global_load_dwordx2 v[78:79], v[84:85], off offset:1024 nt
	global_load_dwordx2 v[80:81], v[84:85], off offset:1536 nt
	v_lshl_add_u64 v[82:83], v[82:83], 0, s[0:1]
	v_lshl_add_u64 v[84:85], v[84:85], 0, s[20:21]
	s_waitcnt vmcnt(32)
	v_lshlrev_b32_e32 v156, 16, v12
	v_and_b32_e32 v157, 0xffff0000, v12
	v_lshlrev_b32_e32 v12, 16, v13
	v_and_b32_e32 v13, 0xffff0000, v13
	v_lshlrev_b32_e32 v158, 16, v14
	v_and_b32_e32 v159, 0xffff0000, v14
	v_lshlrev_b32_e32 v14, 16, v15
	v_and_b32_e32 v15, 0xffff0000, v15
	v_lshlrev_b32_e32 v160, 16, v16
	v_and_b32_e32 v161, 0xffff0000, v16
	v_lshlrev_b32_e32 v16, 16, v17
	v_and_b32_e32 v17, 0xffff0000, v17
	v_lshlrev_b32_e32 v162, 16, v18
	v_and_b32_e32 v163, 0xffff0000, v18
	v_lshlrev_b32_e32 v18, 16, v19
	v_and_b32_e32 v19, 0xffff0000, v19
	v_pk_mul_f32 v[114:115], v[194:195], v[156:157]
	v_pk_mul_f32 v[116:117], v[196:197], v[12:13]
	v_pk_mul_f32 v[118:119], v[198:199], v[158:159]
	v_pk_mul_f32 v[120:121], v[200:201], v[14:15]
	v_pk_mul_f32 v[122:123], v[202:203], v[160:161]
	v_pk_mul_f32 v[124:125], v[204:205], v[16:17]
	v_pk_mul_f32 v[126:127], v[206:207], v[162:163]
	v_pk_mul_f32 v[128:129], v[208:209], v[18:19]
	v_pk_mul_f32 v[114:115], v[10:11], v[114:115]
	v_pk_mul_f32 v[116:117], v[10:11], v[116:117]
	v_pk_mul_f32 v[118:119], v[10:11], v[118:119]
	v_pk_mul_f32 v[120:121], v[10:11], v[120:121]
	v_pk_mul_f32 v[122:123], v[10:11], v[122:123]
	v_pk_mul_f32 v[124:125], v[10:11], v[124:125]
	v_pk_mul_f32 v[126:127], v[10:11], v[126:127]
	v_pk_mul_f32 v[128:129], v[10:11], v[128:129]
	v_pk_fma_f32 v[114:115], v[20:21], s[28:29], v[114:115] op_sel_hi:[1,0,1]
	v_pk_fma_f32 v[116:117], v[22:23], s[28:29], v[116:117] op_sel_hi:[1,0,1]
	v_pk_fma_f32 v[118:119], v[24:25], s[28:29], v[118:119] op_sel_hi:[1,0,1]
	v_pk_fma_f32 v[120:121], v[26:27], s[28:29], v[120:121] op_sel_hi:[1,0,1]
	v_pk_fma_f32 v[122:123], v[0:1], s[28:29], v[122:123] op_sel_hi:[1,0,1]
	v_pk_fma_f32 v[124:125], v[2:3], s[28:29], v[124:125] op_sel_hi:[1,0,1]
	v_pk_fma_f32 v[126:127], v[4:5], s[28:29], v[126:127] op_sel_hi:[1,0,1]
	v_pk_fma_f32 v[128:129], v[6:7], s[28:29], v[128:129] op_sel_hi:[1,0,1]
	v_add_f32_e32 v164, v114, v115
	v_add_f32_e32 v165, v116, v117
	v_add_f32_e32 v166, v118, v119
	v_add_f32_e32 v167, v120, v121
	v_add_f32_e32 v168, v122, v123
	v_add_f32_e32 v169, v124, v125
	v_add_f32_e32 v242, v126, v127
	v_add_f32_e32 v243, v128, v129
	v_add_f32_e32 v164, v164, v165
	v_add_f32_e32 v166, v166, v167
	v_add_f32_e32 v168, v168, v169
	v_add_f32_e32 v242, v242, v243
	v_add_f32_e32 v9, 0, v164
	v_add_f32_e32 v9, v9, v166
	v_add_f32_e32 v9, v9, v168
	v_add_f32_e32 v9, v9, v242
	ds_bpermute_b32 v28, v96, v9
	s_waitcnt lgkmcnt(0)
	v_add_f32_e32 v9, v9, v28
	ds_swizzle_b32 v28, v9 offset:swizzle(SWAP,16)
	s_waitcnt lgkmcnt(0)
	v_add_f32_e32 v9, v9, v28
	ds_swizzle_b32 v28, v9 offset:swizzle(SWAP,8)
	s_waitcnt lgkmcnt(0)
	v_add_f32_e32 v9, v9, v28
	ds_swizzle_b32 v28, v9 offset:swizzle(SWAP,4)
	s_waitcnt lgkmcnt(0)
	v_add_f32_e32 v9, v9, v28
	ds_swizzle_b32 v28, v9 offset:swizzle(SWAP,2)
	s_waitcnt lgkmcnt(0)
	v_add_f32_e32 v9, v9, v28
	ds_swizzle_b32 v28, v9 offset:swizzle(SWAP,1)
	s_waitcnt lgkmcnt(0)
	v_add_f32_e32 v9, v9, v28
	v_fmac_f32_e32 v114, 0xba800000, v9
	v_fmac_f32_e32 v115, 0xba800000, v9
	v_fmac_f32_e32 v116, 0xba800000, v9
	v_fmac_f32_e32 v117, 0xba800000, v9
	v_fmac_f32_e32 v118, 0xba800000, v9
	v_fmac_f32_e32 v119, 0xba800000, v9
	v_fmac_f32_e32 v120, 0xba800000, v9
	v_fmac_f32_e32 v121, 0xba800000, v9
	v_fmac_f32_e32 v122, 0xba800000, v9
	v_fmac_f32_e32 v123, 0xba800000, v9
	v_fmac_f32_e32 v124, 0xba800000, v9
	v_fmac_f32_e32 v125, 0xba800000, v9
	v_fmac_f32_e32 v126, 0xba800000, v9
	v_fmac_f32_e32 v127, 0xba800000, v9
	v_fmac_f32_e32 v128, 0xba800000, v9
	v_fmac_f32_e32 v129, 0xba800000, v9
	v_pk_mul_f32 v[244:245], v[114:115], v[114:115]
	v_pk_mul_f32 v[246:247], v[116:117], v[116:117]
	v_add_f32_e32 v244, v245, v244
	v_add_f32_e32 v246, v246, v247
	v_add_f32_e32 v164, v244, v246
	v_pk_mul_f32 v[244:245], v[118:119], v[118:119]
	v_pk_mul_f32 v[246:247], v[120:121], v[120:121]
	v_add_f32_e32 v244, v245, v244
	v_add_f32_e32 v246, v246, v247
	v_add_f32_e32 v165, v244, v246
	v_mul_f32_e32 v248, v122, v122
	v_mul_f32_e32 v249, v124, v124
	v_fmac_f32_e32 v248, v123, v123
	v_fmac_f32_e32 v249, v125, v125
	v_add_f32_e32 v166, v248, v249
	v_pk_mul_f32 v[244:245], v[126:127], v[126:127]
	v_pk_mul_f32 v[246:247], v[128:129], v[128:129]
	v_add_f32_e32 v244, v244, v245
	v_add_f32_e32 v246, v246, v247
	v_add_f32_e32 v167, v244, v246
	v_add_f32_e32 v164, v164, v165
	v_add_f32_e32 v164, v166, v164
	v_add_f32_e32 v9, v167, v164
	ds_bpermute_b32 v28, v96, v9
	s_waitcnt lgkmcnt(0)
	v_add_f32_e32 v9, v9, v28
	ds_swizzle_b32 v28, v9 offset:swizzle(SWAP,16)
	s_waitcnt lgkmcnt(0)
	v_add_f32_e32 v9, v9, v28
	ds_swizzle_b32 v28, v9 offset:swizzle(SWAP,8)
	s_waitcnt lgkmcnt(0)
	v_add_f32_e32 v9, v9, v28
	ds_swizzle_b32 v28, v9 offset:swizzle(SWAP,4)
	s_waitcnt lgkmcnt(0)
	v_add_f32_e32 v9, v9, v28
	ds_swizzle_b32 v28, v9 offset:swizzle(SWAP,2)
	s_waitcnt lgkmcnt(0)
	v_add_f32_e32 v9, v9, v28
	ds_swizzle_b32 v28, v9 offset:swizzle(SWAP,1)
	s_waitcnt lgkmcnt(0)
	v_add_f32_e32 v9, v9, v28
	v_mov_b32_e32 v28, 0x3727c5ac
	v_fmamk_f32 v9, v9, 0x3a800000, v28
	v_mul_f32_e32 v28, 0x4b800000, v9
	v_cmp_gt_f32_e32 vcc, s37, v9
	s_nop 1
	v_cndmask_b32_e32 v9, v9, v28, vcc
	v_rsq_f32_e32 v9, v9
	s_nop 0
	v_mul_f32_e32 v28, 0x45800000, v9
	v_cndmask_b32_e32 v30, v9, v28, vcc
	v_pk_mul_f32 v[114:115], v[114:115], v[30:31] op_sel_hi:[1,0]
	v_pk_mul_f32 v[116:117], v[116:117], v[30:31] op_sel_hi:[1,0]
	v_pk_fma_f32 v[20:21], v[140:141], v[114:115], v[98:99]
	v_pk_fma_f32 v[22:23], v[142:143], v[116:117], v[100:101]
	global_store_dwordx4 v[86:87], v[20:23], off sc1 nt
	v_pk_fma_f32 v[114:115], v[226:227], v[20:21], v[210:211]
	v_pk_fma_f32 v[116:117], v[228:229], v[22:23], v[212:213]
	s_nop 0
	v_cvt_pk_bf16_f32 v12, v114, v115
	v_cvt_pk_bf16_f32 v13, v116, v117
	global_store_dwordx2 v[88:89], v[12:13], off sc1
	v_pk_mul_f32 v[118:119], v[118:119], v[30:31] op_sel_hi:[1,0]
	v_pk_mul_f32 v[120:121], v[120:121], v[30:31] op_sel_hi:[1,0]
	v_pk_fma_f32 v[24:25], v[144:145], v[118:119], v[102:103]
	v_pk_fma_f32 v[26:27], v[146:147], v[120:121], v[104:105]
	global_store_dwordx4 v[86:87], v[24:27], off offset:1024 sc1 nt
	v_pk_fma_f32 v[118:119], v[230:231], v[24:25], v[214:215]
	v_pk_fma_f32 v[120:121], v[232:233], v[26:27], v[216:217]
	s_nop 0
	v_cvt_pk_bf16_f32 v14, v118, v119
	v_cvt_pk_bf16_f32 v15, v120, v121
	global_store_dwordx2 v[88:89], v[14:15], off offset:512 sc1
	v_pk_mul_f32 v[122:123], v[122:123], v[30:31] op_sel_hi:[1,0]
	v_pk_mul_f32 v[124:125], v[124:125], v[30:31] op_sel_hi:[1,0]
	v_pk_fma_f32 v[0:1], v[148:149], v[122:123], v[106:107]
	v_pk_fma_f32 v[2:3], v[150:151], v[124:125], v[108:109]
	global_store_dwordx4 v[86:87], v[0:3], off offset:2048 sc1 nt
	v_pk_fma_f32 v[122:123], v[234:235], v[0:1], v[218:219]
	v_pk_fma_f32 v[124:125], v[236:237], v[2:3], v[220:221]
	s_nop 0
	v_cvt_pk_bf16_f32 v16, v122, v123
	v_cvt_pk_bf16_f32 v17, v124, v125
	global_store_dwordx2 v[88:89], v[16:17], off offset:1024 sc1
	v_pk_mul_f32 v[126:127], v[126:127], v[30:31] op_sel_hi:[1,0]
	v_pk_mul_f32 v[128:129], v[128:129], v[30:31] op_sel_hi:[1,0]
	v_pk_fma_f32 v[4:5], v[152:153], v[126:127], v[110:111]
	v_pk_fma_f32 v[6:7], v[154:155], v[128:129], v[112:113]
	global_store_dwordx4 v[86:87], v[4:7], off offset:3072 sc1 nt
	v_pk_fma_f32 v[126:127], v[238:239], v[4:5], v[222:223]
	v_pk_fma_f32 v[128:129], v[240:241], v[6:7], v[224:225]
	s_nop 0
	v_cvt_pk_bf16_f32 v18, v126, v127
	v_cvt_pk_bf16_f32 v19, v128, v129
	global_store_dwordx2 v[88:89], v[18:19], off offset:1536 sc1
	v_lshl_add_u64 v[86:87], v[86:87], 0, s[0:1]
	v_lshl_add_u64 v[88:89], v[88:89], 0, s[20:21]
	global_load_dwordx4 v[20:23], v[82:83], off nt
	global_load_dwordx4 v[24:27], v[82:83], off offset:1024 nt
	global_load_dwordx4 v[0:3], v[82:83], off offset:2048 nt
	global_load_dwordx4 v[4:7], v[82:83], off offset:3072 nt
	global_load_dwordx2 v[12:13], v[84:85], off nt
	global_load_dwordx2 v[14:15], v[84:85], off offset:512 nt
	global_load_dwordx2 v[16:17], v[84:85], off offset:1024 nt
	global_load_dwordx2 v[18:19], v[84:85], off offset:1536 nt
	v_lshl_add_u64 v[82:83], v[82:83], 0, s[0:1]
	v_lshl_add_u64 v[84:85], v[84:85], 0, s[20:21]
	s_waitcnt vmcnt(32)
	v_lshlrev_b32_e32 v156, 16, v50
	v_and_b32_e32 v157, 0xffff0000, v50
	v_lshlrev_b32_e32 v50, 16, v51
	v_and_b32_e32 v51, 0xffff0000, v51
	v_lshlrev_b32_e32 v158, 16, v52
	v_and_b32_e32 v159, 0xffff0000, v52
	v_lshlrev_b32_e32 v52, 16, v53
	v_and_b32_e32 v53, 0xffff0000, v53
	v_lshlrev_b32_e32 v160, 16, v54
	v_and_b32_e32 v161, 0xffff0000, v54
	v_lshlrev_b32_e32 v54, 16, v55
	v_and_b32_e32 v55, 0xffff0000, v55
	v_lshlrev_b32_e32 v162, 16, v56
	v_and_b32_e32 v163, 0xffff0000, v56
	v_lshlrev_b32_e32 v56, 16, v57
	v_and_b32_e32 v57, 0xffff0000, v57
	v_pk_mul_f32 v[114:115], v[194:195], v[156:157]
	v_pk_mul_f32 v[116:117], v[196:197], v[50:51]
	v_pk_mul_f32 v[118:119], v[198:199], v[158:159]
	v_pk_mul_f32 v[120:121], v[200:201], v[52:53]
	v_pk_mul_f32 v[122:123], v[202:203], v[160:161]
	v_pk_mul_f32 v[124:125], v[204:205], v[54:55]
	v_pk_mul_f32 v[126:127], v[206:207], v[162:163]
	v_pk_mul_f32 v[128:129], v[208:209], v[56:57]
	v_pk_mul_f32 v[114:115], v[10:11], v[114:115]
	v_pk_mul_f32 v[116:117], v[10:11], v[116:117]
	v_pk_mul_f32 v[118:119], v[10:11], v[118:119]
	v_pk_mul_f32 v[120:121], v[10:11], v[120:121]
	v_pk_mul_f32 v[122:123], v[10:11], v[122:123]
	v_pk_mul_f32 v[124:125], v[10:11], v[124:125]
	v_pk_mul_f32 v[126:127], v[10:11], v[126:127]
	v_pk_mul_f32 v[128:129], v[10:11], v[128:129]
	v_pk_fma_f32 v[114:115], v[34:35], s[28:29], v[114:115] op_sel_hi:[1,0,1]
	v_pk_fma_f32 v[116:117], v[36:37], s[28:29], v[116:117] op_sel_hi:[1,0,1]
	v_pk_fma_f32 v[118:119], v[38:39], s[28:29], v[118:119] op_sel_hi:[1,0,1]
	v_pk_fma_f32 v[120:121], v[40:41], s[28:29], v[120:121] op_sel_hi:[1,0,1]
	v_pk_fma_f32 v[122:123], v[42:43], s[28:29], v[122:123] op_sel_hi:[1,0,1]
	v_pk_fma_f32 v[124:125], v[44:45], s[28:29], v[124:125] op_sel_hi:[1,0,1]
	v_pk_fma_f32 v[126:127], v[46:47], s[28:29], v[126:127] op_sel_hi:[1,0,1]
	v_pk_fma_f32 v[128:129], v[48:49], s[28:29], v[128:129] op_sel_hi:[1,0,1]
	v_add_f32_e32 v164, v114, v115
	v_add_f32_e32 v165, v116, v117
	v_add_f32_e32 v166, v118, v119
	v_add_f32_e32 v167, v120, v121
	v_add_f32_e32 v168, v122, v123
	v_add_f32_e32 v169, v124, v125
	v_add_f32_e32 v242, v126, v127
	v_add_f32_e32 v243, v128, v129
	v_add_f32_e32 v164, v164, v165
	v_add_f32_e32 v166, v166, v167
	v_add_f32_e32 v168, v168, v169
	v_add_f32_e32 v242, v242, v243
	v_add_f32_e32 v9, 0, v164
	v_add_f32_e32 v9, v9, v166
	v_add_f32_e32 v9, v9, v168
	v_add_f32_e32 v9, v9, v242
	ds_bpermute_b32 v28, v96, v9
	s_waitcnt lgkmcnt(0)
	v_add_f32_e32 v9, v9, v28
	ds_swizzle_b32 v28, v9 offset:swizzle(SWAP,16)
	s_waitcnt lgkmcnt(0)
	v_add_f32_e32 v9, v9, v28
	ds_swizzle_b32 v28, v9 offset:swizzle(SWAP,8)
	s_waitcnt lgkmcnt(0)
	v_add_f32_e32 v9, v9, v28
	ds_swizzle_b32 v28, v9 offset:swizzle(SWAP,4)
	s_waitcnt lgkmcnt(0)
	v_add_f32_e32 v9, v9, v28
	ds_swizzle_b32 v28, v9 offset:swizzle(SWAP,2)
	s_waitcnt lgkmcnt(0)
	v_add_f32_e32 v9, v9, v28
	ds_swizzle_b32 v28, v9 offset:swizzle(SWAP,1)
	s_waitcnt lgkmcnt(0)
	v_add_f32_e32 v9, v9, v28
	v_fmac_f32_e32 v114, 0xba800000, v9
	v_fmac_f32_e32 v115, 0xba800000, v9
	v_fmac_f32_e32 v116, 0xba800000, v9
	v_fmac_f32_e32 v117, 0xba800000, v9
	v_fmac_f32_e32 v118, 0xba800000, v9
	v_fmac_f32_e32 v119, 0xba800000, v9
	v_fmac_f32_e32 v120, 0xba800000, v9
	v_fmac_f32_e32 v121, 0xba800000, v9
	v_fmac_f32_e32 v122, 0xba800000, v9
	v_fmac_f32_e32 v123, 0xba800000, v9
	v_fmac_f32_e32 v124, 0xba800000, v9
	v_fmac_f32_e32 v125, 0xba800000, v9
	v_fmac_f32_e32 v126, 0xba800000, v9
	v_fmac_f32_e32 v127, 0xba800000, v9
	v_fmac_f32_e32 v128, 0xba800000, v9
	v_fmac_f32_e32 v129, 0xba800000, v9
	v_pk_mul_f32 v[244:245], v[114:115], v[114:115]
	v_pk_mul_f32 v[246:247], v[116:117], v[116:117]
	v_add_f32_e32 v244, v245, v244
	v_add_f32_e32 v246, v246, v247
	v_add_f32_e32 v164, v244, v246
	v_pk_mul_f32 v[244:245], v[118:119], v[118:119]
	v_pk_mul_f32 v[246:247], v[120:121], v[120:121]
	v_add_f32_e32 v244, v245, v244
	v_add_f32_e32 v246, v246, v247
	v_add_f32_e32 v165, v244, v246
	v_mul_f32_e32 v248, v122, v122
	v_mul_f32_e32 v249, v124, v124
	v_fmac_f32_e32 v248, v123, v123
	v_fmac_f32_e32 v249, v125, v125
	v_add_f32_e32 v166, v248, v249
	v_pk_mul_f32 v[244:245], v[126:127], v[126:127]
	v_pk_mul_f32 v[246:247], v[128:129], v[128:129]
	v_add_f32_e32 v244, v244, v245
	v_add_f32_e32 v246, v246, v247
	v_add_f32_e32 v167, v244, v246
	v_add_f32_e32 v164, v164, v165
	v_add_f32_e32 v164, v166, v164
	v_add_f32_e32 v9, v167, v164
	ds_bpermute_b32 v28, v96, v9
	s_waitcnt lgkmcnt(0)
	v_add_f32_e32 v9, v9, v28
	ds_swizzle_b32 v28, v9 offset:swizzle(SWAP,16)
	s_waitcnt lgkmcnt(0)
	v_add_f32_e32 v9, v9, v28
	ds_swizzle_b32 v28, v9 offset:swizzle(SWAP,8)
	s_waitcnt lgkmcnt(0)
	v_add_f32_e32 v9, v9, v28
	ds_swizzle_b32 v28, v9 offset:swizzle(SWAP,4)
	s_waitcnt lgkmcnt(0)
	v_add_f32_e32 v9, v9, v28
	ds_swizzle_b32 v28, v9 offset:swizzle(SWAP,2)
	s_waitcnt lgkmcnt(0)
	v_add_f32_e32 v9, v9, v28
	ds_swizzle_b32 v28, v9 offset:swizzle(SWAP,1)
	s_waitcnt lgkmcnt(0)
	v_add_f32_e32 v9, v9, v28
	v_mov_b32_e32 v28, 0x3727c5ac
	v_fmamk_f32 v9, v9, 0x3a800000, v28
	v_mul_f32_e32 v28, 0x4b800000, v9
	v_cmp_gt_f32_e32 vcc, s37, v9
	s_nop 1
	v_cndmask_b32_e32 v9, v9, v28, vcc
	v_rsq_f32_e32 v9, v9
	s_nop 0
	v_mul_f32_e32 v28, 0x45800000, v9
	v_cndmask_b32_e32 v30, v9, v28, vcc
	v_pk_mul_f32 v[114:115], v[114:115], v[30:31] op_sel_hi:[1,0]
	v_pk_mul_f32 v[116:117], v[116:117], v[30:31] op_sel_hi:[1,0]
	v_pk_fma_f32 v[34:35], v[140:141], v[114:115], v[98:99]
	v_pk_fma_f32 v[36:37], v[142:143], v[116:117], v[100:101]
	global_store_dwordx4 v[86:87], v[34:37], off sc1 nt
	v_pk_fma_f32 v[114:115], v[226:227], v[34:35], v[210:211]
	v_pk_fma_f32 v[116:117], v[228:229], v[36:37], v[212:213]
	s_nop 0
	v_cvt_pk_bf16_f32 v50, v114, v115
	v_cvt_pk_bf16_f32 v51, v116, v117
	global_store_dwordx2 v[88:89], v[50:51], off sc1
	v_pk_mul_f32 v[118:119], v[118:119], v[30:31] op_sel_hi:[1,0]
	v_pk_mul_f32 v[120:121], v[120:121], v[30:31] op_sel_hi:[1,0]
	v_pk_fma_f32 v[38:39], v[144:145], v[118:119], v[102:103]
	v_pk_fma_f32 v[40:41], v[146:147], v[120:121], v[104:105]
	global_store_dwordx4 v[86:87], v[38:41], off offset:1024 sc1 nt
	v_pk_fma_f32 v[118:119], v[230:231], v[38:39], v[214:215]
	v_pk_fma_f32 v[120:121], v[232:233], v[40:41], v[216:217]
	s_nop 0
	v_cvt_pk_bf16_f32 v52, v118, v119
	v_cvt_pk_bf16_f32 v53, v120, v121
	global_store_dwordx2 v[88:89], v[52:53], off offset:512 sc1
	v_pk_mul_f32 v[122:123], v[122:123], v[30:31] op_sel_hi:[1,0]
	v_pk_mul_f32 v[124:125], v[124:125], v[30:31] op_sel_hi:[1,0]
	v_pk_fma_f32 v[42:43], v[148:149], v[122:123], v[106:107]
	v_pk_fma_f32 v[44:45], v[150:151], v[124:125], v[108:109]
	global_store_dwordx4 v[86:87], v[42:45], off offset:2048 sc1 nt
	v_pk_fma_f32 v[122:123], v[234:235], v[42:43], v[218:219]
	v_pk_fma_f32 v[124:125], v[236:237], v[44:45], v[220:221]
	s_nop 0
	v_cvt_pk_bf16_f32 v54, v122, v123
	v_cvt_pk_bf16_f32 v55, v124, v125
	global_store_dwordx2 v[88:89], v[54:55], off offset:1024 sc1
	v_pk_mul_f32 v[126:127], v[126:127], v[30:31] op_sel_hi:[1,0]
	v_pk_mul_f32 v[128:129], v[128:129], v[30:31] op_sel_hi:[1,0]
	v_pk_fma_f32 v[46:47], v[152:153], v[126:127], v[110:111]
	v_pk_fma_f32 v[48:49], v[154:155], v[128:129], v[112:113]
	global_store_dwordx4 v[86:87], v[46:49], off offset:3072 sc1 nt
	v_pk_fma_f32 v[126:127], v[238:239], v[46:47], v[222:223]
	v_pk_fma_f32 v[128:129], v[240:241], v[48:49], v[224:225]
	s_nop 0
	v_cvt_pk_bf16_f32 v56, v126, v127
	v_cvt_pk_bf16_f32 v57, v128, v129
	global_store_dwordx2 v[88:89], v[56:57], off offset:1536 sc1
	v_lshl_add_u64 v[86:87], v[86:87], 0, s[0:1]
	v_lshl_add_u64 v[88:89], v[88:89], 0, s[20:21]
	global_load_dwordx4 v[34:37], v[82:83], off nt
	global_load_dwordx4 v[38:41], v[82:83], off offset:1024 nt
	global_load_dwordx4 v[42:45], v[82:83], off offset:2048 nt
	global_load_dwordx4 v[46:49], v[82:83], off offset:3072 nt
	global_load_dwordx2 v[50:51], v[84:85], off nt
	global_load_dwordx2 v[52:53], v[84:85], off offset:512 nt
	global_load_dwordx2 v[54:55], v[84:85], off offset:1024 nt
	global_load_dwordx2 v[56:57], v[84:85], off offset:1536 nt
	v_lshl_add_u64 v[82:83], v[82:83], 0, s[0:1]
	v_lshl_add_u64 v[84:85], v[84:85], 0, s[20:21]
	s_waitcnt vmcnt(32)
	v_lshlrev_b32_e32 v156, 16, v74
	v_and_b32_e32 v157, 0xffff0000, v74
	v_lshlrev_b32_e32 v74, 16, v75
	v_and_b32_e32 v75, 0xffff0000, v75
	v_lshlrev_b32_e32 v158, 16, v76
	v_and_b32_e32 v159, 0xffff0000, v76
	v_lshlrev_b32_e32 v76, 16, v77
	v_and_b32_e32 v77, 0xffff0000, v77
	v_lshlrev_b32_e32 v160, 16, v78
	v_and_b32_e32 v161, 0xffff0000, v78
	v_lshlrev_b32_e32 v78, 16, v79
	v_and_b32_e32 v79, 0xffff0000, v79
	v_lshlrev_b32_e32 v162, 16, v80
	v_and_b32_e32 v163, 0xffff0000, v80
	v_lshlrev_b32_e32 v80, 16, v81
	v_and_b32_e32 v81, 0xffff0000, v81
	v_pk_mul_f32 v[114:115], v[194:195], v[156:157]
	v_pk_mul_f32 v[116:117], v[196:197], v[74:75]
	v_pk_mul_f32 v[118:119], v[198:199], v[158:159]
	v_pk_mul_f32 v[120:121], v[200:201], v[76:77]
	v_pk_mul_f32 v[122:123], v[202:203], v[160:161]
	v_pk_mul_f32 v[124:125], v[204:205], v[78:79]
	v_pk_mul_f32 v[126:127], v[206:207], v[162:163]
	v_pk_mul_f32 v[128:129], v[208:209], v[80:81]
	v_pk_mul_f32 v[114:115], v[10:11], v[114:115]
	v_pk_mul_f32 v[116:117], v[10:11], v[116:117]
	v_pk_mul_f32 v[118:119], v[10:11], v[118:119]
	v_pk_mul_f32 v[120:121], v[10:11], v[120:121]
	v_pk_mul_f32 v[122:123], v[10:11], v[122:123]
	v_pk_mul_f32 v[124:125], v[10:11], v[124:125]
	v_pk_mul_f32 v[126:127], v[10:11], v[126:127]
	v_pk_mul_f32 v[128:129], v[10:11], v[128:129]
	v_pk_fma_f32 v[114:115], v[58:59], s[28:29], v[114:115] op_sel_hi:[1,0,1]
	v_pk_fma_f32 v[116:117], v[60:61], s[28:29], v[116:117] op_sel_hi:[1,0,1]
	v_pk_fma_f32 v[118:119], v[62:63], s[28:29], v[118:119] op_sel_hi:[1,0,1]
	v_pk_fma_f32 v[120:121], v[64:65], s[28:29], v[120:121] op_sel_hi:[1,0,1]
	v_pk_fma_f32 v[122:123], v[66:67], s[28:29], v[122:123] op_sel_hi:[1,0,1]
	v_pk_fma_f32 v[124:125], v[68:69], s[28:29], v[124:125] op_sel_hi:[1,0,1]
	v_pk_fma_f32 v[126:127], v[70:71], s[28:29], v[126:127] op_sel_hi:[1,0,1]
	v_pk_fma_f32 v[128:129], v[72:73], s[28:29], v[128:129] op_sel_hi:[1,0,1]
	v_add_f32_e32 v164, v114, v115
	v_add_f32_e32 v165, v116, v117
	v_add_f32_e32 v166, v118, v119
	v_add_f32_e32 v167, v120, v121
	v_add_f32_e32 v168, v122, v123
	v_add_f32_e32 v169, v124, v125
	v_add_f32_e32 v242, v126, v127
	v_add_f32_e32 v243, v128, v129
	v_add_f32_e32 v164, v164, v165
	v_add_f32_e32 v166, v166, v167
	v_add_f32_e32 v168, v168, v169
	v_add_f32_e32 v242, v242, v243
	v_add_f32_e32 v9, 0, v164
	v_add_f32_e32 v9, v9, v166
	v_add_f32_e32 v9, v9, v168
	v_add_f32_e32 v9, v9, v242
	ds_bpermute_b32 v28, v96, v9
	s_waitcnt lgkmcnt(0)
	v_add_f32_e32 v9, v9, v28
	ds_swizzle_b32 v28, v9 offset:swizzle(SWAP,16)
	s_waitcnt lgkmcnt(0)
	v_add_f32_e32 v9, v9, v28
	ds_swizzle_b32 v28, v9 offset:swizzle(SWAP,8)
	s_waitcnt lgkmcnt(0)
	v_add_f32_e32 v9, v9, v28
	ds_swizzle_b32 v28, v9 offset:swizzle(SWAP,4)
	s_waitcnt lgkmcnt(0)
	v_add_f32_e32 v9, v9, v28
	ds_swizzle_b32 v28, v9 offset:swizzle(SWAP,2)
	s_waitcnt lgkmcnt(0)
	v_add_f32_e32 v9, v9, v28
	ds_swizzle_b32 v28, v9 offset:swizzle(SWAP,1)
	s_waitcnt lgkmcnt(0)
	v_add_f32_e32 v9, v9, v28
	v_fmac_f32_e32 v114, 0xba800000, v9
	v_fmac_f32_e32 v115, 0xba800000, v9
	v_fmac_f32_e32 v116, 0xba800000, v9
	v_fmac_f32_e32 v117, 0xba800000, v9
	v_fmac_f32_e32 v118, 0xba800000, v9
	v_fmac_f32_e32 v119, 0xba800000, v9
	v_fmac_f32_e32 v120, 0xba800000, v9
	v_fmac_f32_e32 v121, 0xba800000, v9
	v_fmac_f32_e32 v122, 0xba800000, v9
	v_fmac_f32_e32 v123, 0xba800000, v9
	v_fmac_f32_e32 v124, 0xba800000, v9
	v_fmac_f32_e32 v125, 0xba800000, v9
	v_fmac_f32_e32 v126, 0xba800000, v9
	v_fmac_f32_e32 v127, 0xba800000, v9
	v_fmac_f32_e32 v128, 0xba800000, v9
	v_fmac_f32_e32 v129, 0xba800000, v9
	v_pk_mul_f32 v[244:245], v[114:115], v[114:115]
	v_pk_mul_f32 v[246:247], v[116:117], v[116:117]
	v_add_f32_e32 v244, v245, v244
	v_add_f32_e32 v246, v246, v247
	v_add_f32_e32 v164, v244, v246
	v_pk_mul_f32 v[244:245], v[118:119], v[118:119]
	v_pk_mul_f32 v[246:247], v[120:121], v[120:121]
	v_add_f32_e32 v244, v245, v244
	v_add_f32_e32 v246, v246, v247
	v_add_f32_e32 v165, v244, v246
	v_mul_f32_e32 v248, v122, v122
	v_mul_f32_e32 v249, v124, v124
	v_fmac_f32_e32 v248, v123, v123
	v_fmac_f32_e32 v249, v125, v125
	v_add_f32_e32 v166, v248, v249
	v_pk_mul_f32 v[244:245], v[126:127], v[126:127]
	v_pk_mul_f32 v[246:247], v[128:129], v[128:129]
	v_add_f32_e32 v244, v244, v245
	v_add_f32_e32 v246, v246, v247
	v_add_f32_e32 v167, v244, v246
	v_add_f32_e32 v164, v164, v165
	v_add_f32_e32 v164, v166, v164
	v_add_f32_e32 v9, v167, v164
	ds_bpermute_b32 v28, v96, v9
	s_waitcnt lgkmcnt(0)
	v_add_f32_e32 v9, v9, v28
	ds_swizzle_b32 v28, v9 offset:swizzle(SWAP,16)
	s_waitcnt lgkmcnt(0)
	v_add_f32_e32 v9, v9, v28
	ds_swizzle_b32 v28, v9 offset:swizzle(SWAP,8)
	s_waitcnt lgkmcnt(0)
	v_add_f32_e32 v9, v9, v28
	ds_swizzle_b32 v28, v9 offset:swizzle(SWAP,4)
	s_waitcnt lgkmcnt(0)
	v_add_f32_e32 v9, v9, v28
	ds_swizzle_b32 v28, v9 offset:swizzle(SWAP,2)
	s_waitcnt lgkmcnt(0)
	v_add_f32_e32 v9, v9, v28
	ds_swizzle_b32 v28, v9 offset:swizzle(SWAP,1)
	s_waitcnt lgkmcnt(0)
	v_add_f32_e32 v9, v9, v28
	v_mov_b32_e32 v28, 0x3727c5ac
	v_fmamk_f32 v9, v9, 0x3a800000, v28
	v_mul_f32_e32 v28, 0x4b800000, v9
	v_cmp_gt_f32_e32 vcc, s37, v9
	s_nop 1
	v_cndmask_b32_e32 v9, v9, v28, vcc
	v_rsq_f32_e32 v9, v9
	s_nop 0
	v_mul_f32_e32 v28, 0x45800000, v9
	v_cndmask_b32_e32 v30, v9, v28, vcc
	v_pk_mul_f32 v[114:115], v[114:115], v[30:31] op_sel_hi:[1,0]
	v_pk_mul_f32 v[116:117], v[116:117], v[30:31] op_sel_hi:[1,0]
	v_pk_fma_f32 v[58:59], v[140:141], v[114:115], v[98:99]
	v_pk_fma_f32 v[60:61], v[142:143], v[116:117], v[100:101]
	global_store_dwordx4 v[86:87], v[58:61], off sc1 nt
	v_pk_fma_f32 v[114:115], v[226:227], v[58:59], v[210:211]
	v_pk_fma_f32 v[116:117], v[228:229], v[60:61], v[212:213]
	s_nop 0
	v_cvt_pk_bf16_f32 v74, v114, v115
	v_cvt_pk_bf16_f32 v75, v116, v117
	global_store_dwordx2 v[88:89], v[74:75], off sc1
	v_pk_mul_f32 v[118:119], v[118:119], v[30:31] op_sel_hi:[1,0]
	v_pk_mul_f32 v[120:121], v[120:121], v[30:31] op_sel_hi:[1,0]
	v_pk_fma_f32 v[62:63], v[144:145], v[118:119], v[102:103]
	v_pk_fma_f32 v[64:65], v[146:147], v[120:121], v[104:105]
	global_store_dwordx4 v[86:87], v[62:65], off offset:1024 sc1 nt
	v_pk_fma_f32 v[118:119], v[230:231], v[62:63], v[214:215]
	v_pk_fma_f32 v[120:121], v[232:233], v[64:65], v[216:217]
	s_nop 0
	v_cvt_pk_bf16_f32 v76, v118, v119
	v_cvt_pk_bf16_f32 v77, v120, v121
	global_store_dwordx2 v[88:89], v[76:77], off offset:512 sc1
	v_pk_mul_f32 v[122:123], v[122:123], v[30:31] op_sel_hi:[1,0]
	v_pk_mul_f32 v[124:125], v[124:125], v[30:31] op_sel_hi:[1,0]
	v_pk_fma_f32 v[66:67], v[148:149], v[122:123], v[106:107]
	v_pk_fma_f32 v[68:69], v[150:151], v[124:125], v[108:109]
	global_store_dwordx4 v[86:87], v[66:69], off offset:2048 sc1 nt
	v_pk_fma_f32 v[122:123], v[234:235], v[66:67], v[218:219]
	v_pk_fma_f32 v[124:125], v[236:237], v[68:69], v[220:221]
	s_nop 0
	v_cvt_pk_bf16_f32 v78, v122, v123
	v_cvt_pk_bf16_f32 v79, v124, v125
	global_store_dwordx2 v[88:89], v[78:79], off offset:1024 sc1
	v_pk_mul_f32 v[126:127], v[126:127], v[30:31] op_sel_hi:[1,0]
	v_pk_mul_f32 v[128:129], v[128:129], v[30:31] op_sel_hi:[1,0]
	v_pk_fma_f32 v[70:71], v[152:153], v[126:127], v[110:111]
	v_pk_fma_f32 v[72:73], v[154:155], v[128:129], v[112:113]
	global_store_dwordx4 v[86:87], v[70:73], off offset:3072 sc1 nt
	v_pk_fma_f32 v[126:127], v[238:239], v[70:71], v[222:223]
	v_pk_fma_f32 v[128:129], v[240:241], v[72:73], v[224:225]
	s_nop 0
	v_cvt_pk_bf16_f32 v80, v126, v127
	v_cvt_pk_bf16_f32 v81, v128, v129
	global_store_dwordx2 v[88:89], v[80:81], off offset:1536 sc1
	v_lshl_add_u64 v[86:87], v[86:87], 0, s[0:1]
	v_lshl_add_u64 v[88:89], v[88:89], 0, s[20:21]
	s_waitcnt vmcnt(24)
	v_lshlrev_b32_e32 v156, 16, v12
	v_and_b32_e32 v157, 0xffff0000, v12
	v_lshlrev_b32_e32 v12, 16, v13
	v_and_b32_e32 v13, 0xffff0000, v13
	v_lshlrev_b32_e32 v158, 16, v14
	v_and_b32_e32 v159, 0xffff0000, v14
	v_lshlrev_b32_e32 v14, 16, v15
	v_and_b32_e32 v15, 0xffff0000, v15
	v_lshlrev_b32_e32 v160, 16, v16
	v_and_b32_e32 v161, 0xffff0000, v16
	v_lshlrev_b32_e32 v16, 16, v17
	v_and_b32_e32 v17, 0xffff0000, v17
	v_lshlrev_b32_e32 v162, 16, v18
	v_and_b32_e32 v163, 0xffff0000, v18
	v_lshlrev_b32_e32 v18, 16, v19
	v_and_b32_e32 v19, 0xffff0000, v19
	v_pk_mul_f32 v[114:115], v[194:195], v[156:157]
	v_pk_mul_f32 v[116:117], v[196:197], v[12:13]
	v_pk_mul_f32 v[118:119], v[198:199], v[158:159]
	v_pk_mul_f32 v[120:121], v[200:201], v[14:15]
	v_pk_mul_f32 v[122:123], v[202:203], v[160:161]
	v_pk_mul_f32 v[124:125], v[204:205], v[16:17]
	v_pk_mul_f32 v[126:127], v[206:207], v[162:163]
	v_pk_mul_f32 v[128:129], v[208:209], v[18:19]
	v_pk_mul_f32 v[114:115], v[10:11], v[114:115]
	v_pk_mul_f32 v[116:117], v[10:11], v[116:117]
	v_pk_mul_f32 v[118:119], v[10:11], v[118:119]
	v_pk_mul_f32 v[120:121], v[10:11], v[120:121]
	v_pk_mul_f32 v[122:123], v[10:11], v[122:123]
	v_pk_mul_f32 v[124:125], v[10:11], v[124:125]
	v_pk_mul_f32 v[126:127], v[10:11], v[126:127]
	v_pk_mul_f32 v[128:129], v[10:11], v[128:129]
	v_pk_fma_f32 v[114:115], v[20:21], s[28:29], v[114:115] op_sel_hi:[1,0,1]
	v_pk_fma_f32 v[116:117], v[22:23], s[28:29], v[116:117] op_sel_hi:[1,0,1]
	v_pk_fma_f32 v[118:119], v[24:25], s[28:29], v[118:119] op_sel_hi:[1,0,1]
	v_pk_fma_f32 v[120:121], v[26:27], s[28:29], v[120:121] op_sel_hi:[1,0,1]
	v_pk_fma_f32 v[122:123], v[0:1], s[28:29], v[122:123] op_sel_hi:[1,0,1]
	v_pk_fma_f32 v[124:125], v[2:3], s[28:29], v[124:125] op_sel_hi:[1,0,1]
	v_pk_fma_f32 v[126:127], v[4:5], s[28:29], v[126:127] op_sel_hi:[1,0,1]
	v_pk_fma_f32 v[128:129], v[6:7], s[28:29], v[128:129] op_sel_hi:[1,0,1]
	v_add_f32_e32 v164, v114, v115
	v_add_f32_e32 v165, v116, v117
	v_add_f32_e32 v166, v118, v119
	v_add_f32_e32 v167, v120, v121
	v_add_f32_e32 v168, v122, v123
	v_add_f32_e32 v169, v124, v125
	v_add_f32_e32 v242, v126, v127
	v_add_f32_e32 v243, v128, v129
	v_add_f32_e32 v164, v164, v165
	v_add_f32_e32 v166, v166, v167
	v_add_f32_e32 v168, v168, v169
	v_add_f32_e32 v242, v242, v243
	v_add_f32_e32 v9, 0, v164
	v_add_f32_e32 v9, v9, v166
	v_add_f32_e32 v9, v9, v168
	v_add_f32_e32 v9, v9, v242
	ds_bpermute_b32 v28, v96, v9
	s_waitcnt lgkmcnt(0)
	v_add_f32_e32 v9, v9, v28
	ds_swizzle_b32 v28, v9 offset:swizzle(SWAP,16)
	s_waitcnt lgkmcnt(0)
	v_add_f32_e32 v9, v9, v28
	ds_swizzle_b32 v28, v9 offset:swizzle(SWAP,8)
	s_waitcnt lgkmcnt(0)
	v_add_f32_e32 v9, v9, v28
	ds_swizzle_b32 v28, v9 offset:swizzle(SWAP,4)
	s_waitcnt lgkmcnt(0)
	v_add_f32_e32 v9, v9, v28
	ds_swizzle_b32 v28, v9 offset:swizzle(SWAP,2)
	s_waitcnt lgkmcnt(0)
	v_add_f32_e32 v9, v9, v28
	ds_swizzle_b32 v28, v9 offset:swizzle(SWAP,1)
	s_waitcnt lgkmcnt(0)
	v_add_f32_e32 v9, v9, v28
	v_fmac_f32_e32 v114, 0xba800000, v9
	v_fmac_f32_e32 v115, 0xba800000, v9
	v_fmac_f32_e32 v116, 0xba800000, v9
	v_fmac_f32_e32 v117, 0xba800000, v9
	v_fmac_f32_e32 v118, 0xba800000, v9
	v_fmac_f32_e32 v119, 0xba800000, v9
	v_fmac_f32_e32 v120, 0xba800000, v9
	v_fmac_f32_e32 v121, 0xba800000, v9
	v_fmac_f32_e32 v122, 0xba800000, v9
	v_fmac_f32_e32 v123, 0xba800000, v9
	v_fmac_f32_e32 v124, 0xba800000, v9
	v_fmac_f32_e32 v125, 0xba800000, v9
	v_fmac_f32_e32 v126, 0xba800000, v9
	v_fmac_f32_e32 v127, 0xba800000, v9
	v_fmac_f32_e32 v128, 0xba800000, v9
	v_fmac_f32_e32 v129, 0xba800000, v9
	v_pk_mul_f32 v[244:245], v[114:115], v[114:115]
	v_pk_mul_f32 v[246:247], v[116:117], v[116:117]
	v_add_f32_e32 v244, v245, v244
	v_add_f32_e32 v246, v246, v247
	v_add_f32_e32 v164, v244, v246
	v_pk_mul_f32 v[244:245], v[118:119], v[118:119]
	v_pk_mul_f32 v[246:247], v[120:121], v[120:121]
	v_add_f32_e32 v244, v245, v244
	v_add_f32_e32 v246, v246, v247
	v_add_f32_e32 v165, v244, v246
	v_mul_f32_e32 v248, v122, v122
	v_mul_f32_e32 v249, v124, v124
	v_fmac_f32_e32 v248, v123, v123
	v_fmac_f32_e32 v249, v125, v125
	v_add_f32_e32 v166, v248, v249
	v_pk_mul_f32 v[244:245], v[126:127], v[126:127]
	v_pk_mul_f32 v[246:247], v[128:129], v[128:129]
	v_add_f32_e32 v244, v244, v245
	v_add_f32_e32 v246, v246, v247
	v_add_f32_e32 v167, v244, v246
	v_add_f32_e32 v164, v164, v165
	v_add_f32_e32 v164, v166, v164
	v_add_f32_e32 v9, v167, v164
	ds_bpermute_b32 v28, v96, v9
	s_waitcnt lgkmcnt(0)
	v_add_f32_e32 v9, v9, v28
	ds_swizzle_b32 v28, v9 offset:swizzle(SWAP,16)
	s_waitcnt lgkmcnt(0)
	v_add_f32_e32 v9, v9, v28
	ds_swizzle_b32 v28, v9 offset:swizzle(SWAP,8)
	s_waitcnt lgkmcnt(0)
	v_add_f32_e32 v9, v9, v28
	ds_swizzle_b32 v28, v9 offset:swizzle(SWAP,4)
	s_waitcnt lgkmcnt(0)
	v_add_f32_e32 v9, v9, v28
	ds_swizzle_b32 v28, v9 offset:swizzle(SWAP,2)
	s_waitcnt lgkmcnt(0)
	v_add_f32_e32 v9, v9, v28
	ds_swizzle_b32 v28, v9 offset:swizzle(SWAP,1)
	s_waitcnt lgkmcnt(0)
	v_add_f32_e32 v9, v9, v28
	v_mov_b32_e32 v28, 0x3727c5ac
	v_fmamk_f32 v9, v9, 0x3a800000, v28
	v_mul_f32_e32 v28, 0x4b800000, v9
	v_cmp_gt_f32_e32 vcc, s37, v9
	s_nop 1
	v_cndmask_b32_e32 v9, v9, v28, vcc
	v_rsq_f32_e32 v9, v9
	s_nop 0
	v_mul_f32_e32 v28, 0x45800000, v9
	v_cndmask_b32_e32 v30, v9, v28, vcc
	v_pk_mul_f32 v[114:115], v[114:115], v[30:31] op_sel_hi:[1,0]
	v_pk_mul_f32 v[116:117], v[116:117], v[30:31] op_sel_hi:[1,0]
	v_pk_fma_f32 v[20:21], v[140:141], v[114:115], v[98:99]
	v_pk_fma_f32 v[22:23], v[142:143], v[116:117], v[100:101]
	global_store_dwordx4 v[86:87], v[20:23], off sc1 nt
	v_pk_fma_f32 v[114:115], v[226:227], v[20:21], v[210:211]
	v_pk_fma_f32 v[116:117], v[228:229], v[22:23], v[212:213]
	s_nop 0
	v_cvt_pk_bf16_f32 v12, v114, v115
	v_cvt_pk_bf16_f32 v13, v116, v117
	global_store_dwordx2 v[88:89], v[12:13], off sc1
	v_pk_mul_f32 v[118:119], v[118:119], v[30:31] op_sel_hi:[1,0]
	v_pk_mul_f32 v[120:121], v[120:121], v[30:31] op_sel_hi:[1,0]
	v_pk_fma_f32 v[24:25], v[144:145], v[118:119], v[102:103]
	v_pk_fma_f32 v[26:27], v[146:147], v[120:121], v[104:105]
	global_store_dwordx4 v[86:87], v[24:27], off offset:1024 sc1 nt
	v_pk_fma_f32 v[118:119], v[230:231], v[24:25], v[214:215]
	v_pk_fma_f32 v[120:121], v[232:233], v[26:27], v[216:217]
	s_nop 0
	v_cvt_pk_bf16_f32 v14, v118, v119
	v_cvt_pk_bf16_f32 v15, v120, v121
	global_store_dwordx2 v[88:89], v[14:15], off offset:512 sc1
	v_pk_mul_f32 v[122:123], v[122:123], v[30:31] op_sel_hi:[1,0]
	v_pk_mul_f32 v[124:125], v[124:125], v[30:31] op_sel_hi:[1,0]
	v_pk_fma_f32 v[0:1], v[148:149], v[122:123], v[106:107]
	v_pk_fma_f32 v[2:3], v[150:151], v[124:125], v[108:109]
	global_store_dwordx4 v[86:87], v[0:3], off offset:2048 sc1 nt
	v_pk_fma_f32 v[122:123], v[234:235], v[0:1], v[218:219]
	v_pk_fma_f32 v[124:125], v[236:237], v[2:3], v[220:221]
	s_nop 0
	v_cvt_pk_bf16_f32 v16, v122, v123
	v_cvt_pk_bf16_f32 v17, v124, v125
	global_store_dwordx2 v[88:89], v[16:17], off offset:1024 sc1
	v_pk_mul_f32 v[126:127], v[126:127], v[30:31] op_sel_hi:[1,0]
	v_pk_mul_f32 v[128:129], v[128:129], v[30:31] op_sel_hi:[1,0]
	v_pk_fma_f32 v[4:5], v[152:153], v[126:127], v[110:111]
	v_pk_fma_f32 v[6:7], v[154:155], v[128:129], v[112:113]
	global_store_dwordx4 v[86:87], v[4:7], off offset:3072 sc1 nt
	v_pk_fma_f32 v[126:127], v[238:239], v[4:5], v[222:223]
	v_pk_fma_f32 v[128:129], v[240:241], v[6:7], v[224:225]
	s_nop 0
	v_cvt_pk_bf16_f32 v18, v126, v127
	v_cvt_pk_bf16_f32 v19, v128, v129
	global_store_dwordx2 v[88:89], v[18:19], off offset:1536 sc1
	v_lshl_add_u64 v[86:87], v[86:87], 0, s[0:1]
	v_lshl_add_u64 v[88:89], v[88:89], 0, s[20:21]
	s_waitcnt vmcnt(16)
	v_lshlrev_b32_e32 v156, 16, v50
	v_and_b32_e32 v157, 0xffff0000, v50
	v_lshlrev_b32_e32 v50, 16, v51
	v_and_b32_e32 v51, 0xffff0000, v51
	v_lshlrev_b32_e32 v158, 16, v52
	v_and_b32_e32 v159, 0xffff0000, v52
	v_lshlrev_b32_e32 v52, 16, v53
	v_and_b32_e32 v53, 0xffff0000, v53
	v_lshlrev_b32_e32 v160, 16, v54
	v_and_b32_e32 v161, 0xffff0000, v54
	v_lshlrev_b32_e32 v54, 16, v55
	v_and_b32_e32 v55, 0xffff0000, v55
	v_lshlrev_b32_e32 v162, 16, v56
	v_and_b32_e32 v163, 0xffff0000, v56
	v_lshlrev_b32_e32 v56, 16, v57
	v_and_b32_e32 v57, 0xffff0000, v57
	v_pk_mul_f32 v[114:115], v[194:195], v[156:157]
	v_pk_mul_f32 v[116:117], v[196:197], v[50:51]
	v_pk_mul_f32 v[118:119], v[198:199], v[158:159]
	v_pk_mul_f32 v[120:121], v[200:201], v[52:53]
	v_pk_mul_f32 v[122:123], v[202:203], v[160:161]
	v_pk_mul_f32 v[124:125], v[204:205], v[54:55]
	v_pk_mul_f32 v[126:127], v[206:207], v[162:163]
	v_pk_mul_f32 v[128:129], v[208:209], v[56:57]
	v_pk_mul_f32 v[114:115], v[10:11], v[114:115]
	v_pk_mul_f32 v[116:117], v[10:11], v[116:117]
	v_pk_mul_f32 v[118:119], v[10:11], v[118:119]
	v_pk_mul_f32 v[120:121], v[10:11], v[120:121]
	v_pk_mul_f32 v[122:123], v[10:11], v[122:123]
	v_pk_mul_f32 v[124:125], v[10:11], v[124:125]
	v_pk_mul_f32 v[126:127], v[10:11], v[126:127]
	v_pk_mul_f32 v[128:129], v[10:11], v[128:129]
	v_pk_fma_f32 v[114:115], v[34:35], s[28:29], v[114:115] op_sel_hi:[1,0,1]
	v_pk_fma_f32 v[116:117], v[36:37], s[28:29], v[116:117] op_sel_hi:[1,0,1]
	v_pk_fma_f32 v[118:119], v[38:39], s[28:29], v[118:119] op_sel_hi:[1,0,1]
	v_pk_fma_f32 v[120:121], v[40:41], s[28:29], v[120:121] op_sel_hi:[1,0,1]
	v_pk_fma_f32 v[122:123], v[42:43], s[28:29], v[122:123] op_sel_hi:[1,0,1]
	v_pk_fma_f32 v[124:125], v[44:45], s[28:29], v[124:125] op_sel_hi:[1,0,1]
	v_pk_fma_f32 v[126:127], v[46:47], s[28:29], v[126:127] op_sel_hi:[1,0,1]
	v_pk_fma_f32 v[128:129], v[48:49], s[28:29], v[128:129] op_sel_hi:[1,0,1]
	v_add_f32_e32 v164, v114, v115
	v_add_f32_e32 v165, v116, v117
	v_add_f32_e32 v166, v118, v119
	v_add_f32_e32 v167, v120, v121
	v_add_f32_e32 v168, v122, v123
	v_add_f32_e32 v169, v124, v125
	v_add_f32_e32 v242, v126, v127
	v_add_f32_e32 v243, v128, v129
	v_add_f32_e32 v164, v164, v165
	v_add_f32_e32 v166, v166, v167
	v_add_f32_e32 v168, v168, v169
	v_add_f32_e32 v242, v242, v243
	v_add_f32_e32 v9, 0, v164
	v_add_f32_e32 v9, v9, v166
	v_add_f32_e32 v9, v9, v168
	v_add_f32_e32 v9, v9, v242
	ds_bpermute_b32 v28, v96, v9
	s_waitcnt lgkmcnt(0)
	v_add_f32_e32 v9, v9, v28
	ds_swizzle_b32 v28, v9 offset:swizzle(SWAP,16)
	s_waitcnt lgkmcnt(0)
	v_add_f32_e32 v9, v9, v28
	ds_swizzle_b32 v28, v9 offset:swizzle(SWAP,8)
	s_waitcnt lgkmcnt(0)
	v_add_f32_e32 v9, v9, v28
	ds_swizzle_b32 v28, v9 offset:swizzle(SWAP,4)
	s_waitcnt lgkmcnt(0)
	v_add_f32_e32 v9, v9, v28
	ds_swizzle_b32 v28, v9 offset:swizzle(SWAP,2)
	s_waitcnt lgkmcnt(0)
	v_add_f32_e32 v9, v9, v28
	ds_swizzle_b32 v28, v9 offset:swizzle(SWAP,1)
	s_waitcnt lgkmcnt(0)
	v_add_f32_e32 v9, v9, v28
	v_fmac_f32_e32 v114, 0xba800000, v9
	v_fmac_f32_e32 v115, 0xba800000, v9
	v_fmac_f32_e32 v116, 0xba800000, v9
	v_fmac_f32_e32 v117, 0xba800000, v9
	v_fmac_f32_e32 v118, 0xba800000, v9
	v_fmac_f32_e32 v119, 0xba800000, v9
	v_fmac_f32_e32 v120, 0xba800000, v9
	v_fmac_f32_e32 v121, 0xba800000, v9
	v_fmac_f32_e32 v122, 0xba800000, v9
	v_fmac_f32_e32 v123, 0xba800000, v9
	v_fmac_f32_e32 v124, 0xba800000, v9
	v_fmac_f32_e32 v125, 0xba800000, v9
	v_fmac_f32_e32 v126, 0xba800000, v9
	v_fmac_f32_e32 v127, 0xba800000, v9
	v_fmac_f32_e32 v128, 0xba800000, v9
	v_fmac_f32_e32 v129, 0xba800000, v9
	v_pk_mul_f32 v[244:245], v[114:115], v[114:115]
	v_pk_mul_f32 v[246:247], v[116:117], v[116:117]
	v_add_f32_e32 v244, v245, v244
	v_add_f32_e32 v246, v246, v247
	v_add_f32_e32 v164, v244, v246
	v_pk_mul_f32 v[244:245], v[118:119], v[118:119]
	v_pk_mul_f32 v[246:247], v[120:121], v[120:121]
	v_add_f32_e32 v244, v245, v244
	v_add_f32_e32 v246, v246, v247
	v_add_f32_e32 v165, v244, v246
	v_mul_f32_e32 v248, v122, v122
	v_mul_f32_e32 v249, v124, v124
	v_fmac_f32_e32 v248, v123, v123
	v_fmac_f32_e32 v249, v125, v125
	v_add_f32_e32 v166, v248, v249
	v_pk_mul_f32 v[244:245], v[126:127], v[126:127]
	v_pk_mul_f32 v[246:247], v[128:129], v[128:129]
	v_add_f32_e32 v244, v244, v245
	v_add_f32_e32 v246, v246, v247
	v_add_f32_e32 v167, v244, v246
	v_add_f32_e32 v164, v164, v165
	v_add_f32_e32 v164, v166, v164
	v_add_f32_e32 v9, v167, v164
	ds_bpermute_b32 v28, v96, v9
	s_waitcnt lgkmcnt(0)
	v_add_f32_e32 v9, v9, v28
	ds_swizzle_b32 v28, v9 offset:swizzle(SWAP,16)
	s_waitcnt lgkmcnt(0)
	v_add_f32_e32 v9, v9, v28
	ds_swizzle_b32 v28, v9 offset:swizzle(SWAP,8)
	s_waitcnt lgkmcnt(0)
	v_add_f32_e32 v9, v9, v28
	ds_swizzle_b32 v28, v9 offset:swizzle(SWAP,4)
	s_waitcnt lgkmcnt(0)
	v_add_f32_e32 v9, v9, v28
	ds_swizzle_b32 v28, v9 offset:swizzle(SWAP,2)
	s_waitcnt lgkmcnt(0)
	v_add_f32_e32 v9, v9, v28
	ds_swizzle_b32 v28, v9 offset:swizzle(SWAP,1)
	s_waitcnt lgkmcnt(0)
	v_add_f32_e32 v9, v9, v28
	v_mov_b32_e32 v28, 0x3727c5ac
	v_fmamk_f32 v9, v9, 0x3a800000, v28
	v_mul_f32_e32 v28, 0x4b800000, v9
	v_cmp_gt_f32_e32 vcc, s37, v9
	s_nop 1
	v_cndmask_b32_e32 v9, v9, v28, vcc
	v_rsq_f32_e32 v9, v9
	s_nop 0
	v_mul_f32_e32 v28, 0x45800000, v9
	v_cndmask_b32_e32 v30, v9, v28, vcc
	v_pk_mul_f32 v[114:115], v[114:115], v[30:31] op_sel_hi:[1,0]
	v_pk_mul_f32 v[116:117], v[116:117], v[30:31] op_sel_hi:[1,0]
	v_pk_fma_f32 v[34:35], v[140:141], v[114:115], v[98:99]
	v_pk_fma_f32 v[36:37], v[142:143], v[116:117], v[100:101]
	global_store_dwordx4 v[86:87], v[34:37], off sc1 nt
	v_pk_fma_f32 v[114:115], v[226:227], v[34:35], v[210:211]
	v_pk_fma_f32 v[116:117], v[228:229], v[36:37], v[212:213]
	s_nop 0
	v_cvt_pk_bf16_f32 v50, v114, v115
	v_cvt_pk_bf16_f32 v51, v116, v117
	global_store_dwordx2 v[88:89], v[50:51], off sc1
	v_pk_mul_f32 v[118:119], v[118:119], v[30:31] op_sel_hi:[1,0]
	v_pk_mul_f32 v[120:121], v[120:121], v[30:31] op_sel_hi:[1,0]
	v_pk_fma_f32 v[38:39], v[144:145], v[118:119], v[102:103]
	v_pk_fma_f32 v[40:41], v[146:147], v[120:121], v[104:105]
	global_store_dwordx4 v[86:87], v[38:41], off offset:1024 sc1 nt
	v_pk_fma_f32 v[118:119], v[230:231], v[38:39], v[214:215]
	v_pk_fma_f32 v[120:121], v[232:233], v[40:41], v[216:217]
	s_nop 0
	v_cvt_pk_bf16_f32 v52, v118, v119
	v_cvt_pk_bf16_f32 v53, v120, v121
	global_store_dwordx2 v[88:89], v[52:53], off offset:512 sc1
	v_pk_mul_f32 v[122:123], v[122:123], v[30:31] op_sel_hi:[1,0]
	v_pk_mul_f32 v[124:125], v[124:125], v[30:31] op_sel_hi:[1,0]
	v_pk_fma_f32 v[42:43], v[148:149], v[122:123], v[106:107]
	v_pk_fma_f32 v[44:45], v[150:151], v[124:125], v[108:109]
	global_store_dwordx4 v[86:87], v[42:45], off offset:2048 sc1 nt
	v_pk_fma_f32 v[122:123], v[234:235], v[42:43], v[218:219]
	v_pk_fma_f32 v[124:125], v[236:237], v[44:45], v[220:221]
	s_nop 0
	v_cvt_pk_bf16_f32 v54, v122, v123
	v_cvt_pk_bf16_f32 v55, v124, v125
	global_store_dwordx2 v[88:89], v[54:55], off offset:1024 sc1
	v_pk_mul_f32 v[126:127], v[126:127], v[30:31] op_sel_hi:[1,0]
	v_pk_mul_f32 v[128:129], v[128:129], v[30:31] op_sel_hi:[1,0]
	v_pk_fma_f32 v[46:47], v[152:153], v[126:127], v[110:111]
	v_pk_fma_f32 v[48:49], v[154:155], v[128:129], v[112:113]
	global_store_dwordx4 v[86:87], v[46:49], off offset:3072 sc1 nt
	v_pk_fma_f32 v[126:127], v[238:239], v[46:47], v[222:223]
	v_pk_fma_f32 v[128:129], v[240:241], v[48:49], v[224:225]
	s_nop 0
	v_cvt_pk_bf16_f32 v56, v126, v127
	v_cvt_pk_bf16_f32 v57, v128, v129
	global_store_dwordx2 v[88:89], v[56:57], off offset:1536 sc1
	v_lshl_add_u64 v[86:87], v[86:87], 0, s[0:1]
	v_lshl_add_u64 v[88:89], v[88:89], 0, s[20:21]
	s_branch .LBB0_53

.LBB0_92:
	s_add_i32 s1, s1, s4
	s_cmp_ge_i32 s1, s16
	s_waitcnt lgkmcnt(0)
	s_cselect_b64 s[44:45], -1, 0
	s_cmp_lt_i32 s1, s16
	s_cselect_b64 s[52:53], -1, 0
	s_and_b64 s[18:19], s[52:53], exec
	s_cselect_b32 s7, s1, 0
	s_and_b64 vcc, exec, s[40:41]
	s_mov_b32 s30, 0
	s_cbranch_vccnz .LBB0_97
	v_readlane_b32 s17, v255, 61
	s_mov_b32 s30, s5
	s_cmp_ge_u32 s17, s5
	s_cbranch_scc1 .LBB0_97
	s_lshl_b32 s18, s17, 2
	s_add_u32 s48, s58, s18
	s_addc_u32 s49, s59, 0
	s_branch .LBB0_95

.LBB0_97:
	v_writelane_b32 v255, s30, 61
	s_cmp_eq_u32 s30, 0
	s_mov_b32 s17, 0
	s_cbranch_scc1 .LBB0_99
	s_lshl_b64 s[18:19], s[30:31], 2
	s_add_u32 s18, s72, s18
	s_addc_u32 s19, s73, s19
	s_load_dword s17, s[18:19], 0x44c
	s_mov_b64 s[48:49], s[30:31]
	s_branch .LBB0_100

.LBB0_264:
	s_add_i32 s22, s84, 2
	s_add_u32 s0, s82, 0x80
	s_addc_u32 s1, s83, 0
	s_add_i32 s30, 0, 0x10000
	s_cmp_eq_u32 s57, s84
	s_cselect_b32 s85, s45, s1
	s_cselect_b32 s84, s44, s0
	v_add_u32_e32 v154, s30, v139
	s_cselect_b32 s1, s81, vcc_hi
	s_cselect_b32 s0, s80, vcc_lo
	s_add_i32 s86, 0, 0x14000
	ds_read_b128 v[130:133], v154
	ds_read_b128 v[150:153], v154 offset:1024
	ds_read_b128 v[162:165], v154 offset:2048
	ds_read_b128 v[166:169], v154 offset:3072
	v_add_u32_e32 v154, s86, v139
	ds_read_b128 v[194:197], v154
	ds_read_b128 v[198:201], v154 offset:1024
	ds_read_b128 v[202:205], v154 offset:2048
	ds_read_b128 v[206:209], v154 offset:3072
	v_lshl_add_u64 v[154:155], s[82:83], 0, v[146:147]
	s_add_i32 m0, s91, 0xc000
	ds_read_b128 v[210:213], v160
	ds_read_b128 v[214:217], v160 offset:1024
	ds_read_b128 v[218:221], v160 offset:2048
	ds_read_b128 v[222:225], v160 offset:3072
	ds_read_b128 v[226:229], v160 offset:4096
	ds_read_b128 v[230:233], v160 offset:5120
	ds_read_b128 v[234:237], v160 offset:6144
	ds_read_b128 v[238:241], v160 offset:7168
	global_load_lds_dwordx4 v[154:155], off
	v_lshl_add_u64 v[154:155], s[82:83], 0, v[148:149]
	s_add_i32 m0, s91, 0xe000
	s_nop 0
	global_load_lds_dwordx4 v[154:155], off
	s_waitcnt vmcnt(8)
	s_waitcnt lgkmcnt(0)
	s_barrier
	s_waitcnt lgkmcnt(0)
	v_mfma_f32_16x16x32_bf16 v[126:129], v[130:133], v[210:213], v[126:129]
	v_mfma_f32_16x16x32_bf16 v[122:125], v[162:165], v[210:213], v[122:125]
	v_mfma_f32_16x16x32_bf16 v[110:113], v[130:133], v[218:221], v[110:113]
	v_mfma_f32_16x16x32_bf16 v[106:109], v[162:165], v[218:221], v[106:109]
	v_mfma_f32_16x16x32_bf16 v[94:97], v[130:133], v[226:229], v[94:97]
	v_mfma_f32_16x16x32_bf16 v[90:93], v[162:165], v[226:229], v[90:93]
	v_mfma_f32_16x16x32_bf16 v[78:81], v[130:133], v[234:237], v[78:81]
	v_mfma_f32_16x16x32_bf16 v[74:77], v[162:165], v[234:237], v[74:77]
	v_mfma_f32_16x16x32_bf16 v[126:129], v[150:153], v[214:217], v[126:129]
	v_mfma_f32_16x16x32_bf16 v[122:125], v[166:169], v[214:217], v[122:125]
	v_mfma_f32_16x16x32_bf16 v[110:113], v[150:153], v[222:225], v[110:113]
	v_mfma_f32_16x16x32_bf16 v[106:109], v[166:169], v[222:225], v[106:109]
	v_mfma_f32_16x16x32_bf16 v[94:97], v[150:153], v[230:233], v[94:97]
	v_mfma_f32_16x16x32_bf16 v[90:93], v[166:169], v[230:233], v[90:93]
	v_mfma_f32_16x16x32_bf16 v[78:81], v[150:153], v[238:241], v[78:81]
	v_mfma_f32_16x16x32_bf16 v[74:77], v[166:169], v[238:241], v[74:77]
	v_mfma_f32_16x16x32_bf16 v[118:121], v[194:197], v[210:213], v[118:121]
	v_mfma_f32_16x16x32_bf16 v[114:117], v[202:205], v[210:213], v[114:117]
	v_mfma_f32_16x16x32_bf16 v[102:105], v[194:197], v[218:221], v[102:105]
	v_mfma_f32_16x16x32_bf16 v[98:101], v[202:205], v[218:221], v[98:101]
	v_mfma_f32_16x16x32_bf16 v[86:89], v[194:197], v[226:229], v[86:89]
	v_mfma_f32_16x16x32_bf16 v[82:85], v[202:205], v[226:229], v[82:85]
	v_mfma_f32_16x16x32_bf16 v[70:73], v[194:197], v[234:237], v[70:73]
	v_mfma_f32_16x16x32_bf16 v[66:69], v[202:205], v[234:237], v[66:69]
	v_mfma_f32_16x16x32_bf16 v[118:121], v[198:201], v[214:217], v[118:121]
	v_mfma_f32_16x16x32_bf16 v[114:117], v[206:209], v[214:217], v[114:117]
	v_mfma_f32_16x16x32_bf16 v[102:105], v[198:201], v[222:225], v[102:105]
	v_mfma_f32_16x16x32_bf16 v[98:101], v[206:209], v[222:225], v[98:101]
	v_mfma_f32_16x16x32_bf16 v[86:89], v[198:201], v[230:233], v[86:89]
	v_mfma_f32_16x16x32_bf16 v[82:85], v[206:209], v[230:233], v[82:85]
	v_mfma_f32_16x16x32_bf16 v[70:73], v[198:201], v[238:241], v[70:73]
	v_mfma_f32_16x16x32_bf16 v[66:69], v[206:209], v[238:241], v[66:69]
	s_barrier
	s_add_i32 s30, s30, s99
	v_lshl_add_u64 v[154:155], s[0:1], 0, v[32:33]
	s_mov_b32 m0, s30
	ds_read_b128 v[210:213], v160 offset:16384
	ds_read_b128 v[214:217], v160 offset:17408
	ds_read_b128 v[218:221], v160 offset:18432
	ds_read_b128 v[222:225], v160 offset:19456
	ds_read_b128 v[226:229], v160 offset:20480
	ds_read_b128 v[230:233], v160 offset:21504
	ds_read_b128 v[234:237], v160 offset:22528
	ds_read_b128 v[238:241], v160 offset:23552
	global_load_lds_dwordx4 v[154:155], off
	s_add_i32 m0, s30, 0x2000
	v_lshl_add_u64 v[158:159], s[0:1], 0, v[144:145]
	s_add_u32 s0, s0, s66
	s_addc_u32 s1, s1, s67
	s_add_i32 s30, s86, s99
	global_load_lds_dwordx4 v[158:159], off
	v_lshl_add_u64 v[242:243], s[0:1], 0, v[32:33]
	s_mov_b32 m0, s30
	v_lshl_add_u64 v[244:245], s[0:1], 0, v[144:145]
	global_load_lds_dwordx4 v[242:243], off
	s_add_i32 m0, s30, 0x2000
	v_lshl_add_u64 v[246:247], s[84:85], 0, v[140:141]
	global_load_lds_dwordx4 v[244:245], off
	s_mov_b32 m0, s91
	v_lshl_add_u64 v[248:249], s[84:85], 0, v[142:143]
	global_load_lds_dwordx4 v[246:247], off
	s_mov_b32 m0, s20
	s_nop 0
	global_load_lds_dwordx4 v[248:249], off
	s_waitcnt vmcnt(8)
	s_waitcnt lgkmcnt(0)
	s_barrier
	s_waitcnt lgkmcnt(0)
	v_mfma_f32_16x16x32_bf16 v[62:65], v[130:133], v[210:213], v[62:65]
	v_mfma_f32_16x16x32_bf16 v[58:61], v[162:165], v[210:213], v[58:61]
	v_mfma_f32_16x16x32_bf16 v[46:49], v[130:133], v[218:221], v[46:49]
	v_mfma_f32_16x16x32_bf16 v[42:45], v[162:165], v[218:221], v[42:45]
	v_mfma_f32_16x16x32_bf16 v[28:31], v[130:133], v[226:229], v[28:31]
	v_mfma_f32_16x16x32_bf16 v[24:27], v[162:165], v[226:229], v[24:27]
	v_mfma_f32_16x16x32_bf16 v[12:15], v[130:133], v[234:237], v[12:15]
	v_mfma_f32_16x16x32_bf16 v[8:11], v[162:165], v[234:237], v[8:11]
	v_mfma_f32_16x16x32_bf16 v[62:65], v[150:153], v[214:217], v[62:65]
	v_mfma_f32_16x16x32_bf16 v[58:61], v[166:169], v[214:217], v[58:61]
	v_mfma_f32_16x16x32_bf16 v[46:49], v[150:153], v[222:225], v[46:49]
	v_mfma_f32_16x16x32_bf16 v[42:45], v[166:169], v[222:225], v[42:45]
	v_mfma_f32_16x16x32_bf16 v[28:31], v[150:153], v[230:233], v[28:31]
	v_mfma_f32_16x16x32_bf16 v[24:27], v[166:169], v[230:233], v[24:27]
	v_mfma_f32_16x16x32_bf16 v[12:15], v[150:153], v[238:241], v[12:15]
	v_mfma_f32_16x16x32_bf16 v[8:11], v[166:169], v[238:241], v[8:11]
	v_mfma_f32_16x16x32_bf16 v[54:57], v[194:197], v[210:213], v[54:57]
	v_mfma_f32_16x16x32_bf16 v[50:53], v[202:205], v[210:213], v[50:53]
	v_mfma_f32_16x16x32_bf16 v[38:41], v[194:197], v[218:221], v[38:41]
	v_mfma_f32_16x16x32_bf16 v[34:37], v[202:205], v[218:221], v[34:37]
	v_mfma_f32_16x16x32_bf16 v[20:23], v[194:197], v[226:229], v[20:23]
	v_mfma_f32_16x16x32_bf16 v[16:19], v[202:205], v[226:229], v[16:19]
	v_mfma_f32_16x16x32_bf16 v[4:7], v[194:197], v[234:237], v[4:7]
	v_mfma_f32_16x16x32_bf16 v[0:3], v[202:205], v[234:237], v[0:3]
	v_mfma_f32_16x16x32_bf16 v[54:57], v[198:201], v[214:217], v[54:57]
	v_mfma_f32_16x16x32_bf16 v[50:53], v[206:209], v[214:217], v[50:53]
	v_mfma_f32_16x16x32_bf16 v[38:41], v[198:201], v[222:225], v[38:41]
	v_mfma_f32_16x16x32_bf16 v[34:37], v[206:209], v[222:225], v[34:37]
	v_mfma_f32_16x16x32_bf16 v[20:23], v[198:201], v[230:233], v[20:23]
	v_mfma_f32_16x16x32_bf16 v[16:19], v[206:209], v[230:233], v[16:19]
	v_mfma_f32_16x16x32_bf16 v[4:7], v[198:201], v[238:241], v[4:7]
	v_mfma_f32_16x16x32_bf16 v[0:3], v[206:209], v[238:241], v[0:3]
	s_barrier
	s_add_i32 s30, 0, 0x18000
	v_add_u32_e32 v156, s30, v139
	s_add_i32 s86, 0, 0x1c000
	ds_read_b128 v[130:133], v156
	ds_read_b128 v[150:153], v156 offset:1024
	ds_read_b128 v[162:165], v156 offset:2048
	ds_read_b128 v[166:169], v156 offset:3072
	v_add_u32_e32 v156, s86, v139
	ds_read_b128 v[194:197], v156
	ds_read_b128 v[198:201], v156 offset:1024
	ds_read_b128 v[202:205], v156 offset:2048
	ds_read_b128 v[206:209], v156 offset:3072
	s_add_u32 s0, s84, s66
	s_addc_u32 s1, s85, s67
	s_mov_b32 m0, s25
	v_lshl_add_u64 v[250:251], s[0:1], 0, v[140:141]
	ds_read_b128 v[210:213], v160 offset:32768
	ds_read_b128 v[214:217], v160 offset:33792
	ds_read_b128 v[218:221], v160 offset:34816
	ds_read_b128 v[222:225], v160 offset:35840
	ds_read_b128 v[226:229], v160 offset:36864
	ds_read_b128 v[230:233], v160 offset:37888
	ds_read_b128 v[234:237], v160 offset:38912
	ds_read_b128 v[238:241], v160 offset:39936
	global_load_lds_dwordx4 v[250:251], off
	v_lshl_add_u64 v[250:251], s[0:1], 0, v[142:143]
	s_mov_b32 m0, s52
	s_nop 0
	global_load_lds_dwordx4 v[250:251], off
	s_waitcnt vmcnt(8)
	s_waitcnt lgkmcnt(0)
	s_barrier
	s_waitcnt lgkmcnt(0)
	v_mfma_f32_16x16x32_bf16 v[126:129], v[130:133], v[210:213], v[126:129]
	v_mfma_f32_16x16x32_bf16 v[122:125], v[162:165], v[210:213], v[122:125]
	v_mfma_f32_16x16x32_bf16 v[110:113], v[130:133], v[218:221], v[110:113]
	v_mfma_f32_16x16x32_bf16 v[106:109], v[162:165], v[218:221], v[106:109]
	v_mfma_f32_16x16x32_bf16 v[94:97], v[130:133], v[226:229], v[94:97]
	v_mfma_f32_16x16x32_bf16 v[90:93], v[162:165], v[226:229], v[90:93]
	v_mfma_f32_16x16x32_bf16 v[78:81], v[130:133], v[234:237], v[78:81]
	v_mfma_f32_16x16x32_bf16 v[74:77], v[162:165], v[234:237], v[74:77]
	v_mfma_f32_16x16x32_bf16 v[126:129], v[150:153], v[214:217], v[126:129]
	v_mfma_f32_16x16x32_bf16 v[122:125], v[166:169], v[214:217], v[122:125]
	v_mfma_f32_16x16x32_bf16 v[110:113], v[150:153], v[222:225], v[110:113]
	v_mfma_f32_16x16x32_bf16 v[106:109], v[166:169], v[222:225], v[106:109]
	v_mfma_f32_16x16x32_bf16 v[94:97], v[150:153], v[230:233], v[94:97]
	v_mfma_f32_16x16x32_bf16 v[90:93], v[166:169], v[230:233], v[90:93]
	v_mfma_f32_16x16x32_bf16 v[78:81], v[150:153], v[238:241], v[78:81]
	v_mfma_f32_16x16x32_bf16 v[74:77], v[166:169], v[238:241], v[74:77]
	v_mfma_f32_16x16x32_bf16 v[118:121], v[194:197], v[210:213], v[118:121]
	v_mfma_f32_16x16x32_bf16 v[114:117], v[202:205], v[210:213], v[114:117]
	v_mfma_f32_16x16x32_bf16 v[102:105], v[194:197], v[218:221], v[102:105]
	v_mfma_f32_16x16x32_bf16 v[98:101], v[202:205], v[218:221], v[98:101]
	v_mfma_f32_16x16x32_bf16 v[86:89], v[194:197], v[226:229], v[86:89]
	v_mfma_f32_16x16x32_bf16 v[82:85], v[202:205], v[226:229], v[82:85]
	v_mfma_f32_16x16x32_bf16 v[70:73], v[194:197], v[234:237], v[70:73]
	v_mfma_f32_16x16x32_bf16 v[66:69], v[202:205], v[234:237], v[66:69]
	v_mfma_f32_16x16x32_bf16 v[118:121], v[198:201], v[214:217], v[118:121]
	v_mfma_f32_16x16x32_bf16 v[114:117], v[206:209], v[214:217], v[114:117]
	v_mfma_f32_16x16x32_bf16 v[102:105], v[198:201], v[222:225], v[102:105]
	v_mfma_f32_16x16x32_bf16 v[98:101], v[206:209], v[222:225], v[98:101]
	v_mfma_f32_16x16x32_bf16 v[86:89], v[198:201], v[230:233], v[86:89]
	v_mfma_f32_16x16x32_bf16 v[82:85], v[206:209], v[230:233], v[82:85]
	v_mfma_f32_16x16x32_bf16 v[70:73], v[198:201], v[238:241], v[70:73]
	v_mfma_f32_16x16x32_bf16 v[66:69], v[206:209], v[238:241], v[66:69]
	s_barrier
	s_add_i32 s0, s30, s99
	v_lshl_add_u64 v[154:155], v[154:155], 0, s[26:27]
	s_mov_b32 m0, s0
	ds_read_b128 v[210:213], v160 offset:49152
	ds_read_b128 v[214:217], v160 offset:50176
	ds_read_b128 v[218:221], v160 offset:51200
	ds_read_b128 v[222:225], v160 offset:52224
	ds_read_b128 v[226:229], v160 offset:53248
	ds_read_b128 v[230:233], v160 offset:54272
	ds_read_b128 v[234:237], v160 offset:55296
	ds_read_b128 v[238:241], v160 offset:56320
	global_load_lds_dwordx4 v[154:155], off
	v_lshl_add_u64 v[154:155], v[158:159], 0, s[26:27]
	s_add_i32 m0, s0, 0x2000
	s_add_i32 s0, s86, s99
	global_load_lds_dwordx4 v[154:155], off
	v_lshl_add_u64 v[154:155], v[242:243], 0, s[26:27]
	s_mov_b32 m0, s0
	s_nop 0
	global_load_lds_dwordx4 v[154:155], off
	v_lshl_add_u64 v[154:155], v[244:245], 0, s[26:27]
	s_add_i32 m0, s0, 0x2000
	s_nop 0
	global_load_lds_dwordx4 v[154:155], off
	v_lshl_add_u64 v[154:155], v[246:247], 0, s[26:27]
	s_mov_b32 m0, s53
	s_nop 0
	global_load_lds_dwordx4 v[154:155], off
	v_lshl_add_u64 v[154:155], v[248:249], 0, s[26:27]
	s_mov_b32 m0, s56
	s_nop 0
	global_load_lds_dwordx4 v[154:155], off
	s_waitcnt vmcnt(8)
	s_waitcnt lgkmcnt(0)
	s_barrier
	s_waitcnt lgkmcnt(0)
	v_mfma_f32_16x16x32_bf16 v[62:65], v[130:133], v[210:213], v[62:65]
	v_mfma_f32_16x16x32_bf16 v[58:61], v[162:165], v[210:213], v[58:61]
	v_mfma_f32_16x16x32_bf16 v[46:49], v[130:133], v[218:221], v[46:49]
	v_mfma_f32_16x16x32_bf16 v[42:45], v[162:165], v[218:221], v[42:45]
	v_mfma_f32_16x16x32_bf16 v[28:31], v[130:133], v[226:229], v[28:31]
	v_mfma_f32_16x16x32_bf16 v[24:27], v[162:165], v[226:229], v[24:27]
	v_mfma_f32_16x16x32_bf16 v[12:15], v[130:133], v[234:237], v[12:15]
	v_mfma_f32_16x16x32_bf16 v[8:11], v[162:165], v[234:237], v[8:11]
	v_mfma_f32_16x16x32_bf16 v[62:65], v[150:153], v[214:217], v[62:65]
	v_mfma_f32_16x16x32_bf16 v[58:61], v[166:169], v[214:217], v[58:61]
	v_mfma_f32_16x16x32_bf16 v[46:49], v[150:153], v[222:225], v[46:49]
	v_mfma_f32_16x16x32_bf16 v[42:45], v[166:169], v[222:225], v[42:45]
	v_mfma_f32_16x16x32_bf16 v[28:31], v[150:153], v[230:233], v[28:31]
	v_mfma_f32_16x16x32_bf16 v[24:27], v[166:169], v[230:233], v[24:27]
	v_mfma_f32_16x16x32_bf16 v[12:15], v[150:153], v[238:241], v[12:15]
	v_mfma_f32_16x16x32_bf16 v[8:11], v[166:169], v[238:241], v[8:11]
	v_mfma_f32_16x16x32_bf16 v[54:57], v[194:197], v[210:213], v[54:57]
	v_mfma_f32_16x16x32_bf16 v[50:53], v[202:205], v[210:213], v[50:53]
	v_mfma_f32_16x16x32_bf16 v[38:41], v[194:197], v[218:221], v[38:41]
	v_mfma_f32_16x16x32_bf16 v[34:37], v[202:205], v[218:221], v[34:37]
	v_mfma_f32_16x16x32_bf16 v[20:23], v[194:197], v[226:229], v[20:23]
	v_mfma_f32_16x16x32_bf16 v[16:19], v[202:205], v[226:229], v[16:19]
	v_mfma_f32_16x16x32_bf16 v[4:7], v[194:197], v[234:237], v[4:7]
	v_mfma_f32_16x16x32_bf16 v[0:3], v[202:205], v[234:237], v[0:3]
	v_mfma_f32_16x16x32_bf16 v[54:57], v[198:201], v[214:217], v[54:57]
	v_mfma_f32_16x16x32_bf16 v[50:53], v[206:209], v[214:217], v[50:53]
	v_mfma_f32_16x16x32_bf16 v[38:41], v[198:201], v[222:225], v[38:41]
	v_mfma_f32_16x16x32_bf16 v[34:37], v[206:209], v[222:225], v[34:37]
	v_mfma_f32_16x16x32_bf16 v[20:23], v[198:201], v[230:233], v[20:23]
	v_mfma_f32_16x16x32_bf16 v[16:19], v[206:209], v[230:233], v[16:19]
	v_mfma_f32_16x16x32_bf16 v[4:7], v[198:201], v[238:241], v[4:7]
	v_mfma_f32_16x16x32_bf16 v[0:3], v[206:209], v[238:241], v[0:3]
	s_barrier
	s_add_u32 s82, s82, 0x100
	s_addc_u32 s83, s83, 0
	s_add_u32 vcc_lo, vcc_lo, 0x100
	s_addc_u32 vcc_hi, vcc_hi, 0
	s_cmp_ge_i32 s22, s94
	s_mov_b32 s84, s22
	s_cbranch_scc0 .LBB0_264
	s_and_b64 vcc, exec, s[78:79]
	s_cbranch_vccz .LBB0_267
	s_barrier

.LBB0_296:
	s_add_i32 vcc_hi, s82, 2
	s_add_u32 s0, s80, 0x80
	s_addc_u32 s1, s81, 0
	s_add_i32 s30, 0, 0x10000
	s_cmp_eq_u32 s85, s82
	s_cselect_b32 s83, s45, s1
	s_cselect_b32 s82, s44, s0
	v_add_u32_e32 v146, s30, v139
	s_cselect_b32 s1, s79, vcc_lo
	s_cselect_b32 s0, s78, s90
	s_add_i32 s86, 0, 0x14000
	ds_read_b128 v[150:153], v146
	ds_read_b128 v[154:157], v146 offset:1024
	ds_read_b128 v[158:161], v146 offset:2048
	ds_read_b128 v[162:165], v146 offset:3072
	v_add_u32_e32 v146, s86, v139
	ds_read_b128 v[166:169], v146
	ds_read_b128 v[194:197], v146 offset:1024
	ds_read_b128 v[198:201], v146 offset:2048
	ds_read_b128 v[202:205], v146 offset:3072
	v_lshl_add_u64 v[146:147], s[80:81], 0, v[130:131]
	s_add_i32 m0, s54, 0xc000
	ds_read_b128 v[206:209], v149
	ds_read_b128 v[210:213], v149 offset:1024
	ds_read_b128 v[214:217], v149 offset:2048
	ds_read_b128 v[218:221], v149 offset:3072
	ds_read_b128 v[222:225], v149 offset:4096
	ds_read_b128 v[226:229], v149 offset:5120
	ds_read_b128 v[230:233], v149 offset:6144
	ds_read_b128 v[234:237], v149 offset:7168
	global_load_lds_dwordx4 v[146:147], off
	v_lshl_add_u64 v[146:147], s[80:81], 0, v[132:133]
	s_add_i32 m0, s54, 0xe000
	s_nop 0
	global_load_lds_dwordx4 v[146:147], off
	s_waitcnt vmcnt(8)
	s_waitcnt lgkmcnt(0)
	s_barrier
	s_waitcnt lgkmcnt(0)
	v_mfma_f32_16x16x32_bf16 v[126:129], v[150:153], v[206:209], v[126:129]
	v_mfma_f32_16x16x32_bf16 v[118:121], v[158:161], v[206:209], v[118:121]
	v_mfma_f32_16x16x32_bf16 v[110:113], v[150:153], v[214:217], v[110:113]
	v_mfma_f32_16x16x32_bf16 v[102:105], v[158:161], v[214:217], v[102:105]
	v_mfma_f32_16x16x32_bf16 v[94:97], v[150:153], v[222:225], v[94:97]
	v_mfma_f32_16x16x32_bf16 v[86:89], v[158:161], v[222:225], v[86:89]
	v_mfma_f32_16x16x32_bf16 v[78:81], v[150:153], v[230:233], v[78:81]
	v_mfma_f32_16x16x32_bf16 v[70:73], v[158:161], v[230:233], v[70:73]
	v_mfma_f32_16x16x32_bf16 v[126:129], v[154:157], v[210:213], v[126:129]
	v_mfma_f32_16x16x32_bf16 v[118:121], v[162:165], v[210:213], v[118:121]
	v_mfma_f32_16x16x32_bf16 v[110:113], v[154:157], v[218:221], v[110:113]
	v_mfma_f32_16x16x32_bf16 v[102:105], v[162:165], v[218:221], v[102:105]
	v_mfma_f32_16x16x32_bf16 v[94:97], v[154:157], v[226:229], v[94:97]
	v_mfma_f32_16x16x32_bf16 v[86:89], v[162:165], v[226:229], v[86:89]
	v_mfma_f32_16x16x32_bf16 v[78:81], v[154:157], v[234:237], v[78:81]
	v_mfma_f32_16x16x32_bf16 v[70:73], v[162:165], v[234:237], v[70:73]
	v_mfma_f32_16x16x32_bf16 v[122:125], v[166:169], v[206:209], v[122:125]
	v_mfma_f32_16x16x32_bf16 v[114:117], v[198:201], v[206:209], v[114:117]
	v_mfma_f32_16x16x32_bf16 v[106:109], v[166:169], v[214:217], v[106:109]
	v_mfma_f32_16x16x32_bf16 v[98:101], v[198:201], v[214:217], v[98:101]
	v_mfma_f32_16x16x32_bf16 v[90:93], v[166:169], v[222:225], v[90:93]
	v_mfma_f32_16x16x32_bf16 v[82:85], v[198:201], v[222:225], v[82:85]
	v_mfma_f32_16x16x32_bf16 v[74:77], v[166:169], v[230:233], v[74:77]
	v_mfma_f32_16x16x32_bf16 v[66:69], v[198:201], v[230:233], v[66:69]
	v_mfma_f32_16x16x32_bf16 v[122:125], v[194:197], v[210:213], v[122:125]
	v_mfma_f32_16x16x32_bf16 v[114:117], v[202:205], v[210:213], v[114:117]
	v_mfma_f32_16x16x32_bf16 v[106:109], v[194:197], v[218:221], v[106:109]
	v_mfma_f32_16x16x32_bf16 v[98:101], v[202:205], v[218:221], v[98:101]
	v_mfma_f32_16x16x32_bf16 v[90:93], v[194:197], v[226:229], v[90:93]
	v_mfma_f32_16x16x32_bf16 v[82:85], v[202:205], v[226:229], v[82:85]
	v_mfma_f32_16x16x32_bf16 v[74:77], v[194:197], v[234:237], v[74:77]
	v_mfma_f32_16x16x32_bf16 v[66:69], v[202:205], v[234:237], v[66:69]
	s_barrier
	s_add_i32 s30, s30, s25
	v_lshl_add_u64 v[146:147], s[0:1], 0, v[32:33]
	s_mov_b32 m0, s30
	ds_read_b128 v[206:209], v149 offset:16384
	ds_read_b128 v[210:213], v149 offset:17408
	ds_read_b128 v[214:217], v149 offset:18432
	ds_read_b128 v[218:221], v149 offset:19456
	ds_read_b128 v[222:225], v149 offset:20480
	ds_read_b128 v[226:229], v149 offset:21504
	ds_read_b128 v[230:233], v149 offset:22528
	ds_read_b128 v[234:237], v149 offset:23552
	global_load_lds_dwordx4 v[146:147], off
	s_add_i32 m0, s30, 0x2000
	v_lshl_add_u64 v[238:239], s[0:1], 0, v[144:145]
	s_add_u32 s0, s0, s66
	s_addc_u32 s1, s1, s67
	s_add_i32 s30, s86, s25
	global_load_lds_dwordx4 v[238:239], off
	v_lshl_add_u64 v[240:241], s[0:1], 0, v[32:33]
	s_mov_b32 m0, s30
	v_lshl_add_u64 v[242:243], s[0:1], 0, v[144:145]
	global_load_lds_dwordx4 v[240:241], off
	s_add_i32 m0, s30, 0x2000
	v_lshl_add_u64 v[244:245], s[82:83], 0, v[140:141]
	global_load_lds_dwordx4 v[242:243], off
	s_mov_b32 m0, s54
	v_lshl_add_u64 v[246:247], s[82:83], 0, v[142:143]
	global_load_lds_dwordx4 v[244:245], off
	s_mov_b32 m0, s55
	s_nop 0
	global_load_lds_dwordx4 v[246:247], off
	s_waitcnt vmcnt(8)
	s_waitcnt lgkmcnt(0)
	s_barrier
	s_waitcnt lgkmcnt(0)
	v_mfma_f32_16x16x32_bf16 v[62:65], v[150:153], v[206:209], v[62:65]
	v_mfma_f32_16x16x32_bf16 v[54:57], v[158:161], v[206:209], v[54:57]
	v_mfma_f32_16x16x32_bf16 v[46:49], v[150:153], v[214:217], v[46:49]
	v_mfma_f32_16x16x32_bf16 v[38:41], v[158:161], v[214:217], v[38:41]
	v_mfma_f32_16x16x32_bf16 v[28:31], v[150:153], v[222:225], v[28:31]
	v_mfma_f32_16x16x32_bf16 v[20:23], v[158:161], v[222:225], v[20:23]
	v_mfma_f32_16x16x32_bf16 v[12:15], v[150:153], v[230:233], v[12:15]
	v_mfma_f32_16x16x32_bf16 v[4:7], v[158:161], v[230:233], v[4:7]
	v_mfma_f32_16x16x32_bf16 v[62:65], v[154:157], v[210:213], v[62:65]
	v_mfma_f32_16x16x32_bf16 v[54:57], v[162:165], v[210:213], v[54:57]
	v_mfma_f32_16x16x32_bf16 v[46:49], v[154:157], v[218:221], v[46:49]
	v_mfma_f32_16x16x32_bf16 v[38:41], v[162:165], v[218:221], v[38:41]
	v_mfma_f32_16x16x32_bf16 v[28:31], v[154:157], v[226:229], v[28:31]
	v_mfma_f32_16x16x32_bf16 v[20:23], v[162:165], v[226:229], v[20:23]
	v_mfma_f32_16x16x32_bf16 v[12:15], v[154:157], v[234:237], v[12:15]
	v_mfma_f32_16x16x32_bf16 v[4:7], v[162:165], v[234:237], v[4:7]
	v_mfma_f32_16x16x32_bf16 v[58:61], v[166:169], v[206:209], v[58:61]
	v_mfma_f32_16x16x32_bf16 v[50:53], v[198:201], v[206:209], v[50:53]
	v_mfma_f32_16x16x32_bf16 v[42:45], v[166:169], v[214:217], v[42:45]
	v_mfma_f32_16x16x32_bf16 v[34:37], v[198:201], v[214:217], v[34:37]
	v_mfma_f32_16x16x32_bf16 v[24:27], v[166:169], v[222:225], v[24:27]
	v_mfma_f32_16x16x32_bf16 v[16:19], v[198:201], v[222:225], v[16:19]
	v_mfma_f32_16x16x32_bf16 v[8:11], v[166:169], v[230:233], v[8:11]
	v_mfma_f32_16x16x32_bf16 v[0:3], v[198:201], v[230:233], v[0:3]
	v_mfma_f32_16x16x32_bf16 v[58:61], v[194:197], v[210:213], v[58:61]
	v_mfma_f32_16x16x32_bf16 v[50:53], v[202:205], v[210:213], v[50:53]
	v_mfma_f32_16x16x32_bf16 v[42:45], v[194:197], v[218:221], v[42:45]
	v_mfma_f32_16x16x32_bf16 v[34:37], v[202:205], v[218:221], v[34:37]
	v_mfma_f32_16x16x32_bf16 v[24:27], v[194:197], v[226:229], v[24:27]
	v_mfma_f32_16x16x32_bf16 v[16:19], v[202:205], v[226:229], v[16:19]
	v_mfma_f32_16x16x32_bf16 v[8:11], v[194:197], v[234:237], v[8:11]
	v_mfma_f32_16x16x32_bf16 v[0:3], v[202:205], v[234:237], v[0:3]
	s_barrier
	s_add_i32 s30, 0, 0x18000
	s_add_i32 s86, 0, 0x1c000
	v_add_u32_e32 v162, s30, v139
	v_add_u32_e32 v181, s86, v139
	ds_read_b128 v[150:153], v162
	ds_read_b128 v[154:157], v162 offset:1024
	ds_read_b128 v[158:161], v162 offset:2048
	ds_read_b128 v[162:165], v162 offset:3072
	ds_read_b128 v[166:169], v181
	ds_read_b128 v[194:197], v181 offset:1024
	ds_read_b128 v[198:201], v181 offset:2048
	ds_read_b128 v[202:205], v181 offset:3072
	s_add_u32 s0, s82, s66
	s_addc_u32 s1, s83, s67
	s_mov_b32 m0, s56
	v_lshl_add_u64 v[248:249], s[0:1], 0, v[140:141]
	ds_read_b128 v[206:209], v149 offset:32768
	ds_read_b128 v[210:213], v149 offset:33792
	ds_read_b128 v[214:217], v149 offset:34816
	ds_read_b128 v[218:221], v149 offset:35840
	ds_read_b128 v[222:225], v149 offset:36864
	ds_read_b128 v[226:229], v149 offset:37888
	ds_read_b128 v[230:233], v149 offset:38912
	ds_read_b128 v[234:237], v149 offset:39936
	global_load_lds_dwordx4 v[248:249], off
	v_lshl_add_u64 v[248:249], s[0:1], 0, v[142:143]
	s_mov_b32 m0, s57
	s_nop 0
	global_load_lds_dwordx4 v[248:249], off
	s_waitcnt vmcnt(8)
	s_waitcnt lgkmcnt(0)
	s_barrier
	s_waitcnt lgkmcnt(0)
	v_mfma_f32_16x16x32_bf16 v[126:129], v[150:153], v[206:209], v[126:129]
	v_mfma_f32_16x16x32_bf16 v[118:121], v[158:161], v[206:209], v[118:121]
	v_mfma_f32_16x16x32_bf16 v[110:113], v[150:153], v[214:217], v[110:113]
	v_mfma_f32_16x16x32_bf16 v[102:105], v[158:161], v[214:217], v[102:105]
	v_mfma_f32_16x16x32_bf16 v[94:97], v[150:153], v[222:225], v[94:97]
	v_mfma_f32_16x16x32_bf16 v[86:89], v[158:161], v[222:225], v[86:89]
	v_mfma_f32_16x16x32_bf16 v[78:81], v[150:153], v[230:233], v[78:81]
	v_mfma_f32_16x16x32_bf16 v[70:73], v[158:161], v[230:233], v[70:73]
	v_mfma_f32_16x16x32_bf16 v[126:129], v[154:157], v[210:213], v[126:129]
	v_mfma_f32_16x16x32_bf16 v[118:121], v[162:165], v[210:213], v[118:121]
	v_mfma_f32_16x16x32_bf16 v[110:113], v[154:157], v[218:221], v[110:113]
	v_mfma_f32_16x16x32_bf16 v[102:105], v[162:165], v[218:221], v[102:105]
	v_mfma_f32_16x16x32_bf16 v[94:97], v[154:157], v[226:229], v[94:97]
	v_mfma_f32_16x16x32_bf16 v[86:89], v[162:165], v[226:229], v[86:89]
	v_mfma_f32_16x16x32_bf16 v[78:81], v[154:157], v[234:237], v[78:81]
	v_mfma_f32_16x16x32_bf16 v[70:73], v[162:165], v[234:237], v[70:73]
	v_mfma_f32_16x16x32_bf16 v[122:125], v[166:169], v[206:209], v[122:125]
	v_mfma_f32_16x16x32_bf16 v[114:117], v[198:201], v[206:209], v[114:117]
	v_mfma_f32_16x16x32_bf16 v[106:109], v[166:169], v[214:217], v[106:109]
	v_mfma_f32_16x16x32_bf16 v[98:101], v[198:201], v[214:217], v[98:101]
	v_mfma_f32_16x16x32_bf16 v[90:93], v[166:169], v[222:225], v[90:93]
	v_mfma_f32_16x16x32_bf16 v[82:85], v[198:201], v[222:225], v[82:85]
	v_mfma_f32_16x16x32_bf16 v[74:77], v[166:169], v[230:233], v[74:77]
	v_mfma_f32_16x16x32_bf16 v[66:69], v[198:201], v[230:233], v[66:69]
	v_mfma_f32_16x16x32_bf16 v[122:125], v[194:197], v[210:213], v[122:125]
	v_mfma_f32_16x16x32_bf16 v[114:117], v[202:205], v[210:213], v[114:117]
	v_mfma_f32_16x16x32_bf16 v[106:109], v[194:197], v[218:221], v[106:109]
	v_mfma_f32_16x16x32_bf16 v[98:101], v[202:205], v[218:221], v[98:101]
	v_mfma_f32_16x16x32_bf16 v[90:93], v[194:197], v[226:229], v[90:93]
	v_mfma_f32_16x16x32_bf16 v[82:85], v[202:205], v[226:229], v[82:85]
	v_mfma_f32_16x16x32_bf16 v[74:77], v[194:197], v[234:237], v[74:77]
	v_mfma_f32_16x16x32_bf16 v[66:69], v[202:205], v[234:237], v[66:69]
	s_barrier
	s_add_i32 s0, s30, s25
	v_lshl_add_u64 v[146:147], v[146:147], 0, s[26:27]
	s_mov_b32 m0, s0
	ds_read_b128 v[206:209], v149 offset:49152
	ds_read_b128 v[210:213], v149 offset:50176
	ds_read_b128 v[214:217], v149 offset:51200
	ds_read_b128 v[218:221], v149 offset:52224
	ds_read_b128 v[222:225], v149 offset:53248
	ds_read_b128 v[226:229], v149 offset:54272
	ds_read_b128 v[230:233], v149 offset:55296
	ds_read_b128 v[234:237], v149 offset:56320
	global_load_lds_dwordx4 v[146:147], off
	v_lshl_add_u64 v[146:147], v[238:239], 0, s[26:27]
	s_add_i32 m0, s0, 0x2000
	s_add_i32 s0, s86, s25
	global_load_lds_dwordx4 v[146:147], off
	v_lshl_add_u64 v[146:147], v[240:241], 0, s[26:27]
	s_mov_b32 m0, s0
	s_nop 0
	global_load_lds_dwordx4 v[146:147], off
	v_lshl_add_u64 v[146:147], v[242:243], 0, s[26:27]
	s_add_i32 m0, s0, 0x2000
	s_nop 0
	global_load_lds_dwordx4 v[146:147], off
	v_lshl_add_u64 v[146:147], v[244:245], 0, s[26:27]
	s_mov_b32 m0, s71
	s_nop 0
	global_load_lds_dwordx4 v[146:147], off
	v_lshl_add_u64 v[146:147], v[246:247], 0, s[26:27]
	s_mov_b32 m0, s84
	s_nop 0
	global_load_lds_dwordx4 v[146:147], off
	s_waitcnt vmcnt(8)
	s_waitcnt lgkmcnt(0)
	s_barrier
	s_waitcnt lgkmcnt(0)
	v_mfma_f32_16x16x32_bf16 v[62:65], v[150:153], v[206:209], v[62:65]
	v_mfma_f32_16x16x32_bf16 v[54:57], v[158:161], v[206:209], v[54:57]
	v_mfma_f32_16x16x32_bf16 v[46:49], v[150:153], v[214:217], v[46:49]
	v_mfma_f32_16x16x32_bf16 v[38:41], v[158:161], v[214:217], v[38:41]
	v_mfma_f32_16x16x32_bf16 v[28:31], v[150:153], v[222:225], v[28:31]
	v_mfma_f32_16x16x32_bf16 v[20:23], v[158:161], v[222:225], v[20:23]
	v_mfma_f32_16x16x32_bf16 v[12:15], v[150:153], v[230:233], v[12:15]
	v_mfma_f32_16x16x32_bf16 v[4:7], v[158:161], v[230:233], v[4:7]
	v_mfma_f32_16x16x32_bf16 v[62:65], v[154:157], v[210:213], v[62:65]
	v_mfma_f32_16x16x32_bf16 v[54:57], v[162:165], v[210:213], v[54:57]
	v_mfma_f32_16x16x32_bf16 v[46:49], v[154:157], v[218:221], v[46:49]
	v_mfma_f32_16x16x32_bf16 v[38:41], v[162:165], v[218:221], v[38:41]
	v_mfma_f32_16x16x32_bf16 v[28:31], v[154:157], v[226:229], v[28:31]
	v_mfma_f32_16x16x32_bf16 v[20:23], v[162:165], v[226:229], v[20:23]
	v_mfma_f32_16x16x32_bf16 v[12:15], v[154:157], v[234:237], v[12:15]
	v_mfma_f32_16x16x32_bf16 v[4:7], v[162:165], v[234:237], v[4:7]
	v_mfma_f32_16x16x32_bf16 v[58:61], v[166:169], v[206:209], v[58:61]
	v_mfma_f32_16x16x32_bf16 v[50:53], v[198:201], v[206:209], v[50:53]
	v_mfma_f32_16x16x32_bf16 v[42:45], v[166:169], v[214:217], v[42:45]
	v_mfma_f32_16x16x32_bf16 v[34:37], v[198:201], v[214:217], v[34:37]
	v_mfma_f32_16x16x32_bf16 v[24:27], v[166:169], v[222:225], v[24:27]
	v_mfma_f32_16x16x32_bf16 v[16:19], v[198:201], v[222:225], v[16:19]
	v_mfma_f32_16x16x32_bf16 v[8:11], v[166:169], v[230:233], v[8:11]
	v_mfma_f32_16x16x32_bf16 v[0:3], v[198:201], v[230:233], v[0:3]
	v_mfma_f32_16x16x32_bf16 v[58:61], v[194:197], v[210:213], v[58:61]
	v_mfma_f32_16x16x32_bf16 v[50:53], v[202:205], v[210:213], v[50:53]
	v_mfma_f32_16x16x32_bf16 v[42:45], v[194:197], v[218:221], v[42:45]
	v_mfma_f32_16x16x32_bf16 v[34:37], v[202:205], v[218:221], v[34:37]
	v_mfma_f32_16x16x32_bf16 v[24:27], v[194:197], v[226:229], v[24:27]
	v_mfma_f32_16x16x32_bf16 v[16:19], v[202:205], v[226:229], v[16:19]
	v_mfma_f32_16x16x32_bf16 v[8:11], v[194:197], v[234:237], v[8:11]
	v_mfma_f32_16x16x32_bf16 v[0:3], v[202:205], v[234:237], v[0:3]
	s_barrier
	s_add_u32 s80, s80, 0x100
	s_addc_u32 s81, s81, 0
	s_add_u32 s90, s90, 0x100
	s_addc_u32 vcc_lo, vcc_lo, 0
	s_cmp_ge_i32 vcc_hi, s94
	s_mov_b32 s82, vcc_hi
	s_cbranch_scc0 .LBB0_296
	s_and_b64 vcc, exec, s[76:77]
	s_cbranch_vccz .LBB0_299
	s_barrier

.LBB0_327:
	s_add_i32 s0, s80, 2
	s_add_u32 s1, s78, 0x80
	s_addc_u32 s30, s79, 0
	s_add_i32 s86, 0, 0x10000
	s_cmp_eq_u32 s82, s80
	s_cselect_b32 s81, s45, s30
	s_cselect_b32 s80, s44, s1
	s_cselect_b32 s99, s77, s97
	s_cselect_b32 s98, s76, s96
	s_add_i32 s1, 0, 0x14000
	v_add_u32_e32 v160, s86, v139
	v_add_u32_e32 v168, s1, v139
	ds_read_b128 v[146:149], v160
	ds_read_b128 v[152:155], v160 offset:1024
	ds_read_b128 v[156:159], v160 offset:2048
	ds_read_b128 v[160:163], v160 offset:3072
	ds_read_b128 v[164:167], v168
	ds_read_b128 v[194:197], v168 offset:1024
	ds_read_b128 v[198:201], v168 offset:2048
	ds_read_b128 v[202:205], v168 offset:3072
	v_lshl_add_u64 v[168:169], s[78:79], 0, v[130:131]
	s_add_i32 m0, s53, 0xc000
	ds_read_b128 v[206:209], v151
	ds_read_b128 v[210:213], v151 offset:1024
	ds_read_b128 v[214:217], v151 offset:2048
	ds_read_b128 v[218:221], v151 offset:3072
	ds_read_b128 v[222:225], v151 offset:4096
	ds_read_b128 v[226:229], v151 offset:5120
	ds_read_b128 v[230:233], v151 offset:6144
	ds_read_b128 v[234:237], v151 offset:7168
	global_load_lds_dwordx4 v[168:169], off
	v_lshl_add_u64 v[168:169], s[78:79], 0, v[132:133]
	s_add_i32 m0, s53, 0xe000
	s_nop 0
	global_load_lds_dwordx4 v[168:169], off
	s_waitcnt vmcnt(8)
	s_waitcnt lgkmcnt(0)
	s_barrier
	s_waitcnt lgkmcnt(0)
	v_mfma_f32_16x16x32_bf16 v[126:129], v[146:149], v[206:209], v[126:129]
	v_mfma_f32_16x16x32_bf16 v[122:125], v[156:159], v[206:209], v[122:125]
	v_mfma_f32_16x16x32_bf16 v[110:113], v[146:149], v[214:217], v[110:113]
	v_mfma_f32_16x16x32_bf16 v[106:109], v[156:159], v[214:217], v[106:109]
	v_mfma_f32_16x16x32_bf16 v[94:97], v[146:149], v[222:225], v[94:97]
	v_mfma_f32_16x16x32_bf16 v[90:93], v[156:159], v[222:225], v[90:93]
	v_mfma_f32_16x16x32_bf16 v[78:81], v[146:149], v[230:233], v[78:81]
	v_mfma_f32_16x16x32_bf16 v[74:77], v[156:159], v[230:233], v[74:77]
	v_mfma_f32_16x16x32_bf16 v[126:129], v[152:155], v[210:213], v[126:129]
	v_mfma_f32_16x16x32_bf16 v[122:125], v[160:163], v[210:213], v[122:125]
	v_mfma_f32_16x16x32_bf16 v[110:113], v[152:155], v[218:221], v[110:113]
	v_mfma_f32_16x16x32_bf16 v[106:109], v[160:163], v[218:221], v[106:109]
	v_mfma_f32_16x16x32_bf16 v[94:97], v[152:155], v[226:229], v[94:97]
	v_mfma_f32_16x16x32_bf16 v[90:93], v[160:163], v[226:229], v[90:93]
	v_mfma_f32_16x16x32_bf16 v[78:81], v[152:155], v[234:237], v[78:81]
	v_mfma_f32_16x16x32_bf16 v[74:77], v[160:163], v[234:237], v[74:77]
	v_mfma_f32_16x16x32_bf16 v[118:121], v[164:167], v[206:209], v[118:121]
	v_mfma_f32_16x16x32_bf16 v[114:117], v[198:201], v[206:209], v[114:117]
	v_mfma_f32_16x16x32_bf16 v[102:105], v[164:167], v[214:217], v[102:105]
	v_mfma_f32_16x16x32_bf16 v[98:101], v[198:201], v[214:217], v[98:101]
	v_mfma_f32_16x16x32_bf16 v[86:89], v[164:167], v[222:225], v[86:89]
	v_mfma_f32_16x16x32_bf16 v[82:85], v[198:201], v[222:225], v[82:85]
	v_mfma_f32_16x16x32_bf16 v[70:73], v[164:167], v[230:233], v[70:73]
	v_mfma_f32_16x16x32_bf16 v[66:69], v[198:201], v[230:233], v[66:69]
	v_mfma_f32_16x16x32_bf16 v[118:121], v[194:197], v[210:213], v[118:121]
	v_mfma_f32_16x16x32_bf16 v[114:117], v[202:205], v[210:213], v[114:117]
	v_mfma_f32_16x16x32_bf16 v[102:105], v[194:197], v[218:221], v[102:105]
	v_mfma_f32_16x16x32_bf16 v[98:101], v[202:205], v[218:221], v[98:101]
	v_mfma_f32_16x16x32_bf16 v[86:89], v[194:197], v[226:229], v[86:89]
	v_mfma_f32_16x16x32_bf16 v[82:85], v[202:205], v[226:229], v[82:85]
	v_mfma_f32_16x16x32_bf16 v[70:73], v[194:197], v[234:237], v[70:73]
	v_mfma_f32_16x16x32_bf16 v[66:69], v[202:205], v[234:237], v[66:69]
	s_barrier
	s_add_i32 s30, s86, s23
	v_lshl_add_u64 v[168:169], s[98:99], 0, v[32:33]
	s_mov_b32 m0, s30
	ds_read_b128 v[206:209], v151 offset:16384
	ds_read_b128 v[210:213], v151 offset:17408
	ds_read_b128 v[214:217], v151 offset:18432
	ds_read_b128 v[218:221], v151 offset:19456
	ds_read_b128 v[222:225], v151 offset:20480
	ds_read_b128 v[226:229], v151 offset:21504
	ds_read_b128 v[230:233], v151 offset:22528
	ds_read_b128 v[234:237], v151 offset:23552
	global_load_lds_dwordx4 v[168:169], off
	s_add_i32 m0, s30, 0x2000
	v_lshl_add_u64 v[238:239], s[98:99], 0, v[144:145]
	s_add_u32 s98, s98, s66
	s_addc_u32 s99, s99, s67
	s_add_i32 s1, s1, s23
	global_load_lds_dwordx4 v[238:239], off
	v_lshl_add_u64 v[240:241], s[98:99], 0, v[32:33]
	s_mov_b32 m0, s1
	v_lshl_add_u64 v[242:243], s[98:99], 0, v[144:145]
	global_load_lds_dwordx4 v[240:241], off
	s_add_i32 m0, s1, 0x2000
	v_lshl_add_u64 v[244:245], s[80:81], 0, v[140:141]
	global_load_lds_dwordx4 v[242:243], off
	s_mov_b32 m0, s53
	v_lshl_add_u64 v[246:247], s[80:81], 0, v[142:143]
	global_load_lds_dwordx4 v[244:245], off
	s_mov_b32 m0, s54
	s_nop 0
	global_load_lds_dwordx4 v[246:247], off
	s_waitcnt vmcnt(8)
	s_waitcnt lgkmcnt(0)
	s_barrier
	s_waitcnt lgkmcnt(0)
	v_mfma_f32_16x16x32_bf16 v[62:65], v[146:149], v[206:209], v[62:65]
	v_mfma_f32_16x16x32_bf16 v[58:61], v[156:159], v[206:209], v[58:61]
	v_mfma_f32_16x16x32_bf16 v[46:49], v[146:149], v[214:217], v[46:49]
	v_mfma_f32_16x16x32_bf16 v[42:45], v[156:159], v[214:217], v[42:45]
	v_mfma_f32_16x16x32_bf16 v[28:31], v[146:149], v[222:225], v[28:31]
	v_mfma_f32_16x16x32_bf16 v[24:27], v[156:159], v[222:225], v[24:27]
	v_mfma_f32_16x16x32_bf16 v[12:15], v[146:149], v[230:233], v[12:15]
	v_mfma_f32_16x16x32_bf16 v[8:11], v[156:159], v[230:233], v[8:11]
	v_mfma_f32_16x16x32_bf16 v[62:65], v[152:155], v[210:213], v[62:65]
	v_mfma_f32_16x16x32_bf16 v[58:61], v[160:163], v[210:213], v[58:61]
	v_mfma_f32_16x16x32_bf16 v[46:49], v[152:155], v[218:221], v[46:49]
	v_mfma_f32_16x16x32_bf16 v[42:45], v[160:163], v[218:221], v[42:45]
	v_mfma_f32_16x16x32_bf16 v[28:31], v[152:155], v[226:229], v[28:31]
	v_mfma_f32_16x16x32_bf16 v[24:27], v[160:163], v[226:229], v[24:27]
	v_mfma_f32_16x16x32_bf16 v[12:15], v[152:155], v[234:237], v[12:15]
	v_mfma_f32_16x16x32_bf16 v[8:11], v[160:163], v[234:237], v[8:11]
	v_mfma_f32_16x16x32_bf16 v[54:57], v[164:167], v[206:209], v[54:57]
	v_mfma_f32_16x16x32_bf16 v[50:53], v[198:201], v[206:209], v[50:53]
	v_mfma_f32_16x16x32_bf16 v[38:41], v[164:167], v[214:217], v[38:41]
	v_mfma_f32_16x16x32_bf16 v[34:37], v[198:201], v[214:217], v[34:37]
	v_mfma_f32_16x16x32_bf16 v[20:23], v[164:167], v[222:225], v[20:23]
	v_mfma_f32_16x16x32_bf16 v[16:19], v[198:201], v[222:225], v[16:19]
	v_mfma_f32_16x16x32_bf16 v[4:7], v[164:167], v[230:233], v[4:7]
	v_mfma_f32_16x16x32_bf16 v[0:3], v[198:201], v[230:233], v[0:3]
	v_mfma_f32_16x16x32_bf16 v[54:57], v[194:197], v[210:213], v[54:57]
	v_mfma_f32_16x16x32_bf16 v[50:53], v[202:205], v[210:213], v[50:53]
	v_mfma_f32_16x16x32_bf16 v[38:41], v[194:197], v[218:221], v[38:41]
	v_mfma_f32_16x16x32_bf16 v[34:37], v[202:205], v[218:221], v[34:37]
	v_mfma_f32_16x16x32_bf16 v[20:23], v[194:197], v[226:229], v[20:23]
	v_mfma_f32_16x16x32_bf16 v[16:19], v[202:205], v[226:229], v[16:19]
	v_mfma_f32_16x16x32_bf16 v[4:7], v[194:197], v[234:237], v[4:7]
	v_mfma_f32_16x16x32_bf16 v[0:3], v[202:205], v[234:237], v[0:3]
	s_barrier
	s_add_i32 s1, 0, 0x18000
	s_add_i32 s30, 0, 0x1c000
	v_add_u32_e32 v160, s1, v139
	v_add_u32_e32 v181, s30, v139
	ds_read_b128 v[146:149], v160
	ds_read_b128 v[152:155], v160 offset:1024
	ds_read_b128 v[156:159], v160 offset:2048
	ds_read_b128 v[160:163], v160 offset:3072
	ds_read_b128 v[164:167], v181
	ds_read_b128 v[194:197], v181 offset:1024
	ds_read_b128 v[198:201], v181 offset:2048
	ds_read_b128 v[202:205], v181 offset:3072
	s_add_u32 s80, s80, s66
	s_addc_u32 s81, s81, s67
	s_mov_b32 m0, s55
	v_lshl_add_u64 v[248:249], s[80:81], 0, v[140:141]
	ds_read_b128 v[206:209], v151 offset:32768
	ds_read_b128 v[210:213], v151 offset:33792
	ds_read_b128 v[214:217], v151 offset:34816
	ds_read_b128 v[218:221], v151 offset:35840
	ds_read_b128 v[222:225], v151 offset:36864
	ds_read_b128 v[226:229], v151 offset:37888
	ds_read_b128 v[230:233], v151 offset:38912
	ds_read_b128 v[234:237], v151 offset:39936
	global_load_lds_dwordx4 v[248:249], off
	v_lshl_add_u64 v[248:249], s[80:81], 0, v[142:143]
	s_mov_b32 m0, s56
	s_nop 0
	global_load_lds_dwordx4 v[248:249], off
	s_waitcnt vmcnt(8)
	s_waitcnt lgkmcnt(0)
	s_barrier
	s_waitcnt lgkmcnt(0)
	v_mfma_f32_16x16x32_bf16 v[126:129], v[146:149], v[206:209], v[126:129]
	v_mfma_f32_16x16x32_bf16 v[122:125], v[156:159], v[206:209], v[122:125]
	v_mfma_f32_16x16x32_bf16 v[110:113], v[146:149], v[214:217], v[110:113]
	v_mfma_f32_16x16x32_bf16 v[106:109], v[156:159], v[214:217], v[106:109]
	v_mfma_f32_16x16x32_bf16 v[94:97], v[146:149], v[222:225], v[94:97]
	v_mfma_f32_16x16x32_bf16 v[90:93], v[156:159], v[222:225], v[90:93]
	v_mfma_f32_16x16x32_bf16 v[78:81], v[146:149], v[230:233], v[78:81]
	v_mfma_f32_16x16x32_bf16 v[74:77], v[156:159], v[230:233], v[74:77]
	v_mfma_f32_16x16x32_bf16 v[126:129], v[152:155], v[210:213], v[126:129]
	v_mfma_f32_16x16x32_bf16 v[122:125], v[160:163], v[210:213], v[122:125]
	v_mfma_f32_16x16x32_bf16 v[110:113], v[152:155], v[218:221], v[110:113]
	v_mfma_f32_16x16x32_bf16 v[106:109], v[160:163], v[218:221], v[106:109]
	v_mfma_f32_16x16x32_bf16 v[94:97], v[152:155], v[226:229], v[94:97]
	v_mfma_f32_16x16x32_bf16 v[90:93], v[160:163], v[226:229], v[90:93]
	v_mfma_f32_16x16x32_bf16 v[78:81], v[152:155], v[234:237], v[78:81]
	v_mfma_f32_16x16x32_bf16 v[74:77], v[160:163], v[234:237], v[74:77]
	v_mfma_f32_16x16x32_bf16 v[118:121], v[164:167], v[206:209], v[118:121]
	v_mfma_f32_16x16x32_bf16 v[114:117], v[198:201], v[206:209], v[114:117]
	v_mfma_f32_16x16x32_bf16 v[102:105], v[164:167], v[214:217], v[102:105]
	v_mfma_f32_16x16x32_bf16 v[98:101], v[198:201], v[214:217], v[98:101]
	v_mfma_f32_16x16x32_bf16 v[86:89], v[164:167], v[222:225], v[86:89]
	v_mfma_f32_16x16x32_bf16 v[82:85], v[198:201], v[222:225], v[82:85]
	v_mfma_f32_16x16x32_bf16 v[70:73], v[164:167], v[230:233], v[70:73]
	v_mfma_f32_16x16x32_bf16 v[66:69], v[198:201], v[230:233], v[66:69]
	v_mfma_f32_16x16x32_bf16 v[118:121], v[194:197], v[210:213], v[118:121]
	v_mfma_f32_16x16x32_bf16 v[114:117], v[202:205], v[210:213], v[114:117]
	v_mfma_f32_16x16x32_bf16 v[102:105], v[194:197], v[218:221], v[102:105]
	v_mfma_f32_16x16x32_bf16 v[98:101], v[202:205], v[218:221], v[98:101]
	v_mfma_f32_16x16x32_bf16 v[86:89], v[194:197], v[226:229], v[86:89]
	v_mfma_f32_16x16x32_bf16 v[82:85], v[202:205], v[226:229], v[82:85]
	v_mfma_f32_16x16x32_bf16 v[70:73], v[194:197], v[234:237], v[70:73]
	v_mfma_f32_16x16x32_bf16 v[66:69], v[202:205], v[234:237], v[66:69]
	s_barrier
	s_add_i32 s1, s1, s23
	v_lshl_add_u64 v[168:169], v[168:169], 0, s[26:27]
	s_mov_b32 m0, s1
	ds_read_b128 v[206:209], v151 offset:49152
	ds_read_b128 v[210:213], v151 offset:50176
	ds_read_b128 v[214:217], v151 offset:51200
	ds_read_b128 v[218:221], v151 offset:52224
	ds_read_b128 v[222:225], v151 offset:53248
	ds_read_b128 v[226:229], v151 offset:54272
	ds_read_b128 v[230:233], v151 offset:55296
	ds_read_b128 v[234:237], v151 offset:56320
	global_load_lds_dwordx4 v[168:169], off
	v_lshl_add_u64 v[168:169], v[238:239], 0, s[26:27]
	s_add_i32 m0, s1, 0x2000
	s_add_i32 s1, s30, s23
	global_load_lds_dwordx4 v[168:169], off
	v_lshl_add_u64 v[168:169], v[240:241], 0, s[26:27]
	s_mov_b32 m0, s1
	s_nop 0
	global_load_lds_dwordx4 v[168:169], off
	v_lshl_add_u64 v[168:169], v[242:243], 0, s[26:27]
	s_add_i32 m0, s1, 0x2000
	s_nop 0
	global_load_lds_dwordx4 v[168:169], off
	v_lshl_add_u64 v[168:169], v[244:245], 0, s[26:27]
	s_mov_b32 m0, s57
	s_nop 0
	global_load_lds_dwordx4 v[168:169], off
	v_lshl_add_u64 v[168:169], v[246:247], 0, s[26:27]
	s_mov_b32 m0, s71
	s_nop 0
	global_load_lds_dwordx4 v[168:169], off
	s_waitcnt vmcnt(8)
	s_waitcnt lgkmcnt(0)
	s_barrier
	s_waitcnt lgkmcnt(0)
	v_mfma_f32_16x16x32_bf16 v[62:65], v[146:149], v[206:209], v[62:65]
	v_mfma_f32_16x16x32_bf16 v[58:61], v[156:159], v[206:209], v[58:61]
	v_mfma_f32_16x16x32_bf16 v[46:49], v[146:149], v[214:217], v[46:49]
	v_mfma_f32_16x16x32_bf16 v[42:45], v[156:159], v[214:217], v[42:45]
	v_mfma_f32_16x16x32_bf16 v[28:31], v[146:149], v[222:225], v[28:31]
	v_mfma_f32_16x16x32_bf16 v[24:27], v[156:159], v[222:225], v[24:27]
	v_mfma_f32_16x16x32_bf16 v[12:15], v[146:149], v[230:233], v[12:15]
	v_mfma_f32_16x16x32_bf16 v[8:11], v[156:159], v[230:233], v[8:11]
	v_mfma_f32_16x16x32_bf16 v[62:65], v[152:155], v[210:213], v[62:65]
	v_mfma_f32_16x16x32_bf16 v[58:61], v[160:163], v[210:213], v[58:61]
	v_mfma_f32_16x16x32_bf16 v[46:49], v[152:155], v[218:221], v[46:49]
	v_mfma_f32_16x16x32_bf16 v[42:45], v[160:163], v[218:221], v[42:45]
	v_mfma_f32_16x16x32_bf16 v[28:31], v[152:155], v[226:229], v[28:31]
	v_mfma_f32_16x16x32_bf16 v[24:27], v[160:163], v[226:229], v[24:27]
	v_mfma_f32_16x16x32_bf16 v[12:15], v[152:155], v[234:237], v[12:15]
	v_mfma_f32_16x16x32_bf16 v[8:11], v[160:163], v[234:237], v[8:11]
	v_mfma_f32_16x16x32_bf16 v[54:57], v[164:167], v[206:209], v[54:57]
	v_mfma_f32_16x16x32_bf16 v[50:53], v[198:201], v[206:209], v[50:53]
	v_mfma_f32_16x16x32_bf16 v[38:41], v[164:167], v[214:217], v[38:41]
	v_mfma_f32_16x16x32_bf16 v[34:37], v[198:201], v[214:217], v[34:37]
	v_mfma_f32_16x16x32_bf16 v[20:23], v[164:167], v[222:225], v[20:23]
	v_mfma_f32_16x16x32_bf16 v[16:19], v[198:201], v[222:225], v[16:19]
	v_mfma_f32_16x16x32_bf16 v[4:7], v[164:167], v[230:233], v[4:7]
	v_mfma_f32_16x16x32_bf16 v[0:3], v[198:201], v[230:233], v[0:3]
	v_mfma_f32_16x16x32_bf16 v[54:57], v[194:197], v[210:213], v[54:57]
	v_mfma_f32_16x16x32_bf16 v[50:53], v[202:205], v[210:213], v[50:53]
	v_mfma_f32_16x16x32_bf16 v[38:41], v[194:197], v[218:221], v[38:41]
	v_mfma_f32_16x16x32_bf16 v[34:37], v[202:205], v[218:221], v[34:37]
	v_mfma_f32_16x16x32_bf16 v[20:23], v[194:197], v[226:229], v[20:23]
	v_mfma_f32_16x16x32_bf16 v[16:19], v[202:205], v[226:229], v[16:19]
	v_mfma_f32_16x16x32_bf16 v[4:7], v[194:197], v[234:237], v[4:7]
	v_mfma_f32_16x16x32_bf16 v[0:3], v[202:205], v[234:237], v[0:3]
	s_barrier
	s_add_u32 s78, s78, 0x100
	s_addc_u32 s79, s79, 0
	s_add_u32 s96, s96, 0x100
	s_addc_u32 s97, s97, 0
	s_cmp_ge_i32 s0, s94
	s_mov_b32 s80, s0
	s_cbranch_scc0 .LBB0_327
	s_and_b64 vcc, exec, s[74:75]
	s_cbranch_vccz .LBB0_330
	s_barrier

.LBB0_356:
	s_add_i32 s91, s76, 2
	s_add_u32 s0, s74, 0x80
	s_addc_u32 s1, s75, 0
	s_add_i32 s95, 0, 0x10000
	s_cmp_eq_u32 s81, s76
	s_cselect_b32 s77, s43, s1
	s_cselect_b32 s76, s42, s0
	s_cselect_b32 s1, s71, s90
	s_cselect_b32 s0, s70, s85
	s_add_i32 s96, 0, 0x14000
	v_add_u32_e32 v160, s95, v139
	v_add_u32_e32 v168, s96, v139
	ds_read_b128 v[148:151], v160
	ds_read_b128 v[152:155], v160 offset:1024
	ds_read_b128 v[156:159], v160 offset:2048
	ds_read_b128 v[160:163], v160 offset:3072
	ds_read_b128 v[164:167], v168
	ds_read_b128 v[194:197], v168 offset:1024
	ds_read_b128 v[198:201], v168 offset:2048
	ds_read_b128 v[202:205], v168 offset:3072
	v_lshl_add_u64 v[168:169], s[74:75], 0, v[130:131]
	s_add_i32 m0, s53, 0xc000
	ds_read_b128 v[206:209], v147
	ds_read_b128 v[210:213], v147 offset:1024
	ds_read_b128 v[214:217], v147 offset:2048
	ds_read_b128 v[218:221], v147 offset:3072
	ds_read_b128 v[222:225], v147 offset:4096
	ds_read_b128 v[226:229], v147 offset:5120
	ds_read_b128 v[230:233], v147 offset:6144
	ds_read_b128 v[234:237], v147 offset:7168
	global_load_lds_dwordx4 v[168:169], off
	v_lshl_add_u64 v[168:169], s[74:75], 0, v[132:133]
	s_add_i32 m0, s53, 0xe000
	s_nop 0
	global_load_lds_dwordx4 v[168:169], off
	s_waitcnt vmcnt(8)
	s_waitcnt lgkmcnt(0)
	s_barrier
	s_waitcnt lgkmcnt(0)
	v_mfma_f32_16x16x32_bf16 v[126:129], v[148:151], v[206:209], v[126:129]
	v_mfma_f32_16x16x32_bf16 v[122:125], v[156:159], v[206:209], v[122:125]
	v_mfma_f32_16x16x32_bf16 v[118:121], v[148:151], v[214:217], v[118:121]
	v_mfma_f32_16x16x32_bf16 v[114:117], v[156:159], v[214:217], v[114:117]
	v_mfma_f32_16x16x32_bf16 v[102:105], v[148:151], v[222:225], v[102:105]
	v_mfma_f32_16x16x32_bf16 v[98:101], v[156:159], v[222:225], v[98:101]
	v_mfma_f32_16x16x32_bf16 v[86:89], v[148:151], v[230:233], v[86:89]
	v_mfma_f32_16x16x32_bf16 v[82:85], v[156:159], v[230:233], v[82:85]
	v_mfma_f32_16x16x32_bf16 v[126:129], v[152:155], v[210:213], v[126:129]
	v_mfma_f32_16x16x32_bf16 v[122:125], v[160:163], v[210:213], v[122:125]
	v_mfma_f32_16x16x32_bf16 v[118:121], v[152:155], v[218:221], v[118:121]
	v_mfma_f32_16x16x32_bf16 v[114:117], v[160:163], v[218:221], v[114:117]
	v_mfma_f32_16x16x32_bf16 v[102:105], v[152:155], v[226:229], v[102:105]
	v_mfma_f32_16x16x32_bf16 v[98:101], v[160:163], v[226:229], v[98:101]
	v_mfma_f32_16x16x32_bf16 v[86:89], v[152:155], v[234:237], v[86:89]
	v_mfma_f32_16x16x32_bf16 v[82:85], v[160:163], v[234:237], v[82:85]
	v_mfma_f32_16x16x32_bf16 v[110:113], v[164:167], v[206:209], v[110:113]
	v_mfma_f32_16x16x32_bf16 v[106:109], v[198:201], v[206:209], v[106:109]
	v_mfma_f32_16x16x32_bf16 v[94:97], v[164:167], v[214:217], v[94:97]
	v_mfma_f32_16x16x32_bf16 v[90:93], v[198:201], v[214:217], v[90:93]
	v_mfma_f32_16x16x32_bf16 v[78:81], v[164:167], v[222:225], v[78:81]
	v_mfma_f32_16x16x32_bf16 v[74:77], v[198:201], v[222:225], v[74:77]
	v_mfma_f32_16x16x32_bf16 v[70:73], v[164:167], v[230:233], v[70:73]
	v_mfma_f32_16x16x32_bf16 v[66:69], v[198:201], v[230:233], v[66:69]
	v_mfma_f32_16x16x32_bf16 v[110:113], v[194:197], v[210:213], v[110:113]
	v_mfma_f32_16x16x32_bf16 v[106:109], v[202:205], v[210:213], v[106:109]
	v_mfma_f32_16x16x32_bf16 v[94:97], v[194:197], v[218:221], v[94:97]
	v_mfma_f32_16x16x32_bf16 v[90:93], v[202:205], v[218:221], v[90:93]
	v_mfma_f32_16x16x32_bf16 v[78:81], v[194:197], v[226:229], v[78:81]
	v_mfma_f32_16x16x32_bf16 v[74:77], v[202:205], v[226:229], v[74:77]
	v_mfma_f32_16x16x32_bf16 v[70:73], v[194:197], v[234:237], v[70:73]
	v_mfma_f32_16x16x32_bf16 v[66:69], v[202:205], v[234:237], v[66:69]
	s_barrier
	s_add_i32 s95, s95, s23
	v_lshl_add_u64 v[168:169], s[0:1], 0, v[32:33]
	s_mov_b32 m0, s95
	ds_read_b128 v[206:209], v147 offset:16384
	ds_read_b128 v[210:213], v147 offset:17408
	ds_read_b128 v[214:217], v147 offset:18432
	ds_read_b128 v[218:221], v147 offset:19456
	ds_read_b128 v[222:225], v147 offset:20480
	ds_read_b128 v[226:229], v147 offset:21504
	ds_read_b128 v[230:233], v147 offset:22528
	ds_read_b128 v[234:237], v147 offset:23552
	global_load_lds_dwordx4 v[168:169], off
	s_add_i32 m0, s95, 0x2000
	v_lshl_add_u64 v[238:239], s[0:1], 0, v[144:145]
	s_add_u32 s0, s0, s66
	s_addc_u32 s1, s1, s67
	s_add_i32 s95, s96, s23
	global_load_lds_dwordx4 v[238:239], off
	v_lshl_add_u64 v[240:241], s[0:1], 0, v[32:33]
	s_mov_b32 m0, s95
	v_lshl_add_u64 v[242:243], s[0:1], 0, v[144:145]
	global_load_lds_dwordx4 v[240:241], off
	s_add_i32 m0, s95, 0x2000
	v_lshl_add_u64 v[244:245], s[76:77], 0, v[140:141]
	global_load_lds_dwordx4 v[242:243], off
	s_mov_b32 m0, s53
	v_lshl_add_u64 v[246:247], s[76:77], 0, v[142:143]
	global_load_lds_dwordx4 v[244:245], off
	s_mov_b32 m0, s54
	s_nop 0
	global_load_lds_dwordx4 v[246:247], off
	s_waitcnt vmcnt(8)
	s_waitcnt lgkmcnt(0)
	s_barrier
	s_waitcnt lgkmcnt(0)
	v_mfma_f32_16x16x32_bf16 v[62:65], v[148:151], v[206:209], v[62:65]
	v_mfma_f32_16x16x32_bf16 v[58:61], v[156:159], v[206:209], v[58:61]
	v_mfma_f32_16x16x32_bf16 v[54:57], v[148:151], v[214:217], v[54:57]
	v_mfma_f32_16x16x32_bf16 v[50:53], v[156:159], v[214:217], v[50:53]
	v_mfma_f32_16x16x32_bf16 v[38:41], v[148:151], v[222:225], v[38:41]
	v_mfma_f32_16x16x32_bf16 v[34:37], v[156:159], v[222:225], v[34:37]
	v_mfma_f32_16x16x32_bf16 v[20:23], v[148:151], v[230:233], v[20:23]
	v_mfma_f32_16x16x32_bf16 v[16:19], v[156:159], v[230:233], v[16:19]
	v_mfma_f32_16x16x32_bf16 v[62:65], v[152:155], v[210:213], v[62:65]
	v_mfma_f32_16x16x32_bf16 v[58:61], v[160:163], v[210:213], v[58:61]
	v_mfma_f32_16x16x32_bf16 v[54:57], v[152:155], v[218:221], v[54:57]
	v_mfma_f32_16x16x32_bf16 v[50:53], v[160:163], v[218:221], v[50:53]
	v_mfma_f32_16x16x32_bf16 v[38:41], v[152:155], v[226:229], v[38:41]
	v_mfma_f32_16x16x32_bf16 v[34:37], v[160:163], v[226:229], v[34:37]
	v_mfma_f32_16x16x32_bf16 v[20:23], v[152:155], v[234:237], v[20:23]
	v_mfma_f32_16x16x32_bf16 v[16:19], v[160:163], v[234:237], v[16:19]
	v_mfma_f32_16x16x32_bf16 v[46:49], v[164:167], v[206:209], v[46:49]
	v_mfma_f32_16x16x32_bf16 v[42:45], v[198:201], v[206:209], v[42:45]
	v_mfma_f32_16x16x32_bf16 v[28:31], v[164:167], v[214:217], v[28:31]
	v_mfma_f32_16x16x32_bf16 v[24:27], v[198:201], v[214:217], v[24:27]
	v_mfma_f32_16x16x32_bf16 v[12:15], v[164:167], v[222:225], v[12:15]
	v_mfma_f32_16x16x32_bf16 v[8:11], v[198:201], v[222:225], v[8:11]
	v_mfma_f32_16x16x32_bf16 v[4:7], v[164:167], v[230:233], v[4:7]
	v_mfma_f32_16x16x32_bf16 v[0:3], v[198:201], v[230:233], v[0:3]
	v_mfma_f32_16x16x32_bf16 v[46:49], v[194:197], v[210:213], v[46:49]
	v_mfma_f32_16x16x32_bf16 v[42:45], v[202:205], v[210:213], v[42:45]
	v_mfma_f32_16x16x32_bf16 v[28:31], v[194:197], v[218:221], v[28:31]
	v_mfma_f32_16x16x32_bf16 v[24:27], v[202:205], v[218:221], v[24:27]
	v_mfma_f32_16x16x32_bf16 v[12:15], v[194:197], v[226:229], v[12:15]
	v_mfma_f32_16x16x32_bf16 v[8:11], v[202:205], v[226:229], v[8:11]
	v_mfma_f32_16x16x32_bf16 v[4:7], v[194:197], v[234:237], v[4:7]
	v_mfma_f32_16x16x32_bf16 v[0:3], v[202:205], v[234:237], v[0:3]
	s_barrier
	s_add_i32 s95, 0, 0x18000
	s_add_i32 s96, 0, 0x1c000
	v_add_u32_e32 v160, s95, v139
	v_add_u32_e32 v181, s96, v139
	ds_read_b128 v[148:151], v160
	ds_read_b128 v[152:155], v160 offset:1024
	ds_read_b128 v[156:159], v160 offset:2048
	ds_read_b128 v[160:163], v160 offset:3072
	ds_read_b128 v[164:167], v181
	ds_read_b128 v[194:197], v181 offset:1024
	ds_read_b128 v[198:201], v181 offset:2048
	ds_read_b128 v[202:205], v181 offset:3072
	s_add_u32 s0, s76, s66
	s_addc_u32 s1, s77, s67
	s_mov_b32 m0, s55
	v_lshl_add_u64 v[248:249], s[0:1], 0, v[140:141]
	ds_read_b128 v[206:209], v147 offset:32768
	ds_read_b128 v[210:213], v147 offset:33792
	ds_read_b128 v[214:217], v147 offset:34816
	ds_read_b128 v[218:221], v147 offset:35840
	ds_read_b128 v[222:225], v147 offset:36864
	ds_read_b128 v[226:229], v147 offset:37888
	ds_read_b128 v[230:233], v147 offset:38912
	ds_read_b128 v[234:237], v147 offset:39936
	global_load_lds_dwordx4 v[248:249], off
	v_lshl_add_u64 v[248:249], s[0:1], 0, v[142:143]
	s_mov_b32 m0, s56
	s_nop 0
	global_load_lds_dwordx4 v[248:249], off
	s_waitcnt vmcnt(8)
	s_waitcnt lgkmcnt(0)
	s_barrier
	s_waitcnt lgkmcnt(0)
	v_mfma_f32_16x16x32_bf16 v[126:129], v[148:151], v[206:209], v[126:129]
	v_mfma_f32_16x16x32_bf16 v[122:125], v[156:159], v[206:209], v[122:125]
	v_mfma_f32_16x16x32_bf16 v[118:121], v[148:151], v[214:217], v[118:121]
	v_mfma_f32_16x16x32_bf16 v[114:117], v[156:159], v[214:217], v[114:117]
	v_mfma_f32_16x16x32_bf16 v[102:105], v[148:151], v[222:225], v[102:105]
	v_mfma_f32_16x16x32_bf16 v[98:101], v[156:159], v[222:225], v[98:101]
	v_mfma_f32_16x16x32_bf16 v[86:89], v[148:151], v[230:233], v[86:89]
	v_mfma_f32_16x16x32_bf16 v[82:85], v[156:159], v[230:233], v[82:85]
	v_mfma_f32_16x16x32_bf16 v[126:129], v[152:155], v[210:213], v[126:129]
	v_mfma_f32_16x16x32_bf16 v[122:125], v[160:163], v[210:213], v[122:125]
	v_mfma_f32_16x16x32_bf16 v[118:121], v[152:155], v[218:221], v[118:121]
	v_mfma_f32_16x16x32_bf16 v[114:117], v[160:163], v[218:221], v[114:117]
	v_mfma_f32_16x16x32_bf16 v[102:105], v[152:155], v[226:229], v[102:105]
	v_mfma_f32_16x16x32_bf16 v[98:101], v[160:163], v[226:229], v[98:101]
	v_mfma_f32_16x16x32_bf16 v[86:89], v[152:155], v[234:237], v[86:89]
	v_mfma_f32_16x16x32_bf16 v[82:85], v[160:163], v[234:237], v[82:85]
	v_mfma_f32_16x16x32_bf16 v[110:113], v[164:167], v[206:209], v[110:113]
	v_mfma_f32_16x16x32_bf16 v[106:109], v[198:201], v[206:209], v[106:109]
	v_mfma_f32_16x16x32_bf16 v[94:97], v[164:167], v[214:217], v[94:97]
	v_mfma_f32_16x16x32_bf16 v[90:93], v[198:201], v[214:217], v[90:93]
	v_mfma_f32_16x16x32_bf16 v[78:81], v[164:167], v[222:225], v[78:81]
	v_mfma_f32_16x16x32_bf16 v[74:77], v[198:201], v[222:225], v[74:77]
	v_mfma_f32_16x16x32_bf16 v[70:73], v[164:167], v[230:233], v[70:73]
	v_mfma_f32_16x16x32_bf16 v[66:69], v[198:201], v[230:233], v[66:69]
	v_mfma_f32_16x16x32_bf16 v[110:113], v[194:197], v[210:213], v[110:113]
	v_mfma_f32_16x16x32_bf16 v[106:109], v[202:205], v[210:213], v[106:109]
	v_mfma_f32_16x16x32_bf16 v[94:97], v[194:197], v[218:221], v[94:97]
	v_mfma_f32_16x16x32_bf16 v[90:93], v[202:205], v[218:221], v[90:93]
	v_mfma_f32_16x16x32_bf16 v[78:81], v[194:197], v[226:229], v[78:81]
	v_mfma_f32_16x16x32_bf16 v[74:77], v[202:205], v[226:229], v[74:77]
	v_mfma_f32_16x16x32_bf16 v[70:73], v[194:197], v[234:237], v[70:73]
	v_mfma_f32_16x16x32_bf16 v[66:69], v[202:205], v[234:237], v[66:69]
	s_barrier
	s_add_i32 s0, s95, s23
	v_lshl_add_u64 v[168:169], v[168:169], 0, s[26:27]
	s_mov_b32 m0, s0
	ds_read_b128 v[206:209], v147 offset:49152
	ds_read_b128 v[210:213], v147 offset:50176
	ds_read_b128 v[214:217], v147 offset:51200
	ds_read_b128 v[218:221], v147 offset:52224
	ds_read_b128 v[222:225], v147 offset:53248
	ds_read_b128 v[226:229], v147 offset:54272
	ds_read_b128 v[230:233], v147 offset:55296
	ds_read_b128 v[234:237], v147 offset:56320
	global_load_lds_dwordx4 v[168:169], off
	v_lshl_add_u64 v[168:169], v[238:239], 0, s[26:27]
	s_add_i32 m0, s0, 0x2000
	s_add_i32 s0, s96, s23
	global_load_lds_dwordx4 v[168:169], off
	v_lshl_add_u64 v[168:169], v[240:241], 0, s[26:27]
	s_mov_b32 m0, s0
	s_nop 0
	global_load_lds_dwordx4 v[168:169], off
	v_lshl_add_u64 v[168:169], v[242:243], 0, s[26:27]
	s_add_i32 m0, s0, 0x2000
	s_nop 0
	global_load_lds_dwordx4 v[168:169], off
	v_lshl_add_u64 v[168:169], v[244:245], 0, s[26:27]
	s_mov_b32 m0, s57
	s_nop 0
	global_load_lds_dwordx4 v[168:169], off
	v_lshl_add_u64 v[168:169], v[246:247], 0, s[26:27]
	s_mov_b32 m0, s78
	s_nop 0
	global_load_lds_dwordx4 v[168:169], off
	s_waitcnt vmcnt(8)
	s_waitcnt lgkmcnt(0)
	s_barrier
	s_waitcnt lgkmcnt(0)
	v_mfma_f32_16x16x32_bf16 v[62:65], v[148:151], v[206:209], v[62:65]
	v_mfma_f32_16x16x32_bf16 v[58:61], v[156:159], v[206:209], v[58:61]
	v_mfma_f32_16x16x32_bf16 v[54:57], v[148:151], v[214:217], v[54:57]
	v_mfma_f32_16x16x32_bf16 v[50:53], v[156:159], v[214:217], v[50:53]
	v_mfma_f32_16x16x32_bf16 v[38:41], v[148:151], v[222:225], v[38:41]
	v_mfma_f32_16x16x32_bf16 v[34:37], v[156:159], v[222:225], v[34:37]
	v_mfma_f32_16x16x32_bf16 v[20:23], v[148:151], v[230:233], v[20:23]
	v_mfma_f32_16x16x32_bf16 v[16:19], v[156:159], v[230:233], v[16:19]
	v_mfma_f32_16x16x32_bf16 v[62:65], v[152:155], v[210:213], v[62:65]
	v_mfma_f32_16x16x32_bf16 v[58:61], v[160:163], v[210:213], v[58:61]
	v_mfma_f32_16x16x32_bf16 v[54:57], v[152:155], v[218:221], v[54:57]
	v_mfma_f32_16x16x32_bf16 v[50:53], v[160:163], v[218:221], v[50:53]
	v_mfma_f32_16x16x32_bf16 v[38:41], v[152:155], v[226:229], v[38:41]
	v_mfma_f32_16x16x32_bf16 v[34:37], v[160:163], v[226:229], v[34:37]
	v_mfma_f32_16x16x32_bf16 v[20:23], v[152:155], v[234:237], v[20:23]
	v_mfma_f32_16x16x32_bf16 v[16:19], v[160:163], v[234:237], v[16:19]
	v_mfma_f32_16x16x32_bf16 v[46:49], v[164:167], v[206:209], v[46:49]
	v_mfma_f32_16x16x32_bf16 v[42:45], v[198:201], v[206:209], v[42:45]
	v_mfma_f32_16x16x32_bf16 v[28:31], v[164:167], v[214:217], v[28:31]
	v_mfma_f32_16x16x32_bf16 v[24:27], v[198:201], v[214:217], v[24:27]
	v_mfma_f32_16x16x32_bf16 v[12:15], v[164:167], v[222:225], v[12:15]
	v_mfma_f32_16x16x32_bf16 v[8:11], v[198:201], v[222:225], v[8:11]
	v_mfma_f32_16x16x32_bf16 v[4:7], v[164:167], v[230:233], v[4:7]
	v_mfma_f32_16x16x32_bf16 v[0:3], v[198:201], v[230:233], v[0:3]
	v_mfma_f32_16x16x32_bf16 v[46:49], v[194:197], v[210:213], v[46:49]
	v_mfma_f32_16x16x32_bf16 v[42:45], v[202:205], v[210:213], v[42:45]
	v_mfma_f32_16x16x32_bf16 v[28:31], v[194:197], v[218:221], v[28:31]
	v_mfma_f32_16x16x32_bf16 v[24:27], v[202:205], v[218:221], v[24:27]
	v_mfma_f32_16x16x32_bf16 v[12:15], v[194:197], v[226:229], v[12:15]
	v_mfma_f32_16x16x32_bf16 v[8:11], v[202:205], v[226:229], v[8:11]
	v_mfma_f32_16x16x32_bf16 v[4:7], v[194:197], v[234:237], v[4:7]
	v_mfma_f32_16x16x32_bf16 v[0:3], v[202:205], v[234:237], v[0:3]
	s_barrier
	s_add_u32 s74, s74, 0x100
	s_addc_u32 s75, s75, 0
	s_add_u32 s85, s85, 0x100
	s_addc_u32 s90, s90, 0
	s_cmp_ge_i32 s91, s94
	s_mov_b32 s76, s91
	s_cbranch_scc0 .LBB0_356
	s_and_b64 vcc, exec, s[72:73]
	s_cbranch_vccz .LBB0_359
	s_barrier
